# baseline (speedup 1.0000x reference)
.Lh2_loop:
	ds_read_b128 v[140:143], v138
	ds_read_b128 v[144:147], v138 offset:1024
	ds_read_b128 v[148:151], v138 offset:2048
	ds_read_b128 v[152:155], v138 offset:3072
	s_add_u32 s8, s6, s65
	s_addc_u32 s9, s7, s66
	ds_read_b128 v[156:159], v134
	ds_read_b128 v[164:167], v133
	ds_read_b128 v[172:175], v132
	ds_read_b128 v[180:183], v131
	ds_read_b128 v[160:163], v134 offset:1024
	ds_read_b128 v[168:171], v133 offset:1024
	ds_read_b128 v[176:179], v132 offset:1024
	ds_read_b128 v[184:187], v131 offset:1024
	s_mov_b32 m0, s76
	s_mov_b32 m0, s75
	s_nop 0
	s_waitcnt lgkmcnt(8)
	s_barrier
	s_waitcnt lgkmcnt(7)
	v_mfma_f32_16x16x32_bf16 v[124:127], v[140:143], v[156:159], v[124:127]
	v_mfma_f32_16x16x32_bf16 v[120:123], v[148:151], v[156:159], v[120:123]
	s_waitcnt lgkmcnt(6)
	v_mfma_f32_16x16x32_bf16 v[116:119], v[140:143], v[164:167], v[116:119]
	v_mfma_f32_16x16x32_bf16 v[112:115], v[148:151], v[164:167], v[112:115]
	s_waitcnt lgkmcnt(5)
	v_mfma_f32_16x16x32_bf16 v[108:111], v[140:143], v[172:175], v[108:111]
	v_mfma_f32_16x16x32_bf16 v[104:107], v[148:151], v[172:175], v[104:107]
	s_waitcnt lgkmcnt(4)
	v_mfma_f32_16x16x32_bf16 v[100:103], v[140:143], v[180:183], v[100:103]
	v_mfma_f32_16x16x32_bf16 v[96:99], v[148:151], v[180:183], v[96:99]
	s_waitcnt lgkmcnt(3)
	v_mfma_f32_16x16x32_bf16 v[124:127], v[144:147], v[160:163], v[124:127]
	v_mfma_f32_16x16x32_bf16 v[120:123], v[152:155], v[160:163], v[120:123]
	s_waitcnt lgkmcnt(2)
	v_mfma_f32_16x16x32_bf16 v[116:119], v[144:147], v[168:171], v[116:119]
	v_mfma_f32_16x16x32_bf16 v[112:115], v[152:155], v[168:171], v[112:115]
	s_waitcnt lgkmcnt(1)
	v_mfma_f32_16x16x32_bf16 v[108:111], v[144:147], v[176:179], v[108:111]
	v_mfma_f32_16x16x32_bf16 v[104:107], v[152:155], v[176:179], v[104:107]
	s_waitcnt lgkmcnt(0)
	v_mfma_f32_16x16x32_bf16 v[100:103], v[144:147], v[184:187], v[100:103]
	v_mfma_f32_16x16x32_bf16 v[96:99], v[152:155], v[184:187], v[96:99]
	s_barrier
	s_add_u32 s10, s6, s36
	s_addc_u32 s11, s7, s37
	ds_read_b128 v[188:191], v137
	ds_read_b128 v[192:195], v137 offset:1024
	ds_read_b128 v[202:205], v137 offset:2048
	ds_read_b128 v[206:209], v137 offset:3072
	s_mov_b32 m0, s63
	s_add_u32 s98, s10, s46
	s_addc_u32 s99, s11, s47
	global_load_lds_dwordx4 v129, s[98:99]
	s_mov_b32 m0, s64
	s_nop 0
	global_load_lds_dwordx4 v130, s[98:99]
	s_barrier
	s_waitcnt lgkmcnt(3)
	v_mfma_f32_16x16x32_bf16 v[92:95], v[188:191], v[156:159], v[92:95]
	s_waitcnt lgkmcnt(1)
	v_mfma_f32_16x16x32_bf16 v[88:91], v[202:205], v[156:159], v[88:91]
	v_mfma_f32_16x16x32_bf16 v[84:87], v[188:191], v[164:167], v[84:87]
	v_mfma_f32_16x16x32_bf16 v[80:83], v[202:205], v[164:167], v[80:83]
	v_mfma_f32_16x16x32_bf16 v[76:79], v[188:191], v[172:175], v[76:79]
	v_mfma_f32_16x16x32_bf16 v[72:75], v[202:205], v[172:175], v[72:75]
	v_mfma_f32_16x16x32_bf16 v[68:71], v[188:191], v[180:183], v[68:71]
	v_mfma_f32_16x16x32_bf16 v[64:67], v[202:205], v[180:183], v[64:67]
	v_mfma_f32_16x16x32_bf16 v[92:95], v[192:195], v[160:163], v[92:95]
	s_waitcnt lgkmcnt(0)
	v_mfma_f32_16x16x32_bf16 v[88:91], v[206:209], v[160:163], v[88:91]
	v_mfma_f32_16x16x32_bf16 v[84:87], v[192:195], v[168:171], v[84:87]
	v_mfma_f32_16x16x32_bf16 v[80:83], v[206:209], v[168:171], v[80:83]
	v_mfma_f32_16x16x32_bf16 v[76:79], v[192:195], v[176:179], v[76:79]
	v_mfma_f32_16x16x32_bf16 v[72:75], v[206:209], v[176:179], v[72:75]
	v_mfma_f32_16x16x32_bf16 v[68:71], v[192:195], v[184:187], v[68:71]
	v_mfma_f32_16x16x32_bf16 v[64:67], v[206:209], v[184:187], v[64:67]
	s_barrier
	s_mov_b32 m0, s62
	s_add_u32 s98, s8, s48
	s_addc_u32 s99, s9, s49
	global_load_lds_dwordx4 v129, s[98:99]
	s_mov_b32 m0, s67
	s_nop 0
	global_load_lds_dwordx4 v130, s[98:99]
	s_waitcnt vmcnt(4)
	s_barrier
	s_mov_b32 m0, s68
	s_add_u32 s98, s10, s50
	s_addc_u32 s99, s11, s51
	global_load_lds_dwordx4 v129, s[98:99]
	s_mov_b32 m0, s69
	s_nop 0
	global_load_lds_dwordx4 v130, s[98:99]
	s_barrier
	ds_read_b128 v[140:143], v136
	ds_read_b128 v[144:147], v136 offset:1024
	ds_read_b128 v[148:151], v136 offset:2048
	ds_read_b128 v[156:159], v134 offset:32768
	ds_read_b128 v[164:167], v133 offset:32768
	ds_read_b128 v[172:175], v132 offset:32768
	ds_read_b128 v[152:155], v136 offset:3072
	ds_read_b128 v[160:163], v134 offset:33792
	ds_read_b128 v[168:171], v133 offset:33792
	ds_read_b128 v[176:179], v132 offset:33792
	ds_read_b128 v[180:183], v131 offset:32768
	ds_read_b128 v[184:187], v131 offset:33792
	s_mov_b32 m0, s70
	s_mov_b32 m0, s71
	s_nop 0
	s_waitcnt lgkmcnt(8)
	s_barrier
	s_waitcnt lgkmcnt(8)
	v_mfma_f32_16x16x32_bf16 v[124:127], v[140:143], v[156:159], v[124:127]
	v_mfma_f32_16x16x32_bf16 v[120:123], v[148:151], v[156:159], v[120:123]
	s_waitcnt lgkmcnt(7)
	v_mfma_f32_16x16x32_bf16 v[116:119], v[140:143], v[164:167], v[116:119]
	v_mfma_f32_16x16x32_bf16 v[112:115], v[148:151], v[164:167], v[112:115]
	s_waitcnt lgkmcnt(6)
	v_mfma_f32_16x16x32_bf16 v[108:111], v[140:143], v[172:175], v[108:111]
	v_mfma_f32_16x16x32_bf16 v[104:107], v[148:151], v[172:175], v[104:107]
	s_waitcnt lgkmcnt(1)
	v_mfma_f32_16x16x32_bf16 v[100:103], v[140:143], v[180:183], v[100:103]
	v_mfma_f32_16x16x32_bf16 v[96:99], v[148:151], v[180:183], v[96:99]
	v_mfma_f32_16x16x32_bf16 v[124:127], v[144:147], v[160:163], v[124:127]
	v_mfma_f32_16x16x32_bf16 v[120:123], v[152:155], v[160:163], v[120:123]
	v_mfma_f32_16x16x32_bf16 v[116:119], v[144:147], v[168:171], v[116:119]
	v_mfma_f32_16x16x32_bf16 v[112:115], v[152:155], v[168:171], v[112:115]
	v_mfma_f32_16x16x32_bf16 v[108:111], v[144:147], v[176:179], v[108:111]
	v_mfma_f32_16x16x32_bf16 v[104:107], v[152:155], v[176:179], v[104:107]
	s_waitcnt lgkmcnt(0)
	v_mfma_f32_16x16x32_bf16 v[100:103], v[144:147], v[184:187], v[100:103]
	v_mfma_f32_16x16x32_bf16 v[96:99], v[152:155], v[184:187], v[96:99]
	s_barrier
	ds_read_b128 v[188:191], v135
	ds_read_b128 v[192:195], v135 offset:1024
	ds_read_b128 v[202:205], v135 offset:2048
	ds_read_b128 v[206:209], v135 offset:3072
	s_mov_b32 m0, s28
	s_add_u32 s98, s10, s92
	s_addc_u32 s99, s11, s93
	global_load_lds_dwordx4 v129, s[98:99]
	s_mov_b32 m0, s29
	s_nop 0
	global_load_lds_dwordx4 v130, s[98:99]
	s_barrier
	s_waitcnt lgkmcnt(3)
	v_mfma_f32_16x16x32_bf16 v[92:95], v[188:191], v[156:159], v[92:95]
	s_waitcnt lgkmcnt(1)
	v_mfma_f32_16x16x32_bf16 v[88:91], v[202:205], v[156:159], v[88:91]
	v_mfma_f32_16x16x32_bf16 v[84:87], v[188:191], v[164:167], v[84:87]
	v_mfma_f32_16x16x32_bf16 v[80:83], v[202:205], v[164:167], v[80:83]
	v_mfma_f32_16x16x32_bf16 v[76:79], v[188:191], v[172:175], v[76:79]
	v_mfma_f32_16x16x32_bf16 v[72:75], v[202:205], v[172:175], v[72:75]
	v_mfma_f32_16x16x32_bf16 v[68:71], v[188:191], v[180:183], v[68:71]
	v_mfma_f32_16x16x32_bf16 v[64:67], v[202:205], v[180:183], v[64:67]
	v_mfma_f32_16x16x32_bf16 v[92:95], v[192:195], v[160:163], v[92:95]
	s_waitcnt lgkmcnt(0)
	v_mfma_f32_16x16x32_bf16 v[88:91], v[206:209], v[160:163], v[88:91]
	v_mfma_f32_16x16x32_bf16 v[84:87], v[192:195], v[168:171], v[84:87]
	v_mfma_f32_16x16x32_bf16 v[80:83], v[206:209], v[168:171], v[80:83]
	v_mfma_f32_16x16x32_bf16 v[76:79], v[192:195], v[176:179], v[76:79]
	v_mfma_f32_16x16x32_bf16 v[72:75], v[206:209], v[176:179], v[72:75]
	v_mfma_f32_16x16x32_bf16 v[68:71], v[192:195], v[184:187], v[68:71]
	v_mfma_f32_16x16x32_bf16 v[64:67], v[206:209], v[184:187], v[64:67]
	v_mov_b32_e32 v210, v130
	s_barrier
	v_mov_b32_e32 v211, v197
	s_mov_b32 m0, s72
	s_add_u32 s98, s8, s96
	s_addc_u32 s99, s9, s97
	global_load_lds_dwordx4 v129, s[98:99]
	s_mov_b32 m0, s73
	s_nop 0
	global_load_lds_dwordx4 v130, s[98:99]
	s_waitcnt vmcnt(4)
	s_barrier
	v_mov_b32_e32 v196, v129
	s_mov_b32 m0, s33
	s_add_u32 s98, s10, vcc_lo
	s_addc_u32 s99, s11, vcc_hi
	global_load_lds_dwordx4 v129, s[98:99]
	s_mov_b32 m0, s74
	s_nop 0
	global_load_lds_dwordx4 v130, s[98:99]
	s_barrier
	s_add_i32 s38, s38, 2
	s_add_u32 s6, s6, 0x100
	s_addc_u32 s7, s7, 0
	s_cmpk_lt_u32 s38, 0x54
	s_cbranch_scc1 .Lh2_loop
	s_add_u32 s4, s4, 0x2b80
	s_addc_u32 s5, s5, 0
	s_mov_b32 m0, s76
	ds_read_b128 v[140:143], v138
	ds_read_b128 v[144:147], v138 offset:1024
	ds_read_b128 v[148:151], v138 offset:2048
	ds_read_b128 v[152:155], v138 offset:3072
	ds_read_b128 v[156:159], v134
	ds_read_b128 v[160:163], v134 offset:1024
	ds_read_b128 v[164:167], v133
	ds_read_b128 v[168:171], v133 offset:1024
	ds_read_b128 v[172:175], v132
	ds_read_b128 v[176:179], v132 offset:1024
	ds_read_b128 v[180:183], v131
	ds_read_b128 v[184:187], v131 offset:1024
	s_nop 0
	s_mov_b32 m0, s75
	s_nop 0
	s_barrier
	s_waitcnt lgkmcnt(0)
	s_setprio 1
	s_waitcnt lgkmcnt(0)
	v_mfma_f32_16x16x32_bf16 v[124:127], v[140:143], v[156:159], v[124:127]
	v_mfma_f32_16x16x32_bf16 v[120:123], v[148:151], v[156:159], v[120:123]
	v_mfma_f32_16x16x32_bf16 v[116:119], v[140:143], v[164:167], v[116:119]
	v_mfma_f32_16x16x32_bf16 v[112:115], v[148:151], v[164:167], v[112:115]
	v_mfma_f32_16x16x32_bf16 v[108:111], v[140:143], v[172:175], v[108:111]
	v_mfma_f32_16x16x32_bf16 v[100:103], v[140:143], v[180:183], v[100:103]
	v_mfma_f32_16x16x32_bf16 v[96:99], v[148:151], v[180:183], v[96:99]
	v_mfma_f32_16x16x32_bf16 v[124:127], v[144:147], v[160:163], v[124:127]
	v_mfma_f32_16x16x32_bf16 v[120:123], v[152:155], v[160:163], v[120:123]
	v_mfma_f32_16x16x32_bf16 v[116:119], v[144:147], v[168:171], v[116:119]
	v_mfma_f32_16x16x32_bf16 v[112:115], v[152:155], v[168:171], v[112:115]
	v_mfma_f32_16x16x32_bf16 v[108:111], v[144:147], v[176:179], v[108:111]
	v_mfma_f32_16x16x32_bf16 v[104:107], v[148:151], v[172:175], v[104:107]
	v_mfma_f32_16x16x32_bf16 v[100:103], v[144:147], v[184:187], v[100:103]
	v_mfma_f32_16x16x32_bf16 v[96:99], v[152:155], v[184:187], v[96:99]
	v_mfma_f32_16x16x32_bf16 v[188:191], v[152:155], v[176:179], v[104:107]
	s_setprio 0
	s_barrier
	s_nop 2
	ds_read_b128 v[104:107], v137
	ds_read_b128 v[192:195], v137 offset:1024
	ds_read_b128 v[202:205], v137 offset:2048
	ds_read_b128 v[206:209], v137 offset:3072
	s_barrier
	s_waitcnt lgkmcnt(0)
	s_setprio 1
	s_waitcnt lgkmcnt(0)
	v_mfma_f32_16x16x32_bf16 v[92:95], v[104:107], v[156:159], v[92:95]
	v_mfma_f32_16x16x32_bf16 v[88:91], v[202:205], v[156:159], v[88:91]
	v_mfma_f32_16x16x32_bf16 v[80:83], v[202:205], v[164:167], v[80:83]
	v_mfma_f32_16x16x32_bf16 v[72:75], v[202:205], v[172:175], v[72:75]
	v_mfma_f32_16x16x32_bf16 v[64:67], v[202:205], v[180:183], v[64:67]
	v_mfma_f32_16x16x32_bf16 v[92:95], v[192:195], v[160:163], v[92:95]
	v_mfma_f32_16x16x32_bf16 v[88:91], v[206:209], v[160:163], v[88:91]
	v_mfma_f32_16x16x32_bf16 v[84:87], v[104:107], v[164:167], v[84:87]
	v_mfma_f32_16x16x32_bf16 v[80:83], v[206:209], v[168:171], v[80:83]
	v_mfma_f32_16x16x32_bf16 v[76:79], v[104:107], v[172:175], v[76:79]
	v_mfma_f32_16x16x32_bf16 v[72:75], v[206:209], v[176:179], v[72:75]
	v_mfma_f32_16x16x32_bf16 v[68:71], v[104:107], v[180:183], v[68:71]
	v_mfma_f32_16x16x32_bf16 v[64:67], v[206:209], v[184:187], v[64:67]
	v_mfma_f32_16x16x32_bf16 v[156:159], v[192:195], v[168:171], v[84:87]
	v_mfma_f32_16x16x32_bf16 v[160:163], v[192:195], v[176:179], v[76:79]
	v_mfma_f32_16x16x32_bf16 v[164:167], v[192:195], v[184:187], v[68:71]
	s_setprio 0
	s_barrier
	s_nop 1
	s_waitcnt vmcnt(2)
	s_barrier
	s_waitcnt lgkmcnt(0)
	s_setprio 1
	s_waitcnt lgkmcnt(0)
	s_setprio 0
	s_setprio 1
	s_setprio 0
	s_barrier
	ds_read_b128 v[16:19], v136
	ds_read_b128 v[180:183], v136 offset:1024
	ds_read_b128 v[184:187], v136 offset:2048
	ds_read_b128 v[192:195], v136 offset:3072
	ds_read_b128 v[0:3], v134 offset:32768
	ds_read_b128 v[4:7], v134 offset:33792
	ds_read_b128 v[8:11], v133 offset:32768
	ds_read_b128 v[12:15], v133 offset:33792
	ds_read_b128 v[44:47], v132 offset:32768
	ds_read_b128 v[202:205], v132 offset:33792
	ds_read_b128 v[206:209], v131 offset:32768
	ds_read_b128 v[222:225], v131 offset:33792
	s_waitcnt vmcnt(0)
	s_barrier
	s_waitcnt lgkmcnt(0)
	s_setprio 1
	s_waitcnt lgkmcnt(0)
	v_mfma_f32_16x16x32_bf16 v[28:31], v[16:19], v[0:3], v[124:127]
	v_mfma_f32_16x16x32_bf16 v[52:55], v[180:183], v[4:7], v[28:31]
	v_mfma_f32_16x16x32_bf16 v[28:31], v[184:187], v[0:3], v[120:123]
	v_mfma_f32_16x16x32_bf16 v[104:107], v[192:195], v[4:7], v[28:31]
	v_mfma_f32_16x16x32_bf16 v[28:31], v[16:19], v[8:11], v[116:119]
	v_mfma_f32_16x16x32_bf16 v[68:71], v[180:183], v[12:15], v[28:31]
	v_mfma_f32_16x16x32_bf16 v[28:31], v[184:187], v[8:11], v[112:115]
	v_mfma_f32_16x16x32_bf16 v[116:119], v[192:195], v[12:15], v[28:31]
	v_mfma_f32_16x16x32_bf16 v[28:31], v[16:19], v[44:47], v[108:111]
	v_mfma_f32_16x16x32_bf16 v[76:79], v[180:183], v[202:205], v[28:31]
	v_mfma_f32_16x16x32_bf16 v[28:31], v[184:187], v[44:47], v[188:191]
	v_mfma_f32_16x16x32_bf16 v[108:111], v[192:195], v[202:205], v[28:31]
	v_mfma_f32_16x16x32_bf16 v[28:31], v[16:19], v[206:209], v[100:103]
	v_mfma_f32_16x16x32_bf16 v[84:87], v[180:183], v[222:225], v[28:31]
	v_mfma_f32_16x16x32_bf16 v[28:31], v[184:187], v[206:209], v[96:99]
	v_mfma_f32_16x16x32_bf16 v[96:99], v[192:195], v[222:225], v[28:31]
	s_setprio 0
	s_barrier
	ds_read_b128 v[188:191], v135
	ds_read_b128 v[228:231], v135 offset:1024
	ds_read_b128 v[232:235], v135 offset:2048
	ds_read_b128 v[236:239], v135 offset:3072
	s_waitcnt vmcnt(0)
	s_barrier
	s_waitcnt lgkmcnt(0)
	s_setprio 1
	s_waitcnt lgkmcnt(0)
	v_mfma_f32_16x16x32_bf16 v[28:31], v[188:191], v[0:3], v[92:95]
	v_mfma_f32_16x16x32_bf16 v[0:3], v[232:235], v[0:3], v[88:91]
	v_mfma_f32_16x16x32_bf16 v[28:31], v[228:231], v[4:7], v[28:31]
	v_mfma_f32_16x16x32_bf16 v[0:3], v[236:239], v[4:7], v[0:3]
	v_mfma_f32_16x16x32_bf16 v[4:7], v[188:191], v[8:11], v[156:159]
	v_mfma_f32_16x16x32_bf16 v[36:39], v[228:231], v[12:15], v[4:7]
	v_mfma_f32_16x16x32_bf16 v[4:7], v[232:235], v[8:11], v[80:83]
	v_mfma_f32_16x16x32_bf16 v[4:7], v[236:239], v[12:15], v[4:7]
	v_mfma_f32_16x16x32_bf16 v[8:11], v[188:191], v[44:47], v[160:163]
	v_mfma_f32_16x16x32_bf16 v[12:15], v[188:191], v[206:209], v[164:167]
	v_mfma_f32_16x16x32_bf16 v[40:43], v[228:231], v[202:205], v[8:11]
	v_mfma_f32_16x16x32_bf16 v[8:11], v[232:235], v[44:47], v[72:75]
	v_mfma_f32_16x16x32_bf16 v[44:47], v[228:231], v[222:225], v[12:15]
	v_mfma_f32_16x16x32_bf16 v[12:15], v[232:235], v[206:209], v[64:67]
	v_mfma_f32_16x16x32_bf16 v[8:11], v[236:239], v[202:205], v[8:11]
	v_mfma_f32_16x16x32_bf16 v[12:15], v[236:239], v[222:225], v[12:15]
	s_setprio 0
	s_barrier
	s_barrier
	s_waitcnt lgkmcnt(0)
	s_setprio 1
	s_waitcnt lgkmcnt(0)
	s_setprio 0
	s_setprio 1
	s_setprio 0
	s_movk_i32 s4, 0x100
	v_cmp_gt_u32_e32 vcc, s4, v128
	s_barrier
	s_and_saveexec_b64 s[4:5], vcc
	s_cbranch_execz .Lh2_epi
	s_barrier

.LBB0_138:
	ds_read_b128 v[140:143], v138
	ds_read_b128 v[144:147], v138 offset:1024
	ds_read_b128 v[148:151], v138 offset:2048
	ds_read_b128 v[152:155], v138 offset:3072
	s_add_u32 s8, s6, s65
	s_addc_u32 s9, s7, s66
	ds_read_b128 v[156:159], v134
	ds_read_b128 v[164:167], v133
	ds_read_b128 v[172:175], v132
	ds_read_b128 v[180:183], v131
	ds_read_b128 v[160:163], v134 offset:1024
	ds_read_b128 v[168:171], v133 offset:1024
	ds_read_b128 v[176:179], v132 offset:1024
	ds_read_b128 v[184:187], v131 offset:1024
	s_mov_b32 m0, s76
	s_add_u32 s98, s8, s44
	s_addc_u32 s99, s9, s45
	global_load_lds_dwordx4 v129, s[98:99]
	s_mov_b32 m0, s75
	s_nop 0
	global_load_lds_dwordx4 v130, s[98:99]
	s_waitcnt lgkmcnt(8)
	s_barrier
	s_waitcnt lgkmcnt(7)
	v_mfma_f32_16x16x32_bf16 v[124:127], v[140:143], v[156:159], v[124:127]
	v_mfma_f32_16x16x32_bf16 v[120:123], v[148:151], v[156:159], v[120:123]
	s_waitcnt lgkmcnt(6)
	v_mfma_f32_16x16x32_bf16 v[116:119], v[140:143], v[164:167], v[116:119]
	v_mfma_f32_16x16x32_bf16 v[112:115], v[148:151], v[164:167], v[112:115]
	s_waitcnt lgkmcnt(5)
	v_mfma_f32_16x16x32_bf16 v[108:111], v[140:143], v[172:175], v[108:111]
	v_mfma_f32_16x16x32_bf16 v[104:107], v[148:151], v[172:175], v[104:107]
	s_waitcnt lgkmcnt(4)
	v_mfma_f32_16x16x32_bf16 v[100:103], v[140:143], v[180:183], v[100:103]
	v_mfma_f32_16x16x32_bf16 v[96:99], v[148:151], v[180:183], v[96:99]
	s_waitcnt lgkmcnt(3)
	v_mfma_f32_16x16x32_bf16 v[124:127], v[144:147], v[160:163], v[124:127]
	v_mfma_f32_16x16x32_bf16 v[120:123], v[152:155], v[160:163], v[120:123]
	s_waitcnt lgkmcnt(2)
	v_mfma_f32_16x16x32_bf16 v[116:119], v[144:147], v[168:171], v[116:119]
	v_mfma_f32_16x16x32_bf16 v[112:115], v[152:155], v[168:171], v[112:115]
	s_waitcnt lgkmcnt(1)
	v_mfma_f32_16x16x32_bf16 v[108:111], v[144:147], v[176:179], v[108:111]
	v_mfma_f32_16x16x32_bf16 v[104:107], v[152:155], v[176:179], v[104:107]
	s_waitcnt lgkmcnt(0)
	v_mfma_f32_16x16x32_bf16 v[100:103], v[144:147], v[184:187], v[100:103]
	v_mfma_f32_16x16x32_bf16 v[96:99], v[152:155], v[184:187], v[96:99]
	s_barrier
	s_add_u32 s10, s6, s36
	s_addc_u32 s11, s7, s37
	ds_read_b128 v[188:191], v137
	ds_read_b128 v[192:195], v137 offset:1024
	ds_read_b128 v[202:205], v137 offset:2048
	ds_read_b128 v[206:209], v137 offset:3072
	s_mov_b32 m0, s63
	s_add_u32 s98, s10, s46
	s_addc_u32 s99, s11, s47
	global_load_lds_dwordx4 v129, s[98:99]
	s_mov_b32 m0, s64
	s_nop 0
	global_load_lds_dwordx4 v130, s[98:99]
	s_barrier
	s_waitcnt lgkmcnt(3)
	v_mfma_f32_16x16x32_bf16 v[92:95], v[188:191], v[156:159], v[92:95]
	s_waitcnt lgkmcnt(1)
	v_mfma_f32_16x16x32_bf16 v[88:91], v[202:205], v[156:159], v[88:91]
	v_mfma_f32_16x16x32_bf16 v[84:87], v[188:191], v[164:167], v[84:87]
	v_mfma_f32_16x16x32_bf16 v[80:83], v[202:205], v[164:167], v[80:83]
	v_mfma_f32_16x16x32_bf16 v[76:79], v[188:191], v[172:175], v[76:79]
	v_mfma_f32_16x16x32_bf16 v[72:75], v[202:205], v[172:175], v[72:75]
	v_mfma_f32_16x16x32_bf16 v[68:71], v[188:191], v[180:183], v[68:71]
	v_mfma_f32_16x16x32_bf16 v[64:67], v[202:205], v[180:183], v[64:67]
	v_mfma_f32_16x16x32_bf16 v[92:95], v[192:195], v[160:163], v[92:95]
	s_waitcnt lgkmcnt(0)
	v_mfma_f32_16x16x32_bf16 v[88:91], v[206:209], v[160:163], v[88:91]
	v_mfma_f32_16x16x32_bf16 v[84:87], v[192:195], v[168:171], v[84:87]
	v_mfma_f32_16x16x32_bf16 v[80:83], v[206:209], v[168:171], v[80:83]
	v_mfma_f32_16x16x32_bf16 v[76:79], v[192:195], v[176:179], v[76:79]
	v_mfma_f32_16x16x32_bf16 v[72:75], v[206:209], v[176:179], v[72:75]
	v_mfma_f32_16x16x32_bf16 v[68:71], v[192:195], v[184:187], v[68:71]
	v_mfma_f32_16x16x32_bf16 v[64:67], v[206:209], v[184:187], v[64:67]
	s_barrier
	ds_read_b128 v[156:159], v134 offset:16384
	ds_read_b128 v[164:167], v133 offset:16384
	ds_read_b128 v[172:175], v132 offset:16384
	ds_read_b128 v[180:183], v131 offset:16384
	ds_read_b128 v[160:163], v134 offset:17408
	ds_read_b128 v[168:171], v133 offset:17408
	ds_read_b128 v[176:179], v132 offset:17408
	ds_read_b128 v[184:187], v131 offset:17408
	s_mov_b32 m0, s62
	s_add_u32 s98, s8, s48
	s_addc_u32 s99, s9, s49
	global_load_lds_dwordx4 v129, s[98:99]
	s_mov_b32 m0, s67
	s_nop 0
	global_load_lds_dwordx4 v130, s[98:99]
	s_barrier
	s_waitcnt lgkmcnt(7)
	v_mfma_f32_16x16x32_bf16 v[60:63], v[140:143], v[156:159], v[60:63]
	v_mfma_f32_16x16x32_bf16 v[56:59], v[148:151], v[156:159], v[56:59]
	s_waitcnt lgkmcnt(6)
	v_mfma_f32_16x16x32_bf16 v[52:55], v[140:143], v[164:167], v[52:55]
	v_mfma_f32_16x16x32_bf16 v[48:51], v[148:151], v[164:167], v[48:51]
	s_waitcnt lgkmcnt(5)
	v_mfma_f32_16x16x32_bf16 v[44:47], v[140:143], v[172:175], v[44:47]
	v_mfma_f32_16x16x32_bf16 v[40:43], v[148:151], v[172:175], v[40:43]
	s_waitcnt lgkmcnt(4)
	v_mfma_f32_16x16x32_bf16 v[36:39], v[140:143], v[180:183], v[36:39]
	v_mfma_f32_16x16x32_bf16 v[32:35], v[148:151], v[180:183], v[32:35]
	s_waitcnt lgkmcnt(3)
	v_mfma_f32_16x16x32_bf16 v[60:63], v[144:147], v[160:163], v[60:63]
	v_mfma_f32_16x16x32_bf16 v[56:59], v[152:155], v[160:163], v[56:59]
	s_waitcnt lgkmcnt(2)
	v_mfma_f32_16x16x32_bf16 v[52:55], v[144:147], v[168:171], v[52:55]
	v_mfma_f32_16x16x32_bf16 v[48:51], v[152:155], v[168:171], v[48:51]
	s_waitcnt lgkmcnt(1)
	v_mfma_f32_16x16x32_bf16 v[44:47], v[144:147], v[176:179], v[44:47]
	v_mfma_f32_16x16x32_bf16 v[40:43], v[152:155], v[176:179], v[40:43]
	s_waitcnt lgkmcnt(0)
	v_mfma_f32_16x16x32_bf16 v[36:39], v[144:147], v[184:187], v[36:39]
	v_mfma_f32_16x16x32_bf16 v[32:35], v[152:155], v[184:187], v[32:35]
	s_barrier
	s_mov_b32 m0, s68
	s_add_u32 s98, s10, s50
	s_addc_u32 s99, s11, s51
	global_load_lds_dwordx4 v129, s[98:99]
	s_mov_b32 m0, s69
	s_nop 0
	global_load_lds_dwordx4 v130, s[98:99]
	s_waitcnt vmcnt(6)
	s_barrier
	v_mfma_f32_16x16x32_bf16 v[28:31], v[188:191], v[156:159], v[28:31]
	v_mfma_f32_16x16x32_bf16 v[24:27], v[202:205], v[156:159], v[24:27]
	v_mfma_f32_16x16x32_bf16 v[20:23], v[188:191], v[164:167], v[20:23]
	v_mfma_f32_16x16x32_bf16 v[16:19], v[202:205], v[164:167], v[16:19]
	v_mfma_f32_16x16x32_bf16 v[12:15], v[188:191], v[172:175], v[12:15]
	v_mfma_f32_16x16x32_bf16 v[8:11], v[202:205], v[172:175], v[8:11]
	v_mfma_f32_16x16x32_bf16 v[4:7], v[188:191], v[180:183], v[4:7]
	v_mfma_f32_16x16x32_bf16 v[0:3], v[202:205], v[180:183], v[0:3]
	v_mfma_f32_16x16x32_bf16 v[28:31], v[192:195], v[160:163], v[28:31]
	v_mfma_f32_16x16x32_bf16 v[24:27], v[206:209], v[160:163], v[24:27]
	v_mfma_f32_16x16x32_bf16 v[20:23], v[192:195], v[168:171], v[20:23]
	v_mfma_f32_16x16x32_bf16 v[16:19], v[206:209], v[168:171], v[16:19]
	v_mfma_f32_16x16x32_bf16 v[12:15], v[192:195], v[176:179], v[12:15]
	v_mfma_f32_16x16x32_bf16 v[8:11], v[206:209], v[176:179], v[8:11]
	v_mfma_f32_16x16x32_bf16 v[4:7], v[192:195], v[184:187], v[4:7]
	v_mfma_f32_16x16x32_bf16 v[0:3], v[206:209], v[184:187], v[0:3]
	s_barrier
	ds_read_b128 v[140:143], v136
	ds_read_b128 v[144:147], v136 offset:1024
	ds_read_b128 v[148:151], v136 offset:2048
	ds_read_b128 v[152:155], v136 offset:3072
	ds_read_b128 v[156:159], v134 offset:32768
	ds_read_b128 v[164:167], v133 offset:32768
	ds_read_b128 v[172:175], v132 offset:32768
	ds_read_b128 v[180:183], v131 offset:32768
	ds_read_b128 v[160:163], v134 offset:33792
	ds_read_b128 v[168:171], v133 offset:33792
	ds_read_b128 v[176:179], v132 offset:33792
	ds_read_b128 v[184:187], v131 offset:33792
	s_mov_b32 m0, s70
	s_add_u32 s98, s8, s90
	s_addc_u32 s99, s9, s91
	global_load_lds_dwordx4 v129, s[98:99]
	s_mov_b32 m0, s71
	s_nop 0
	global_load_lds_dwordx4 v130, s[98:99]
	s_waitcnt lgkmcnt(8)
	s_barrier
	s_waitcnt lgkmcnt(7)
	v_mfma_f32_16x16x32_bf16 v[124:127], v[140:143], v[156:159], v[124:127]
	v_mfma_f32_16x16x32_bf16 v[120:123], v[148:151], v[156:159], v[120:123]
	s_waitcnt lgkmcnt(6)
	v_mfma_f32_16x16x32_bf16 v[116:119], v[140:143], v[164:167], v[116:119]
	v_mfma_f32_16x16x32_bf16 v[112:115], v[148:151], v[164:167], v[112:115]
	s_waitcnt lgkmcnt(5)
	v_mfma_f32_16x16x32_bf16 v[108:111], v[140:143], v[172:175], v[108:111]
	v_mfma_f32_16x16x32_bf16 v[104:107], v[148:151], v[172:175], v[104:107]
	s_waitcnt lgkmcnt(4)
	v_mfma_f32_16x16x32_bf16 v[100:103], v[140:143], v[180:183], v[100:103]
	v_mfma_f32_16x16x32_bf16 v[96:99], v[148:151], v[180:183], v[96:99]
	s_waitcnt lgkmcnt(3)
	v_mfma_f32_16x16x32_bf16 v[124:127], v[144:147], v[160:163], v[124:127]
	v_mfma_f32_16x16x32_bf16 v[120:123], v[152:155], v[160:163], v[120:123]
	s_waitcnt lgkmcnt(2)
	v_mfma_f32_16x16x32_bf16 v[116:119], v[144:147], v[168:171], v[116:119]
	v_mfma_f32_16x16x32_bf16 v[112:115], v[152:155], v[168:171], v[112:115]
	s_waitcnt lgkmcnt(1)
	v_mfma_f32_16x16x32_bf16 v[108:111], v[144:147], v[176:179], v[108:111]
	v_mfma_f32_16x16x32_bf16 v[104:107], v[152:155], v[176:179], v[104:107]
	s_waitcnt lgkmcnt(0)
	v_mfma_f32_16x16x32_bf16 v[100:103], v[144:147], v[184:187], v[100:103]
	v_mfma_f32_16x16x32_bf16 v[96:99], v[152:155], v[184:187], v[96:99]
	s_barrier
	ds_read_b128 v[188:191], v135
	ds_read_b128 v[192:195], v135 offset:1024
	ds_read_b128 v[202:205], v135 offset:2048
	ds_read_b128 v[206:209], v135 offset:3072
	s_mov_b32 m0, s28
	s_add_u32 s98, s10, s92
	s_addc_u32 s99, s11, s93
	global_load_lds_dwordx4 v129, s[98:99]
	s_mov_b32 m0, s29
	s_nop 0
	global_load_lds_dwordx4 v130, s[98:99]
	s_barrier
	s_waitcnt lgkmcnt(3)
	v_mfma_f32_16x16x32_bf16 v[92:95], v[188:191], v[156:159], v[92:95]
	s_waitcnt lgkmcnt(1)
	v_mfma_f32_16x16x32_bf16 v[88:91], v[202:205], v[156:159], v[88:91]
	v_mfma_f32_16x16x32_bf16 v[84:87], v[188:191], v[164:167], v[84:87]
	v_mfma_f32_16x16x32_bf16 v[80:83], v[202:205], v[164:167], v[80:83]
	v_mfma_f32_16x16x32_bf16 v[76:79], v[188:191], v[172:175], v[76:79]
	v_mfma_f32_16x16x32_bf16 v[72:75], v[202:205], v[172:175], v[72:75]
	v_mfma_f32_16x16x32_bf16 v[68:71], v[188:191], v[180:183], v[68:71]
	v_mfma_f32_16x16x32_bf16 v[64:67], v[202:205], v[180:183], v[64:67]
	v_mfma_f32_16x16x32_bf16 v[92:95], v[192:195], v[160:163], v[92:95]
	s_waitcnt lgkmcnt(0)
	v_mfma_f32_16x16x32_bf16 v[88:91], v[206:209], v[160:163], v[88:91]
	v_mfma_f32_16x16x32_bf16 v[84:87], v[192:195], v[168:171], v[84:87]
	v_mfma_f32_16x16x32_bf16 v[80:83], v[206:209], v[168:171], v[80:83]
	v_mfma_f32_16x16x32_bf16 v[76:79], v[192:195], v[176:179], v[76:79]
	v_mfma_f32_16x16x32_bf16 v[72:75], v[206:209], v[176:179], v[72:75]
	v_mfma_f32_16x16x32_bf16 v[68:71], v[192:195], v[184:187], v[68:71]
	v_mfma_f32_16x16x32_bf16 v[64:67], v[206:209], v[184:187], v[64:67]
	v_mov_b32_e32 v210, v130
	s_barrier
	ds_read_b128 v[156:159], v134 offset:49152
	ds_read_b128 v[164:167], v133 offset:49152
	ds_read_b128 v[172:175], v132 offset:49152
	ds_read_b128 v[180:183], v131 offset:49152
	ds_read_b128 v[160:163], v134 offset:50176
	ds_read_b128 v[168:171], v133 offset:50176
	ds_read_b128 v[176:179], v132 offset:50176
	ds_read_b128 v[184:187], v131 offset:50176
	v_mov_b32_e32 v211, v197
	s_mov_b32 m0, s72
	s_add_u32 s98, s8, s96
	s_addc_u32 s99, s9, s97
	global_load_lds_dwordx4 v129, s[98:99]
	s_mov_b32 m0, s73
	s_nop 0
	global_load_lds_dwordx4 v130, s[98:99]
	s_barrier
	s_waitcnt lgkmcnt(7)
	v_mfma_f32_16x16x32_bf16 v[60:63], v[140:143], v[156:159], v[60:63]
	v_mfma_f32_16x16x32_bf16 v[56:59], v[148:151], v[156:159], v[56:59]
	s_waitcnt lgkmcnt(6)
	v_mfma_f32_16x16x32_bf16 v[52:55], v[140:143], v[164:167], v[52:55]
	v_mfma_f32_16x16x32_bf16 v[48:51], v[148:151], v[164:167], v[48:51]
	s_waitcnt lgkmcnt(5)
	v_mfma_f32_16x16x32_bf16 v[44:47], v[140:143], v[172:175], v[44:47]
	v_mfma_f32_16x16x32_bf16 v[40:43], v[148:151], v[172:175], v[40:43]
	s_waitcnt lgkmcnt(4)
	v_mfma_f32_16x16x32_bf16 v[36:39], v[140:143], v[180:183], v[36:39]
	v_mfma_f32_16x16x32_bf16 v[32:35], v[148:151], v[180:183], v[32:35]
	s_waitcnt lgkmcnt(3)
	v_mfma_f32_16x16x32_bf16 v[60:63], v[144:147], v[160:163], v[60:63]
	v_mfma_f32_16x16x32_bf16 v[56:59], v[152:155], v[160:163], v[56:59]
	s_waitcnt lgkmcnt(2)
	v_mfma_f32_16x16x32_bf16 v[52:55], v[144:147], v[168:171], v[52:55]
	v_mfma_f32_16x16x32_bf16 v[48:51], v[152:155], v[168:171], v[48:51]
	s_waitcnt lgkmcnt(1)
	v_mfma_f32_16x16x32_bf16 v[44:47], v[144:147], v[176:179], v[44:47]
	v_mfma_f32_16x16x32_bf16 v[40:43], v[152:155], v[176:179], v[40:43]
	s_waitcnt lgkmcnt(0)
	v_mfma_f32_16x16x32_bf16 v[36:39], v[144:147], v[184:187], v[36:39]
	v_mfma_f32_16x16x32_bf16 v[32:35], v[152:155], v[184:187], v[32:35]
	s_barrier
	v_mov_b32_e32 v196, v129
	s_mov_b32 m0, s33
	s_add_u32 s98, s10, vcc_lo
	s_addc_u32 s99, s11, vcc_hi
	global_load_lds_dwordx4 v129, s[98:99]
	s_mov_b32 m0, s74
	s_nop 0
	global_load_lds_dwordx4 v130, s[98:99]
	s_waitcnt vmcnt(6)
	s_barrier
	v_mfma_f32_16x16x32_bf16 v[28:31], v[188:191], v[156:159], v[28:31]
	v_mfma_f32_16x16x32_bf16 v[24:27], v[202:205], v[156:159], v[24:27]
	v_mfma_f32_16x16x32_bf16 v[20:23], v[188:191], v[164:167], v[20:23]
	v_mfma_f32_16x16x32_bf16 v[16:19], v[202:205], v[164:167], v[16:19]
	v_mfma_f32_16x16x32_bf16 v[12:15], v[188:191], v[172:175], v[12:15]
	v_mfma_f32_16x16x32_bf16 v[8:11], v[202:205], v[172:175], v[8:11]
	v_mfma_f32_16x16x32_bf16 v[4:7], v[188:191], v[180:183], v[4:7]
	v_mfma_f32_16x16x32_bf16 v[0:3], v[202:205], v[180:183], v[0:3]
	v_mfma_f32_16x16x32_bf16 v[28:31], v[192:195], v[160:163], v[28:31]
	v_mfma_f32_16x16x32_bf16 v[24:27], v[206:209], v[160:163], v[24:27]
	v_mfma_f32_16x16x32_bf16 v[20:23], v[192:195], v[168:171], v[20:23]
	v_mfma_f32_16x16x32_bf16 v[16:19], v[206:209], v[168:171], v[16:19]
	v_mfma_f32_16x16x32_bf16 v[12:15], v[192:195], v[176:179], v[12:15]
	v_mfma_f32_16x16x32_bf16 v[8:11], v[206:209], v[176:179], v[8:11]
	v_mfma_f32_16x16x32_bf16 v[4:7], v[192:195], v[184:187], v[4:7]
	v_mfma_f32_16x16x32_bf16 v[0:3], v[206:209], v[184:187], v[0:3]
	s_add_i32 s38, s38, 2
	s_add_u32 s6, s6, 0x100
	s_addc_u32 s7, s7, 0
	s_cmpk_lt_u32 s38, 0x54
	s_barrier
	s_cbranch_scc1 .LBB0_138
	s_add_u32 s4, s4, 0x2b80
	s_addc_u32 s5, s5, 0
	s_mov_b32 m0, s76
	ds_read_b128 v[140:143], v138
	ds_read_b128 v[144:147], v138 offset:1024
	ds_read_b128 v[148:151], v138 offset:2048
	ds_read_b128 v[152:155], v138 offset:3072
	ds_read_b128 v[156:159], v134
	ds_read_b128 v[160:163], v134 offset:1024
	ds_read_b128 v[164:167], v133
	ds_read_b128 v[168:171], v133 offset:1024
	ds_read_b128 v[172:175], v132
	ds_read_b128 v[176:179], v132 offset:1024
	ds_read_b128 v[180:183], v131
	ds_read_b128 v[184:187], v131 offset:1024
	s_nop 0
	global_load_lds_dwordx4 v129, s[4:5]
	s_mov_b32 m0, s75
	s_nop 0
	global_load_lds_dwordx4 v130, s[4:5]
	s_barrier
	s_waitcnt lgkmcnt(0)
	s_setprio 1
	s_waitcnt lgkmcnt(0)
	v_mfma_f32_16x16x32_bf16 v[124:127], v[140:143], v[156:159], v[124:127]
	v_mfma_f32_16x16x32_bf16 v[120:123], v[148:151], v[156:159], v[120:123]
	v_mfma_f32_16x16x32_bf16 v[116:119], v[140:143], v[164:167], v[116:119]
	v_mfma_f32_16x16x32_bf16 v[112:115], v[148:151], v[164:167], v[112:115]
	v_mfma_f32_16x16x32_bf16 v[108:111], v[140:143], v[172:175], v[108:111]
	v_mfma_f32_16x16x32_bf16 v[100:103], v[140:143], v[180:183], v[100:103]
	v_mfma_f32_16x16x32_bf16 v[96:99], v[148:151], v[180:183], v[96:99]
	v_mfma_f32_16x16x32_bf16 v[124:127], v[144:147], v[160:163], v[124:127]
	v_mfma_f32_16x16x32_bf16 v[120:123], v[152:155], v[160:163], v[120:123]
	v_mfma_f32_16x16x32_bf16 v[116:119], v[144:147], v[168:171], v[116:119]
	v_mfma_f32_16x16x32_bf16 v[112:115], v[152:155], v[168:171], v[112:115]
	v_mfma_f32_16x16x32_bf16 v[108:111], v[144:147], v[176:179], v[108:111]
	v_mfma_f32_16x16x32_bf16 v[104:107], v[148:151], v[172:175], v[104:107]
	v_mfma_f32_16x16x32_bf16 v[100:103], v[144:147], v[184:187], v[100:103]
	v_mfma_f32_16x16x32_bf16 v[96:99], v[152:155], v[184:187], v[96:99]
	v_mfma_f32_16x16x32_bf16 v[188:191], v[152:155], v[176:179], v[104:107]
	s_setprio 0
	s_barrier
	s_nop 2
	ds_read_b128 v[104:107], v137
	ds_read_b128 v[192:195], v137 offset:1024
	ds_read_b128 v[202:205], v137 offset:2048
	ds_read_b128 v[206:209], v137 offset:3072
	s_barrier
	s_waitcnt lgkmcnt(0)
	s_setprio 1
	s_waitcnt lgkmcnt(0)
	v_mfma_f32_16x16x32_bf16 v[92:95], v[104:107], v[156:159], v[92:95]
	v_mfma_f32_16x16x32_bf16 v[88:91], v[202:205], v[156:159], v[88:91]
	v_mfma_f32_16x16x32_bf16 v[80:83], v[202:205], v[164:167], v[80:83]
	v_mfma_f32_16x16x32_bf16 v[72:75], v[202:205], v[172:175], v[72:75]
	v_mfma_f32_16x16x32_bf16 v[64:67], v[202:205], v[180:183], v[64:67]
	v_mfma_f32_16x16x32_bf16 v[92:95], v[192:195], v[160:163], v[92:95]
	v_mfma_f32_16x16x32_bf16 v[88:91], v[206:209], v[160:163], v[88:91]
	v_mfma_f32_16x16x32_bf16 v[84:87], v[104:107], v[164:167], v[84:87]
	v_mfma_f32_16x16x32_bf16 v[80:83], v[206:209], v[168:171], v[80:83]
	v_mfma_f32_16x16x32_bf16 v[76:79], v[104:107], v[172:175], v[76:79]
	v_mfma_f32_16x16x32_bf16 v[72:75], v[206:209], v[176:179], v[72:75]
	v_mfma_f32_16x16x32_bf16 v[68:71], v[104:107], v[180:183], v[68:71]
	v_mfma_f32_16x16x32_bf16 v[64:67], v[206:209], v[184:187], v[64:67]
	v_mfma_f32_16x16x32_bf16 v[156:159], v[192:195], v[168:171], v[84:87]
	v_mfma_f32_16x16x32_bf16 v[160:163], v[192:195], v[176:179], v[76:79]
	v_mfma_f32_16x16x32_bf16 v[164:167], v[192:195], v[184:187], v[68:71]
	s_setprio 0
	s_barrier
	s_nop 1
	ds_read_b128 v[68:71], v134 offset:16384
	ds_read_b128 v[76:79], v134 offset:17408
	ds_read_b128 v[84:87], v133 offset:16384
	ds_read_b128 v[168:171], v133 offset:17408
	ds_read_b128 v[172:175], v132 offset:16384
	ds_read_b128 v[176:179], v132 offset:17408
	ds_read_b128 v[180:183], v131 offset:16384
	ds_read_b128 v[184:187], v131 offset:17408
	s_waitcnt vmcnt(4)
	s_barrier
	s_waitcnt lgkmcnt(0)
	s_setprio 1
	s_waitcnt lgkmcnt(0)
	v_mfma_f32_16x16x32_bf16 v[60:63], v[140:143], v[68:71], v[60:63]
	v_mfma_f32_16x16x32_bf16 v[56:59], v[148:151], v[68:71], v[56:59]
	v_mfma_f32_16x16x32_bf16 v[48:51], v[148:151], v[84:87], v[48:51]
	v_mfma_f32_16x16x32_bf16 v[32:35], v[148:151], v[180:183], v[32:35]
	v_mfma_f32_16x16x32_bf16 v[60:63], v[144:147], v[76:79], v[60:63]
	v_mfma_f32_16x16x32_bf16 v[56:59], v[152:155], v[76:79], v[56:59]
	v_mfma_f32_16x16x32_bf16 v[52:55], v[140:143], v[84:87], v[52:55]
	v_mfma_f32_16x16x32_bf16 v[48:51], v[152:155], v[168:171], v[48:51]
	v_mfma_f32_16x16x32_bf16 v[44:47], v[140:143], v[172:175], v[44:47]
	v_mfma_f32_16x16x32_bf16 v[40:43], v[148:151], v[172:175], v[40:43]
	v_mfma_f32_16x16x32_bf16 v[36:39], v[140:143], v[180:183], v[36:39]
	v_mfma_f32_16x16x32_bf16 v[32:35], v[152:155], v[184:187], v[32:35]
	v_mfma_f32_16x16x32_bf16 v[210:213], v[144:147], v[168:171], v[52:55]
	v_mfma_f32_16x16x32_bf16 v[214:217], v[144:147], v[176:179], v[44:47]
	v_mfma_f32_16x16x32_bf16 v[218:221], v[152:155], v[176:179], v[40:43]
	v_mfma_f32_16x16x32_bf16 v[138:141], v[144:147], v[184:187], v[36:39]
	s_setprio 0
	s_setprio 1
	v_mfma_f32_16x16x32_bf16 v[24:27], v[202:205], v[68:71], v[24:27]
	v_mfma_f32_16x16x32_bf16 v[20:23], v[104:107], v[84:87], v[20:23]
	v_mfma_f32_16x16x32_bf16 v[28:31], v[104:107], v[68:71], v[28:31]
	v_mfma_f32_16x16x32_bf16 v[24:27], v[206:209], v[76:79], v[24:27]
	v_mfma_f32_16x16x32_bf16 v[20:23], v[192:195], v[168:171], v[20:23]
	v_mfma_f32_16x16x32_bf16 v[16:19], v[202:205], v[84:87], v[16:19]
	v_mfma_f32_16x16x32_bf16 v[12:15], v[104:107], v[172:175], v[12:15]
	v_mfma_f32_16x16x32_bf16 v[8:11], v[202:205], v[172:175], v[8:11]
	v_mfma_f32_16x16x32_bf16 v[4:7], v[104:107], v[180:183], v[4:7]
	v_mfma_f32_16x16x32_bf16 v[0:3], v[202:205], v[180:183], v[0:3]
	v_mfma_f32_16x16x32_bf16 v[142:145], v[192:195], v[76:79], v[28:31]
	v_mfma_f32_16x16x32_bf16 v[146:149], v[206:209], v[168:171], v[16:19]
	v_mfma_f32_16x16x32_bf16 v[150:153], v[192:195], v[176:179], v[12:15]
	v_mfma_f32_16x16x32_bf16 v[168:171], v[206:209], v[176:179], v[8:11]
	v_mfma_f32_16x16x32_bf16 v[172:175], v[192:195], v[184:187], v[4:7]
	v_mfma_f32_16x16x32_bf16 v[176:179], v[206:209], v[184:187], v[0:3]
	s_setprio 0
	s_barrier
	ds_read_b128 v[16:19], v136
	ds_read_b128 v[180:183], v136 offset:1024
	ds_read_b128 v[184:187], v136 offset:2048
	ds_read_b128 v[192:195], v136 offset:3072
	ds_read_b128 v[0:3], v134 offset:32768
	ds_read_b128 v[4:7], v134 offset:33792
	ds_read_b128 v[8:11], v133 offset:32768
	ds_read_b128 v[12:15], v133 offset:33792
	ds_read_b128 v[44:47], v132 offset:32768
	ds_read_b128 v[202:205], v132 offset:33792
	ds_read_b128 v[206:209], v131 offset:32768
	ds_read_b128 v[222:225], v131 offset:33792
	s_waitcnt vmcnt(2)
	s_barrier
	s_waitcnt lgkmcnt(0)
	s_setprio 1
	s_waitcnt lgkmcnt(0)
	v_mfma_f32_16x16x32_bf16 v[28:31], v[16:19], v[0:3], v[124:127]
	v_mfma_f32_16x16x32_bf16 v[52:55], v[180:183], v[4:7], v[28:31]
	v_mfma_f32_16x16x32_bf16 v[28:31], v[184:187], v[0:3], v[120:123]
	v_mfma_f32_16x16x32_bf16 v[104:107], v[192:195], v[4:7], v[28:31]
	v_mfma_f32_16x16x32_bf16 v[28:31], v[16:19], v[8:11], v[116:119]
	v_mfma_f32_16x16x32_bf16 v[68:71], v[180:183], v[12:15], v[28:31]
	v_mfma_f32_16x16x32_bf16 v[28:31], v[184:187], v[8:11], v[112:115]
	v_mfma_f32_16x16x32_bf16 v[116:119], v[192:195], v[12:15], v[28:31]
	v_mfma_f32_16x16x32_bf16 v[28:31], v[16:19], v[44:47], v[108:111]
	v_mfma_f32_16x16x32_bf16 v[76:79], v[180:183], v[202:205], v[28:31]
	v_mfma_f32_16x16x32_bf16 v[28:31], v[184:187], v[44:47], v[188:191]
	v_mfma_f32_16x16x32_bf16 v[108:111], v[192:195], v[202:205], v[28:31]
	v_mfma_f32_16x16x32_bf16 v[28:31], v[16:19], v[206:209], v[100:103]
	v_mfma_f32_16x16x32_bf16 v[84:87], v[180:183], v[222:225], v[28:31]
	v_mfma_f32_16x16x32_bf16 v[28:31], v[184:187], v[206:209], v[96:99]
	v_mfma_f32_16x16x32_bf16 v[96:99], v[192:195], v[222:225], v[28:31]
	s_setprio 0
	s_barrier
	ds_read_b128 v[188:191], v135
	ds_read_b128 v[228:231], v135 offset:1024
	ds_read_b128 v[232:235], v135 offset:2048
	ds_read_b128 v[236:239], v135 offset:3072
	s_waitcnt vmcnt(0)
	s_barrier
	s_waitcnt lgkmcnt(0)
	s_setprio 1
	s_waitcnt lgkmcnt(0)
	v_mfma_f32_16x16x32_bf16 v[28:31], v[188:191], v[0:3], v[92:95]
	v_mfma_f32_16x16x32_bf16 v[0:3], v[232:235], v[0:3], v[88:91]
	v_mfma_f32_16x16x32_bf16 v[28:31], v[228:231], v[4:7], v[28:31]
	v_mfma_f32_16x16x32_bf16 v[0:3], v[236:239], v[4:7], v[0:3]
	v_mfma_f32_16x16x32_bf16 v[4:7], v[188:191], v[8:11], v[156:159]
	v_mfma_f32_16x16x32_bf16 v[36:39], v[228:231], v[12:15], v[4:7]
	v_mfma_f32_16x16x32_bf16 v[4:7], v[232:235], v[8:11], v[80:83]
	v_mfma_f32_16x16x32_bf16 v[4:7], v[236:239], v[12:15], v[4:7]
	v_mfma_f32_16x16x32_bf16 v[8:11], v[188:191], v[44:47], v[160:163]
	v_mfma_f32_16x16x32_bf16 v[12:15], v[188:191], v[206:209], v[164:167]
	v_mfma_f32_16x16x32_bf16 v[40:43], v[228:231], v[202:205], v[8:11]
	v_mfma_f32_16x16x32_bf16 v[8:11], v[232:235], v[44:47], v[72:75]
	v_mfma_f32_16x16x32_bf16 v[44:47], v[228:231], v[222:225], v[12:15]
	v_mfma_f32_16x16x32_bf16 v[12:15], v[232:235], v[206:209], v[64:67]
	v_mfma_f32_16x16x32_bf16 v[8:11], v[236:239], v[202:205], v[8:11]
	v_mfma_f32_16x16x32_bf16 v[12:15], v[236:239], v[222:225], v[12:15]
	s_setprio 0
	s_barrier
	ds_read_b128 v[64:67], v134 offset:49152
	ds_read_b128 v[134:137], v134 offset:50176
	ds_read_b128 v[154:157], v133 offset:49152
	ds_read_b128 v[158:161], v133 offset:50176
	ds_read_b128 v[162:165], v132 offset:49152
	ds_read_b128 v[202:205], v132 offset:50176
	ds_read_b128 v[206:209], v131 offset:49152
	ds_read_b128 v[130:133], v131 offset:50176
	s_barrier
	s_waitcnt lgkmcnt(0)
	s_setprio 1
	s_waitcnt lgkmcnt(0)
	v_mfma_f32_16x16x32_bf16 v[56:59], v[184:187], v[64:67], v[56:59]
	v_mfma_f32_16x16x32_bf16 v[48:51], v[184:187], v[154:157], v[48:51]
	v_mfma_f32_16x16x32_bf16 v[60:63], v[16:19], v[64:67], v[60:63]
	v_mfma_f32_16x16x32_bf16 v[92:95], v[192:195], v[134:137], v[56:59]
	v_mfma_f32_16x16x32_bf16 v[56:59], v[16:19], v[154:157], v[210:213]
	v_mfma_f32_16x16x32_bf16 v[88:91], v[192:195], v[158:161], v[48:51]
	v_mfma_f32_16x16x32_bf16 v[48:51], v[16:19], v[162:165], v[214:217]
	v_mfma_f32_16x16x32_bf16 v[16:19], v[16:19], v[206:209], v[138:141]
	v_mfma_f32_16x16x32_bf16 v[120:123], v[180:183], v[202:205], v[48:51]
	v_mfma_f32_16x16x32_bf16 v[48:51], v[184:187], v[162:165], v[218:221]
	v_mfma_f32_16x16x32_bf16 v[124:127], v[180:183], v[130:133], v[16:19]
	v_mfma_f32_16x16x32_bf16 v[16:19], v[184:187], v[206:209], v[32:35]
	v_mfma_f32_16x16x32_bf16 v[100:103], v[180:183], v[134:137], v[60:63]
	v_mfma_f32_16x16x32_bf16 v[112:115], v[180:183], v[158:161], v[56:59]
	v_mfma_f32_16x16x32_bf16 v[80:83], v[192:195], v[202:205], v[48:51]
	v_mfma_f32_16x16x32_bf16 v[72:75], v[192:195], v[130:133], v[16:19]
	s_setprio 0
	s_setprio 1
	v_mfma_f32_16x16x32_bf16 v[16:19], v[188:191], v[64:67], v[142:145]
	v_mfma_f32_16x16x32_bf16 v[48:51], v[228:231], v[134:137], v[16:19]
	v_mfma_f32_16x16x32_bf16 v[16:19], v[232:235], v[64:67], v[24:27]
	v_mfma_f32_16x16x32_bf16 v[20:23], v[188:191], v[154:157], v[20:23]
	v_mfma_f32_16x16x32_bf16 v[24:27], v[188:191], v[162:165], v[150:153]
	v_mfma_f32_16x16x32_bf16 v[32:35], v[188:191], v[206:209], v[172:175]
	v_mfma_f32_16x16x32_bf16 v[56:59], v[228:231], v[158:161], v[20:23]
	v_mfma_f32_16x16x32_bf16 v[20:23], v[232:235], v[154:157], v[146:149]
	v_mfma_f32_16x16x32_bf16 v[60:63], v[228:231], v[202:205], v[24:27]
	v_mfma_f32_16x16x32_bf16 v[24:27], v[232:235], v[162:165], v[168:171]
	v_mfma_f32_16x16x32_bf16 v[64:67], v[228:231], v[130:133], v[32:35]
	v_mfma_f32_16x16x32_bf16 v[32:35], v[232:235], v[206:209], v[176:179]
	v_mfma_f32_16x16x32_bf16 v[16:19], v[236:239], v[134:137], v[16:19]
	v_mfma_f32_16x16x32_bf16 v[20:23], v[236:239], v[158:161], v[20:23]
	v_mfma_f32_16x16x32_bf16 v[24:27], v[236:239], v[202:205], v[24:27]
	v_mfma_f32_16x16x32_bf16 v[32:35], v[236:239], v[130:133], v[32:35]
	s_setprio 0
	s_movk_i32 s4, 0x100
	v_cmp_gt_u32_e32 vcc, s4, v128
	s_barrier
	s_and_saveexec_b64 s[4:5], vcc
	s_cbranch_execz .LBB0_95
	s_barrier
	s_branch .LBB0_95

.Lhf_192:
	ds_read_b128 v[140:143], v129
	ds_read_b128 v[144:147], v129 offset:1024
	ds_read_b128 v[148:151], v129 offset:2048
	ds_read_b128 v[152:155], v129 offset:3072
	s_add_u32 s28, s56, s4
	s_addc_u32 s29, s57, s5
	ds_read_b128 v[156:159], v136
	ds_read_b128 v[164:167], v135
	ds_read_b128 v[172:175], v134
	ds_read_b128 v[180:183], v133
	ds_read_b128 v[160:163], v136 offset:1024
	ds_read_b128 v[168:171], v135 offset:1024
	ds_read_b128 v[176:179], v134 offset:1024
	ds_read_b128 v[184:187], v133 offset:1024
	s_add_i32 s40, s52, 0xc000
	s_mov_b32 m0, s40
	s_add_i32 s39, s52, 0xe000
	s_mov_b32 m0, s39
	s_nop 0
	s_waitcnt lgkmcnt(8)
	s_barrier
	s_waitcnt lgkmcnt(7)
	v_mfma_f32_16x16x32_bf16 v[124:127], v[140:143], v[156:159], v[124:127]
	v_mfma_f32_16x16x32_bf16 v[120:123], v[148:151], v[156:159], v[120:123]
	s_waitcnt lgkmcnt(6)
	v_mfma_f32_16x16x32_bf16 v[116:119], v[140:143], v[164:167], v[116:119]
	v_mfma_f32_16x16x32_bf16 v[112:115], v[148:151], v[164:167], v[112:115]
	s_waitcnt lgkmcnt(5)
	v_mfma_f32_16x16x32_bf16 v[108:111], v[140:143], v[172:175], v[108:111]
	v_mfma_f32_16x16x32_bf16 v[104:107], v[148:151], v[172:175], v[104:107]
	s_waitcnt lgkmcnt(4)
	v_mfma_f32_16x16x32_bf16 v[100:103], v[140:143], v[180:183], v[100:103]
	v_mfma_f32_16x16x32_bf16 v[96:99], v[148:151], v[180:183], v[96:99]
	s_waitcnt lgkmcnt(3)
	v_mfma_f32_16x16x32_bf16 v[124:127], v[144:147], v[160:163], v[124:127]
	v_mfma_f32_16x16x32_bf16 v[120:123], v[152:155], v[160:163], v[120:123]
	s_waitcnt lgkmcnt(2)
	v_mfma_f32_16x16x32_bf16 v[116:119], v[144:147], v[168:171], v[116:119]
	v_mfma_f32_16x16x32_bf16 v[112:115], v[152:155], v[168:171], v[112:115]
	s_waitcnt lgkmcnt(1)
	v_mfma_f32_16x16x32_bf16 v[108:111], v[144:147], v[176:179], v[108:111]
	v_mfma_f32_16x16x32_bf16 v[104:107], v[152:155], v[176:179], v[104:107]
	s_waitcnt lgkmcnt(0)
	v_mfma_f32_16x16x32_bf16 v[100:103], v[144:147], v[184:187], v[100:103]
	v_mfma_f32_16x16x32_bf16 v[96:99], v[152:155], v[184:187], v[96:99]
	s_barrier
	s_add_u32 s58, s56, s36
	s_addc_u32 s59, s57, s37
	ds_read_b128 v[188:191], v139
	ds_read_b128 v[192:195], v139 offset:1024
	ds_read_b128 v[202:205], v139 offset:2048
	ds_read_b128 v[206:209], v139 offset:3072
	s_add_i32 m0, s52, 0x10000
	s_add_u32 s98, s58, s46
	s_addc_u32 s99, s59, s47
	global_load_lds_dwordx4 v128, s[98:99]
	s_add_i32 m0, s52, 0x12000
	s_nop 0
	global_load_lds_dwordx4 v130, s[98:99]
	s_barrier
	s_waitcnt lgkmcnt(3)
	v_mfma_f32_16x16x32_bf16 v[92:95], v[188:191], v[156:159], v[92:95]
	s_waitcnt lgkmcnt(1)
	v_mfma_f32_16x16x32_bf16 v[88:91], v[202:205], v[156:159], v[88:91]
	v_mfma_f32_16x16x32_bf16 v[84:87], v[188:191], v[164:167], v[84:87]
	v_mfma_f32_16x16x32_bf16 v[80:83], v[202:205], v[164:167], v[80:83]
	v_mfma_f32_16x16x32_bf16 v[76:79], v[188:191], v[172:175], v[76:79]
	v_mfma_f32_16x16x32_bf16 v[72:75], v[202:205], v[172:175], v[72:75]
	v_mfma_f32_16x16x32_bf16 v[68:71], v[188:191], v[180:183], v[68:71]
	v_mfma_f32_16x16x32_bf16 v[64:67], v[202:205], v[180:183], v[64:67]
	v_mfma_f32_16x16x32_bf16 v[92:95], v[192:195], v[160:163], v[92:95]
	s_waitcnt lgkmcnt(0)
	v_mfma_f32_16x16x32_bf16 v[88:91], v[206:209], v[160:163], v[88:91]
	v_mfma_f32_16x16x32_bf16 v[84:87], v[192:195], v[168:171], v[84:87]
	v_mfma_f32_16x16x32_bf16 v[80:83], v[206:209], v[168:171], v[80:83]
	v_mfma_f32_16x16x32_bf16 v[76:79], v[192:195], v[176:179], v[76:79]
	v_mfma_f32_16x16x32_bf16 v[72:75], v[206:209], v[176:179], v[72:75]
	v_mfma_f32_16x16x32_bf16 v[68:71], v[192:195], v[184:187], v[68:71]
	v_mfma_f32_16x16x32_bf16 v[64:67], v[206:209], v[184:187], v[64:67]
	s_barrier
	s_mov_b32 m0, s52
	s_add_u32 s98, s28, s48
	s_addc_u32 s99, s29, s49
	global_load_lds_dwordx4 v128, s[98:99]
	s_add_i32 m0, s52, 0x2000
	s_nop 0
	global_load_lds_dwordx4 v130, s[98:99]
	s_waitcnt vmcnt(4)
	s_barrier
	s_add_i32 m0, s52, 0x14000
	s_add_u32 s98, s58, s50
	s_addc_u32 s99, s59, s51
	global_load_lds_dwordx4 v128, s[98:99]
	s_add_i32 m0, s52, 0x16000
	s_nop 0
	global_load_lds_dwordx4 v130, s[98:99]
	s_barrier
	ds_read_b128 v[140:143], v138
	ds_read_b128 v[144:147], v138 offset:1024
	ds_read_b128 v[148:151], v138 offset:2048
	ds_read_b128 v[156:159], v136 offset:32768
	ds_read_b128 v[164:167], v135 offset:32768
	ds_read_b128 v[172:175], v134 offset:32768
	ds_read_b128 v[152:155], v138 offset:3072
	ds_read_b128 v[160:163], v136 offset:33792
	ds_read_b128 v[168:171], v135 offset:33792
	ds_read_b128 v[176:179], v134 offset:33792
	ds_read_b128 v[180:183], v133 offset:32768
	ds_read_b128 v[184:187], v133 offset:33792
	s_add_i32 m0, s52, 0x4000
	s_add_i32 m0, s52, 0x6000
	s_nop 0
	s_waitcnt lgkmcnt(8)
	s_barrier
	s_waitcnt lgkmcnt(8)
	v_mfma_f32_16x16x32_bf16 v[124:127], v[140:143], v[156:159], v[124:127]
	v_mfma_f32_16x16x32_bf16 v[120:123], v[148:151], v[156:159], v[120:123]
	s_waitcnt lgkmcnt(7)
	v_mfma_f32_16x16x32_bf16 v[116:119], v[140:143], v[164:167], v[116:119]
	v_mfma_f32_16x16x32_bf16 v[112:115], v[148:151], v[164:167], v[112:115]
	s_waitcnt lgkmcnt(6)
	v_mfma_f32_16x16x32_bf16 v[108:111], v[140:143], v[172:175], v[108:111]
	v_mfma_f32_16x16x32_bf16 v[104:107], v[148:151], v[172:175], v[104:107]
	s_waitcnt lgkmcnt(1)
	v_mfma_f32_16x16x32_bf16 v[100:103], v[140:143], v[180:183], v[100:103]
	v_mfma_f32_16x16x32_bf16 v[96:99], v[148:151], v[180:183], v[96:99]
	v_mfma_f32_16x16x32_bf16 v[124:127], v[144:147], v[160:163], v[124:127]
	v_mfma_f32_16x16x32_bf16 v[120:123], v[152:155], v[160:163], v[120:123]
	v_mfma_f32_16x16x32_bf16 v[116:119], v[144:147], v[168:171], v[116:119]
	v_mfma_f32_16x16x32_bf16 v[112:115], v[152:155], v[168:171], v[112:115]
	v_mfma_f32_16x16x32_bf16 v[108:111], v[144:147], v[176:179], v[108:111]
	v_mfma_f32_16x16x32_bf16 v[104:107], v[152:155], v[176:179], v[104:107]
	s_waitcnt lgkmcnt(0)
	v_mfma_f32_16x16x32_bf16 v[100:103], v[144:147], v[184:187], v[100:103]
	v_mfma_f32_16x16x32_bf16 v[96:99], v[152:155], v[184:187], v[96:99]
	s_barrier
	ds_read_b128 v[188:191], v137
	ds_read_b128 v[192:195], v137 offset:1024
	ds_read_b128 v[202:205], v137 offset:2048
	ds_read_b128 v[206:209], v137 offset:3072
	s_mov_b32 m0, s7
	s_add_u32 s98, s58, s68
	s_addc_u32 s99, s59, s69
	global_load_lds_dwordx4 v128, s[98:99]
	s_mov_b32 m0, s53
	s_nop 0
	global_load_lds_dwordx4 v130, s[98:99]
	s_barrier
	s_waitcnt lgkmcnt(3)
	v_mfma_f32_16x16x32_bf16 v[92:95], v[188:191], v[156:159], v[92:95]
	s_waitcnt lgkmcnt(1)
	v_mfma_f32_16x16x32_bf16 v[88:91], v[202:205], v[156:159], v[88:91]
	v_mfma_f32_16x16x32_bf16 v[84:87], v[188:191], v[164:167], v[84:87]
	v_mfma_f32_16x16x32_bf16 v[80:83], v[202:205], v[164:167], v[80:83]
	v_mfma_f32_16x16x32_bf16 v[76:79], v[188:191], v[172:175], v[76:79]
	v_mfma_f32_16x16x32_bf16 v[72:75], v[202:205], v[172:175], v[72:75]
	v_mfma_f32_16x16x32_bf16 v[68:71], v[188:191], v[180:183], v[68:71]
	v_mfma_f32_16x16x32_bf16 v[64:67], v[202:205], v[180:183], v[64:67]
	v_mfma_f32_16x16x32_bf16 v[92:95], v[192:195], v[160:163], v[92:95]
	s_waitcnt lgkmcnt(0)
	v_mfma_f32_16x16x32_bf16 v[88:91], v[206:209], v[160:163], v[88:91]
	v_mfma_f32_16x16x32_bf16 v[84:87], v[192:195], v[168:171], v[84:87]
	v_mfma_f32_16x16x32_bf16 v[80:83], v[206:209], v[168:171], v[80:83]
	v_mfma_f32_16x16x32_bf16 v[76:79], v[192:195], v[176:179], v[76:79]
	v_mfma_f32_16x16x32_bf16 v[72:75], v[206:209], v[176:179], v[72:75]
	v_mfma_f32_16x16x32_bf16 v[68:71], v[192:195], v[184:187], v[68:71]
	v_mfma_f32_16x16x32_bf16 v[64:67], v[206:209], v[184:187], v[64:67]
	v_mov_b32_e32 v210, v130
	s_barrier
	v_mov_b32_e32 v211, v197
	s_mov_b32 m0, s9
	s_add_u32 s98, s28, s70
	s_addc_u32 s99, s29, s71
	global_load_lds_dwordx4 v128, s[98:99]
	s_mov_b32 m0, s33
	s_nop 0
	global_load_lds_dwordx4 v130, s[98:99]
	s_waitcnt vmcnt(4)
	s_barrier
	v_mov_b32_e32 v196, v128
	s_mov_b32 m0, s65
	s_add_u32 s98, s58, s72
	s_addc_u32 s99, s59, s73
	global_load_lds_dwordx4 v128, s[98:99]
	s_mov_b32 m0, s66
	s_nop 0
	global_load_lds_dwordx4 v130, s[98:99]
	s_barrier
	s_add_i32 s38, s38, 2
	s_add_u32 s56, s56, 0x100
	s_addc_u32 s57, s57, 0
	s_cmp_lt_u32 s38, 28
	s_cbranch_scc1 .Lhf_192
	s_lshl_b64 s[4:5], s[10:11], 12
	v_readlane_b32 s10, v254, 12
	v_readlane_b32 s11, v254, 13
	s_add_u32 s4, s10, s4
	s_addc_u32 s5, s11, s5
	ds_read_b128 v[140:143], v129
	ds_read_b128 v[144:147], v129 offset:1024
	ds_read_b128 v[148:151], v129 offset:2048
	ds_read_b128 v[152:155], v129 offset:3072
	ds_read_b128 v[156:159], v136
	ds_read_b128 v[160:163], v136 offset:1024
	ds_read_b128 v[164:167], v135
	ds_read_b128 v[168:171], v135 offset:1024
	ds_read_b128 v[172:175], v134
	ds_read_b128 v[176:179], v134 offset:1024
	ds_read_b128 v[180:183], v133
	ds_read_b128 v[184:187], v133 offset:1024
	v_mov_b32_e32 v129, v197
	v_lshl_add_u64 v[128:129], s[4:5], 0, v[128:129]
	s_mov_b64 s[10:11], 0xf80
	s_mov_b32 m0, s40
	v_lshl_add_u64 v[128:129], v[128:129], 0, s[10:11]
	v_mov_b32_e32 v131, v197
	v_lshl_add_u64 v[128:129], s[4:5], 0, v[130:131]
	v_lshl_add_u64 v[128:129], v[128:129], 0, s[10:11]
	s_mov_b32 m0, s39
	s_nop 0
	s_barrier
	s_waitcnt lgkmcnt(0)
	s_setprio 1
	s_waitcnt lgkmcnt(0)
	v_mfma_f32_16x16x32_bf16 v[124:127], v[140:143], v[156:159], v[124:127]
	v_mfma_f32_16x16x32_bf16 v[116:119], v[140:143], v[164:167], v[116:119]
	v_mfma_f32_16x16x32_bf16 v[112:115], v[148:151], v[164:167], v[112:115]
	v_mfma_f32_16x16x32_bf16 v[108:111], v[140:143], v[172:175], v[108:111]
	v_mfma_f32_16x16x32_bf16 v[104:107], v[148:151], v[172:175], v[104:107]
	v_mfma_f32_16x16x32_bf16 v[100:103], v[140:143], v[180:183], v[100:103]
	v_mfma_f32_16x16x32_bf16 v[96:99], v[148:151], v[180:183], v[96:99]
	v_mfma_f32_16x16x32_bf16 v[124:127], v[144:147], v[160:163], v[124:127]
	v_mfma_f32_16x16x32_bf16 v[120:123], v[148:151], v[156:159], v[120:123]
	v_mfma_f32_16x16x32_bf16 v[116:119], v[144:147], v[168:171], v[116:119]
	v_mfma_f32_16x16x32_bf16 v[112:115], v[152:155], v[168:171], v[112:115]
	v_mfma_f32_16x16x32_bf16 v[108:111], v[144:147], v[176:179], v[108:111]
	v_mfma_f32_16x16x32_bf16 v[104:107], v[152:155], v[176:179], v[104:107]
	v_mfma_f32_16x16x32_bf16 v[100:103], v[144:147], v[184:187], v[100:103]
	v_mfma_f32_16x16x32_bf16 v[96:99], v[152:155], v[184:187], v[96:99]
	v_mfma_f32_16x16x32_bf16 v[128:131], v[152:155], v[160:163], v[120:123]
	s_setprio 0
	s_barrier
	s_nop 0
	ds_read_b128 v[120:123], v139
	ds_read_b128 v[188:191], v139 offset:1024
	ds_read_b128 v[192:195], v139 offset:2048
	ds_read_b128 v[202:205], v139 offset:3072
	s_barrier
	s_waitcnt lgkmcnt(0)
	s_setprio 1
	s_waitcnt lgkmcnt(0)
	v_mfma_f32_16x16x32_bf16 v[76:79], v[120:123], v[172:175], v[76:79]
	v_mfma_f32_16x16x32_bf16 v[68:71], v[120:123], v[180:183], v[68:71]
	v_mfma_f32_16x16x32_bf16 v[64:67], v[192:195], v[180:183], v[64:67]
	v_mfma_f32_16x16x32_bf16 v[92:95], v[120:123], v[156:159], v[92:95]
	v_mfma_f32_16x16x32_bf16 v[88:91], v[192:195], v[156:159], v[88:91]
	v_mfma_f32_16x16x32_bf16 v[84:87], v[120:123], v[164:167], v[84:87]
	v_mfma_f32_16x16x32_bf16 v[80:83], v[192:195], v[164:167], v[80:83]
	v_mfma_f32_16x16x32_bf16 v[76:79], v[188:191], v[176:179], v[76:79]
	v_mfma_f32_16x16x32_bf16 v[72:75], v[192:195], v[172:175], v[72:75]
	v_mfma_f32_16x16x32_bf16 v[68:71], v[188:191], v[184:187], v[68:71]
	v_mfma_f32_16x16x32_bf16 v[64:67], v[202:205], v[184:187], v[64:67]
	v_mfma_f32_16x16x32_bf16 v[206:209], v[188:191], v[160:163], v[92:95]
	v_mfma_f32_16x16x32_bf16 v[156:159], v[202:205], v[160:163], v[88:91]
	v_mfma_f32_16x16x32_bf16 v[160:163], v[188:191], v[168:171], v[84:87]
	v_mfma_f32_16x16x32_bf16 v[164:167], v[202:205], v[168:171], v[80:83]
	v_mfma_f32_16x16x32_bf16 v[168:171], v[202:205], v[176:179], v[72:75]
	s_setprio 0
	s_barrier
	s_nop 0
	s_waitcnt vmcnt(2)
	s_barrier
	s_waitcnt lgkmcnt(0)
	s_setprio 1
	s_waitcnt lgkmcnt(0)
	s_setprio 0
	s_setprio 1
	s_setprio 0
	s_barrier
	s_nop 0
	ds_read_b128 v[8:11], v138
	ds_read_b128 v[16:19], v138 offset:1024
	ds_read_b128 v[176:179], v138 offset:2048
	ds_read_b128 v[180:183], v138 offset:3072
	ds_read_b128 v[20:23], v136 offset:32768
	ds_read_b128 v[24:27], v136 offset:33792
	ds_read_b128 v[28:31], v135 offset:32768
	ds_read_b128 v[56:59], v135 offset:33792
	ds_read_b128 v[188:191], v134 offset:32768
	ds_read_b128 v[192:195], v134 offset:33792
	ds_read_b128 v[202:205], v133 offset:32768
	ds_read_b128 v[210:213], v133 offset:33792
	s_waitcnt vmcnt(0)
	s_barrier
	s_waitcnt lgkmcnt(0)
	s_setprio 1
	s_waitcnt lgkmcnt(0)
	v_mfma_f32_16x16x32_bf16 v[72:75], v[8:11], v[20:23], v[124:127]
	v_mfma_f32_16x16x32_bf16 v[120:123], v[16:19], v[24:27], v[72:75]
	v_mfma_f32_16x16x32_bf16 v[72:75], v[176:179], v[20:23], v[128:131]
	v_mfma_f32_16x16x32_bf16 v[124:127], v[180:183], v[24:27], v[72:75]
	v_mfma_f32_16x16x32_bf16 v[72:75], v[8:11], v[28:31], v[116:119]
	v_mfma_f32_16x16x32_bf16 v[116:119], v[16:19], v[56:59], v[72:75]
	v_mfma_f32_16x16x32_bf16 v[72:75], v[176:179], v[28:31], v[112:115]
	v_mfma_f32_16x16x32_bf16 v[112:115], v[180:183], v[56:59], v[72:75]
	v_mfma_f32_16x16x32_bf16 v[72:75], v[8:11], v[188:191], v[108:111]
	v_mfma_f32_16x16x32_bf16 v[88:91], v[16:19], v[192:195], v[72:75]
	v_mfma_f32_16x16x32_bf16 v[72:75], v[176:179], v[188:191], v[104:107]
	v_mfma_f32_16x16x32_bf16 v[92:95], v[180:183], v[192:195], v[72:75]
	v_mfma_f32_16x16x32_bf16 v[72:75], v[8:11], v[202:205], v[100:103]
	v_mfma_f32_16x16x32_bf16 v[84:87], v[16:19], v[210:213], v[72:75]
	v_mfma_f32_16x16x32_bf16 v[72:75], v[176:179], v[202:205], v[96:99]
	v_mfma_f32_16x16x32_bf16 v[80:83], v[180:183], v[210:213], v[72:75]
	s_setprio 0
	s_barrier
	ds_read_b128 v[128:131], v137
	ds_read_b128 v[214:217], v137 offset:1024
	ds_read_b128 v[218:221], v137 offset:2048
	ds_read_b128 v[222:225], v137 offset:3072
	s_waitcnt vmcnt(0)
	s_barrier
	s_waitcnt lgkmcnt(0)
	s_setprio 1
	s_waitcnt lgkmcnt(0)
	v_mfma_f32_16x16x32_bf16 v[72:75], v[128:131], v[20:23], v[206:209]
	v_mfma_f32_16x16x32_bf16 v[20:23], v[218:221], v[20:23], v[156:159]
	v_mfma_f32_16x16x32_bf16 v[108:111], v[222:225], v[24:27], v[20:23]
	v_mfma_f32_16x16x32_bf16 v[20:23], v[128:131], v[28:31], v[160:163]
	v_mfma_f32_16x16x32_bf16 v[100:103], v[214:217], v[56:59], v[20:23]
	v_mfma_f32_16x16x32_bf16 v[20:23], v[218:221], v[28:31], v[164:167]
	v_mfma_f32_16x16x32_bf16 v[96:99], v[222:225], v[56:59], v[20:23]
	v_mfma_f32_16x16x32_bf16 v[20:23], v[128:131], v[188:191], v[76:79]
	v_mfma_f32_16x16x32_bf16 v[104:107], v[214:217], v[24:27], v[72:75]
	v_mfma_f32_16x16x32_bf16 v[72:75], v[214:217], v[192:195], v[20:23]
	v_mfma_f32_16x16x32_bf16 v[20:23], v[218:221], v[188:191], v[168:171]
	v_mfma_f32_16x16x32_bf16 v[76:79], v[222:225], v[192:195], v[20:23]
	v_mfma_f32_16x16x32_bf16 v[20:23], v[128:131], v[202:205], v[68:71]
	v_mfma_f32_16x16x32_bf16 v[68:71], v[214:217], v[210:213], v[20:23]
	v_mfma_f32_16x16x32_bf16 v[20:23], v[218:221], v[202:205], v[64:67]
	v_mfma_f32_16x16x32_bf16 v[64:67], v[222:225], v[210:213], v[20:23]
	s_setprio 0
	s_barrier
	s_barrier
	s_waitcnt lgkmcnt(0)
	s_setprio 1
	s_waitcnt lgkmcnt(0)
	s_setprio 0
	s_setprio 1
	s_setprio 0
	s_movk_i32 s4, 0x100
	v_cmp_gt_u32_e32 vcc, s4, v132
	s_barrier
	s_and_saveexec_b64 s[4:5], vcc
	s_cbranch_execz .Lhf_195
	s_barrier

.LBB0_192:
	ds_read_b128 v[140:143], v129
	ds_read_b128 v[144:147], v129 offset:1024
	ds_read_b128 v[148:151], v129 offset:2048
	ds_read_b128 v[152:155], v129 offset:3072
	s_add_u32 s28, s56, s4
	s_addc_u32 s29, s57, s5
	ds_read_b128 v[156:159], v136
	ds_read_b128 v[164:167], v135
	ds_read_b128 v[172:175], v134
	ds_read_b128 v[180:183], v133
	ds_read_b128 v[160:163], v136 offset:1024
	ds_read_b128 v[168:171], v135 offset:1024
	ds_read_b128 v[176:179], v134 offset:1024
	ds_read_b128 v[184:187], v133 offset:1024
	s_add_i32 s40, s52, 0xc000
	s_mov_b32 m0, s40
	s_add_i32 s39, s52, 0xe000
	s_add_u32 s98, s28, s44
	s_addc_u32 s99, s29, s45
	global_load_lds_dwordx4 v128, s[98:99]
	s_mov_b32 m0, s39
	s_nop 0
	global_load_lds_dwordx4 v130, s[98:99]
	s_waitcnt lgkmcnt(8)
	s_barrier
	s_waitcnt lgkmcnt(7)
	v_mfma_f32_16x16x32_bf16 v[124:127], v[140:143], v[156:159], v[124:127]
	v_mfma_f32_16x16x32_bf16 v[120:123], v[148:151], v[156:159], v[120:123]
	s_waitcnt lgkmcnt(6)
	v_mfma_f32_16x16x32_bf16 v[116:119], v[140:143], v[164:167], v[116:119]
	v_mfma_f32_16x16x32_bf16 v[112:115], v[148:151], v[164:167], v[112:115]
	s_waitcnt lgkmcnt(5)
	v_mfma_f32_16x16x32_bf16 v[108:111], v[140:143], v[172:175], v[108:111]
	v_mfma_f32_16x16x32_bf16 v[104:107], v[148:151], v[172:175], v[104:107]
	s_waitcnt lgkmcnt(4)
	v_mfma_f32_16x16x32_bf16 v[100:103], v[140:143], v[180:183], v[100:103]
	v_mfma_f32_16x16x32_bf16 v[96:99], v[148:151], v[180:183], v[96:99]
	s_waitcnt lgkmcnt(3)
	v_mfma_f32_16x16x32_bf16 v[124:127], v[144:147], v[160:163], v[124:127]
	v_mfma_f32_16x16x32_bf16 v[120:123], v[152:155], v[160:163], v[120:123]
	s_waitcnt lgkmcnt(2)
	v_mfma_f32_16x16x32_bf16 v[116:119], v[144:147], v[168:171], v[116:119]
	v_mfma_f32_16x16x32_bf16 v[112:115], v[152:155], v[168:171], v[112:115]
	s_waitcnt lgkmcnt(1)
	v_mfma_f32_16x16x32_bf16 v[108:111], v[144:147], v[176:179], v[108:111]
	v_mfma_f32_16x16x32_bf16 v[104:107], v[152:155], v[176:179], v[104:107]
	s_waitcnt lgkmcnt(0)
	v_mfma_f32_16x16x32_bf16 v[100:103], v[144:147], v[184:187], v[100:103]
	v_mfma_f32_16x16x32_bf16 v[96:99], v[152:155], v[184:187], v[96:99]
	s_barrier
	s_add_u32 s58, s56, s36
	s_addc_u32 s59, s57, s37
	ds_read_b128 v[188:191], v139
	ds_read_b128 v[192:195], v139 offset:1024
	ds_read_b128 v[202:205], v139 offset:2048
	ds_read_b128 v[206:209], v139 offset:3072
	s_add_i32 m0, s52, 0x10000
	s_add_u32 s98, s58, s46
	s_addc_u32 s99, s59, s47
	global_load_lds_dwordx4 v128, s[98:99]
	s_add_i32 m0, s52, 0x12000
	s_nop 0
	global_load_lds_dwordx4 v130, s[98:99]
	s_barrier
	s_waitcnt lgkmcnt(3)
	v_mfma_f32_16x16x32_bf16 v[92:95], v[188:191], v[156:159], v[92:95]
	s_waitcnt lgkmcnt(1)
	v_mfma_f32_16x16x32_bf16 v[88:91], v[202:205], v[156:159], v[88:91]
	v_mfma_f32_16x16x32_bf16 v[84:87], v[188:191], v[164:167], v[84:87]
	v_mfma_f32_16x16x32_bf16 v[80:83], v[202:205], v[164:167], v[80:83]
	v_mfma_f32_16x16x32_bf16 v[76:79], v[188:191], v[172:175], v[76:79]
	v_mfma_f32_16x16x32_bf16 v[72:75], v[202:205], v[172:175], v[72:75]
	v_mfma_f32_16x16x32_bf16 v[68:71], v[188:191], v[180:183], v[68:71]
	v_mfma_f32_16x16x32_bf16 v[64:67], v[202:205], v[180:183], v[64:67]
	v_mfma_f32_16x16x32_bf16 v[92:95], v[192:195], v[160:163], v[92:95]
	s_waitcnt lgkmcnt(0)
	v_mfma_f32_16x16x32_bf16 v[88:91], v[206:209], v[160:163], v[88:91]
	v_mfma_f32_16x16x32_bf16 v[84:87], v[192:195], v[168:171], v[84:87]
	v_mfma_f32_16x16x32_bf16 v[80:83], v[206:209], v[168:171], v[80:83]
	v_mfma_f32_16x16x32_bf16 v[76:79], v[192:195], v[176:179], v[76:79]
	v_mfma_f32_16x16x32_bf16 v[72:75], v[206:209], v[176:179], v[72:75]
	v_mfma_f32_16x16x32_bf16 v[68:71], v[192:195], v[184:187], v[68:71]
	v_mfma_f32_16x16x32_bf16 v[64:67], v[206:209], v[184:187], v[64:67]
	s_barrier
	ds_read_b128 v[156:159], v136 offset:16384
	ds_read_b128 v[164:167], v135 offset:16384
	ds_read_b128 v[172:175], v134 offset:16384
	ds_read_b128 v[180:183], v133 offset:16384
	ds_read_b128 v[160:163], v136 offset:17408
	ds_read_b128 v[168:171], v135 offset:17408
	ds_read_b128 v[176:179], v134 offset:17408
	ds_read_b128 v[184:187], v133 offset:17408
	s_mov_b32 m0, s52
	s_add_u32 s98, s28, s48
	s_addc_u32 s99, s29, s49
	global_load_lds_dwordx4 v128, s[98:99]
	s_add_i32 m0, s52, 0x2000
	s_nop 0
	global_load_lds_dwordx4 v130, s[98:99]
	s_barrier
	s_waitcnt lgkmcnt(7)
	v_mfma_f32_16x16x32_bf16 v[60:63], v[140:143], v[156:159], v[60:63]
	v_mfma_f32_16x16x32_bf16 v[56:59], v[148:151], v[156:159], v[56:59]
	s_waitcnt lgkmcnt(6)
	v_mfma_f32_16x16x32_bf16 v[52:55], v[140:143], v[164:167], v[52:55]
	v_mfma_f32_16x16x32_bf16 v[48:51], v[148:151], v[164:167], v[48:51]
	s_waitcnt lgkmcnt(5)
	v_mfma_f32_16x16x32_bf16 v[44:47], v[140:143], v[172:175], v[44:47]
	v_mfma_f32_16x16x32_bf16 v[40:43], v[148:151], v[172:175], v[40:43]
	s_waitcnt lgkmcnt(4)
	v_mfma_f32_16x16x32_bf16 v[36:39], v[140:143], v[180:183], v[36:39]
	v_mfma_f32_16x16x32_bf16 v[32:35], v[148:151], v[180:183], v[32:35]
	s_waitcnt lgkmcnt(3)
	v_mfma_f32_16x16x32_bf16 v[60:63], v[144:147], v[160:163], v[60:63]
	v_mfma_f32_16x16x32_bf16 v[56:59], v[152:155], v[160:163], v[56:59]
	s_waitcnt lgkmcnt(2)
	v_mfma_f32_16x16x32_bf16 v[52:55], v[144:147], v[168:171], v[52:55]
	v_mfma_f32_16x16x32_bf16 v[48:51], v[152:155], v[168:171], v[48:51]
	s_waitcnt lgkmcnt(1)
	v_mfma_f32_16x16x32_bf16 v[44:47], v[144:147], v[176:179], v[44:47]
	v_mfma_f32_16x16x32_bf16 v[40:43], v[152:155], v[176:179], v[40:43]
	s_waitcnt lgkmcnt(0)
	v_mfma_f32_16x16x32_bf16 v[36:39], v[144:147], v[184:187], v[36:39]
	v_mfma_f32_16x16x32_bf16 v[32:35], v[152:155], v[184:187], v[32:35]
	s_barrier
	s_add_i32 m0, s52, 0x14000
	s_add_u32 s98, s58, s50
	s_addc_u32 s99, s59, s51
	global_load_lds_dwordx4 v128, s[98:99]
	s_add_i32 m0, s52, 0x16000
	s_nop 0
	global_load_lds_dwordx4 v130, s[98:99]
	s_waitcnt vmcnt(6)
	s_barrier
	v_mfma_f32_16x16x32_bf16 v[28:31], v[188:191], v[156:159], v[28:31]
	v_mfma_f32_16x16x32_bf16 v[24:27], v[202:205], v[156:159], v[24:27]
	v_mfma_f32_16x16x32_bf16 v[20:23], v[188:191], v[164:167], v[20:23]
	v_mfma_f32_16x16x32_bf16 v[16:19], v[202:205], v[164:167], v[16:19]
	v_mfma_f32_16x16x32_bf16 v[12:15], v[188:191], v[172:175], v[12:15]
	v_mfma_f32_16x16x32_bf16 v[8:11], v[202:205], v[172:175], v[8:11]
	v_mfma_f32_16x16x32_bf16 v[4:7], v[188:191], v[180:183], v[4:7]
	v_mfma_f32_16x16x32_bf16 v[0:3], v[202:205], v[180:183], v[0:3]
	v_mfma_f32_16x16x32_bf16 v[28:31], v[192:195], v[160:163], v[28:31]
	v_mfma_f32_16x16x32_bf16 v[24:27], v[206:209], v[160:163], v[24:27]
	v_mfma_f32_16x16x32_bf16 v[20:23], v[192:195], v[168:171], v[20:23]
	v_mfma_f32_16x16x32_bf16 v[16:19], v[206:209], v[168:171], v[16:19]
	v_mfma_f32_16x16x32_bf16 v[12:15], v[192:195], v[176:179], v[12:15]
	v_mfma_f32_16x16x32_bf16 v[8:11], v[206:209], v[176:179], v[8:11]
	v_mfma_f32_16x16x32_bf16 v[4:7], v[192:195], v[184:187], v[4:7]
	v_mfma_f32_16x16x32_bf16 v[0:3], v[206:209], v[184:187], v[0:3]
	s_barrier
	ds_read_b128 v[140:143], v138
	ds_read_b128 v[144:147], v138 offset:1024
	ds_read_b128 v[148:151], v138 offset:2048
	ds_read_b128 v[152:155], v138 offset:3072
	ds_read_b128 v[156:159], v136 offset:32768
	ds_read_b128 v[164:167], v135 offset:32768
	ds_read_b128 v[172:175], v134 offset:32768
	ds_read_b128 v[180:183], v133 offset:32768
	ds_read_b128 v[160:163], v136 offset:33792
	ds_read_b128 v[168:171], v135 offset:33792
	ds_read_b128 v[176:179], v134 offset:33792
	ds_read_b128 v[184:187], v133 offset:33792
	s_add_i32 m0, s52, 0x4000
	s_add_u32 s98, s28, s54
	s_addc_u32 s99, s29, s55
	global_load_lds_dwordx4 v128, s[98:99]
	s_add_i32 m0, s52, 0x6000
	s_nop 0
	global_load_lds_dwordx4 v130, s[98:99]
	s_waitcnt lgkmcnt(8)
	s_barrier
	s_waitcnt lgkmcnt(7)
	v_mfma_f32_16x16x32_bf16 v[124:127], v[140:143], v[156:159], v[124:127]
	v_mfma_f32_16x16x32_bf16 v[120:123], v[148:151], v[156:159], v[120:123]
	s_waitcnt lgkmcnt(6)
	v_mfma_f32_16x16x32_bf16 v[116:119], v[140:143], v[164:167], v[116:119]
	v_mfma_f32_16x16x32_bf16 v[112:115], v[148:151], v[164:167], v[112:115]
	s_waitcnt lgkmcnt(5)
	v_mfma_f32_16x16x32_bf16 v[108:111], v[140:143], v[172:175], v[108:111]
	v_mfma_f32_16x16x32_bf16 v[104:107], v[148:151], v[172:175], v[104:107]
	s_waitcnt lgkmcnt(4)
	v_mfma_f32_16x16x32_bf16 v[100:103], v[140:143], v[180:183], v[100:103]
	v_mfma_f32_16x16x32_bf16 v[96:99], v[148:151], v[180:183], v[96:99]
	s_waitcnt lgkmcnt(3)
	v_mfma_f32_16x16x32_bf16 v[124:127], v[144:147], v[160:163], v[124:127]
	v_mfma_f32_16x16x32_bf16 v[120:123], v[152:155], v[160:163], v[120:123]
	s_waitcnt lgkmcnt(2)
	v_mfma_f32_16x16x32_bf16 v[116:119], v[144:147], v[168:171], v[116:119]
	v_mfma_f32_16x16x32_bf16 v[112:115], v[152:155], v[168:171], v[112:115]
	s_waitcnt lgkmcnt(1)
	v_mfma_f32_16x16x32_bf16 v[108:111], v[144:147], v[176:179], v[108:111]
	v_mfma_f32_16x16x32_bf16 v[104:107], v[152:155], v[176:179], v[104:107]
	s_waitcnt lgkmcnt(0)
	v_mfma_f32_16x16x32_bf16 v[100:103], v[144:147], v[184:187], v[100:103]
	v_mfma_f32_16x16x32_bf16 v[96:99], v[152:155], v[184:187], v[96:99]
	s_barrier
	ds_read_b128 v[188:191], v137
	ds_read_b128 v[192:195], v137 offset:1024
	ds_read_b128 v[202:205], v137 offset:2048
	ds_read_b128 v[206:209], v137 offset:3072
	s_mov_b32 m0, s7
	s_add_u32 s98, s58, s68
	s_addc_u32 s99, s59, s69
	global_load_lds_dwordx4 v128, s[98:99]
	s_mov_b32 m0, s53
	s_nop 0
	global_load_lds_dwordx4 v130, s[98:99]
	s_barrier
	s_waitcnt lgkmcnt(3)
	v_mfma_f32_16x16x32_bf16 v[92:95], v[188:191], v[156:159], v[92:95]
	s_waitcnt lgkmcnt(1)
	v_mfma_f32_16x16x32_bf16 v[88:91], v[202:205], v[156:159], v[88:91]
	v_mfma_f32_16x16x32_bf16 v[84:87], v[188:191], v[164:167], v[84:87]
	v_mfma_f32_16x16x32_bf16 v[80:83], v[202:205], v[164:167], v[80:83]
	v_mfma_f32_16x16x32_bf16 v[76:79], v[188:191], v[172:175], v[76:79]
	v_mfma_f32_16x16x32_bf16 v[72:75], v[202:205], v[172:175], v[72:75]
	v_mfma_f32_16x16x32_bf16 v[68:71], v[188:191], v[180:183], v[68:71]
	v_mfma_f32_16x16x32_bf16 v[64:67], v[202:205], v[180:183], v[64:67]
	v_mfma_f32_16x16x32_bf16 v[92:95], v[192:195], v[160:163], v[92:95]
	s_waitcnt lgkmcnt(0)
	v_mfma_f32_16x16x32_bf16 v[88:91], v[206:209], v[160:163], v[88:91]
	v_mfma_f32_16x16x32_bf16 v[84:87], v[192:195], v[168:171], v[84:87]
	v_mfma_f32_16x16x32_bf16 v[80:83], v[206:209], v[168:171], v[80:83]
	v_mfma_f32_16x16x32_bf16 v[76:79], v[192:195], v[176:179], v[76:79]
	v_mfma_f32_16x16x32_bf16 v[72:75], v[206:209], v[176:179], v[72:75]
	v_mfma_f32_16x16x32_bf16 v[68:71], v[192:195], v[184:187], v[68:71]
	v_mfma_f32_16x16x32_bf16 v[64:67], v[206:209], v[184:187], v[64:67]
	v_mov_b32_e32 v210, v130
	s_barrier
	ds_read_b128 v[156:159], v136 offset:49152
	ds_read_b128 v[164:167], v135 offset:49152
	ds_read_b128 v[172:175], v134 offset:49152
	ds_read_b128 v[180:183], v133 offset:49152
	ds_read_b128 v[160:163], v136 offset:50176
	ds_read_b128 v[168:171], v135 offset:50176
	ds_read_b128 v[176:179], v134 offset:50176
	ds_read_b128 v[184:187], v133 offset:50176
	v_mov_b32_e32 v211, v197
	s_mov_b32 m0, s9
	s_add_u32 s98, s28, s70
	s_addc_u32 s99, s29, s71
	global_load_lds_dwordx4 v128, s[98:99]
	s_mov_b32 m0, s33
	s_nop 0
	global_load_lds_dwordx4 v130, s[98:99]
	s_barrier
	s_waitcnt lgkmcnt(7)
	v_mfma_f32_16x16x32_bf16 v[60:63], v[140:143], v[156:159], v[60:63]
	v_mfma_f32_16x16x32_bf16 v[56:59], v[148:151], v[156:159], v[56:59]
	s_waitcnt lgkmcnt(6)
	v_mfma_f32_16x16x32_bf16 v[52:55], v[140:143], v[164:167], v[52:55]
	v_mfma_f32_16x16x32_bf16 v[48:51], v[148:151], v[164:167], v[48:51]
	s_waitcnt lgkmcnt(5)
	v_mfma_f32_16x16x32_bf16 v[44:47], v[140:143], v[172:175], v[44:47]
	v_mfma_f32_16x16x32_bf16 v[40:43], v[148:151], v[172:175], v[40:43]
	s_waitcnt lgkmcnt(4)
	v_mfma_f32_16x16x32_bf16 v[36:39], v[140:143], v[180:183], v[36:39]
	v_mfma_f32_16x16x32_bf16 v[32:35], v[148:151], v[180:183], v[32:35]
	s_waitcnt lgkmcnt(3)
	v_mfma_f32_16x16x32_bf16 v[60:63], v[144:147], v[160:163], v[60:63]
	v_mfma_f32_16x16x32_bf16 v[56:59], v[152:155], v[160:163], v[56:59]
	s_waitcnt lgkmcnt(2)
	v_mfma_f32_16x16x32_bf16 v[52:55], v[144:147], v[168:171], v[52:55]
	v_mfma_f32_16x16x32_bf16 v[48:51], v[152:155], v[168:171], v[48:51]
	s_waitcnt lgkmcnt(1)
	v_mfma_f32_16x16x32_bf16 v[44:47], v[144:147], v[176:179], v[44:47]
	v_mfma_f32_16x16x32_bf16 v[40:43], v[152:155], v[176:179], v[40:43]
	s_waitcnt lgkmcnt(0)
	v_mfma_f32_16x16x32_bf16 v[36:39], v[144:147], v[184:187], v[36:39]
	v_mfma_f32_16x16x32_bf16 v[32:35], v[152:155], v[184:187], v[32:35]
	s_barrier
	v_mov_b32_e32 v196, v128
	s_mov_b32 m0, s65
	s_add_u32 s98, s58, s72
	s_addc_u32 s99, s59, s73
	global_load_lds_dwordx4 v128, s[98:99]
	s_mov_b32 m0, s66
	s_nop 0
	global_load_lds_dwordx4 v130, s[98:99]
	s_waitcnt vmcnt(6)
	s_barrier
	v_mfma_f32_16x16x32_bf16 v[28:31], v[188:191], v[156:159], v[28:31]
	v_mfma_f32_16x16x32_bf16 v[24:27], v[202:205], v[156:159], v[24:27]
	v_mfma_f32_16x16x32_bf16 v[20:23], v[188:191], v[164:167], v[20:23]
	v_mfma_f32_16x16x32_bf16 v[16:19], v[202:205], v[164:167], v[16:19]
	v_mfma_f32_16x16x32_bf16 v[12:15], v[188:191], v[172:175], v[12:15]
	v_mfma_f32_16x16x32_bf16 v[8:11], v[202:205], v[172:175], v[8:11]
	v_mfma_f32_16x16x32_bf16 v[4:7], v[188:191], v[180:183], v[4:7]
	v_mfma_f32_16x16x32_bf16 v[0:3], v[202:205], v[180:183], v[0:3]
	v_mfma_f32_16x16x32_bf16 v[28:31], v[192:195], v[160:163], v[28:31]
	v_mfma_f32_16x16x32_bf16 v[24:27], v[206:209], v[160:163], v[24:27]
	v_mfma_f32_16x16x32_bf16 v[20:23], v[192:195], v[168:171], v[20:23]
	v_mfma_f32_16x16x32_bf16 v[16:19], v[206:209], v[168:171], v[16:19]
	v_mfma_f32_16x16x32_bf16 v[12:15], v[192:195], v[176:179], v[12:15]
	v_mfma_f32_16x16x32_bf16 v[8:11], v[206:209], v[176:179], v[8:11]
	v_mfma_f32_16x16x32_bf16 v[4:7], v[192:195], v[184:187], v[4:7]
	v_mfma_f32_16x16x32_bf16 v[0:3], v[206:209], v[184:187], v[0:3]
	s_add_i32 s38, s38, 2
	s_add_u32 s56, s56, 0x100
	s_addc_u32 s57, s57, 0
	s_cmp_lt_u32 s38, 28
	s_barrier
	s_cbranch_scc1 .LBB0_192
	s_lshl_b64 s[4:5], s[10:11], 12
	v_readlane_b32 s10, v254, 12
	v_readlane_b32 s11, v254, 13
	s_add_u32 s4, s10, s4
	s_addc_u32 s5, s11, s5
	ds_read_b128 v[140:143], v129
	ds_read_b128 v[144:147], v129 offset:1024
	ds_read_b128 v[148:151], v129 offset:2048
	ds_read_b128 v[152:155], v129 offset:3072
	ds_read_b128 v[156:159], v136
	ds_read_b128 v[160:163], v136 offset:1024
	ds_read_b128 v[164:167], v135
	ds_read_b128 v[168:171], v135 offset:1024
	ds_read_b128 v[172:175], v134
	ds_read_b128 v[176:179], v134 offset:1024
	ds_read_b128 v[180:183], v133
	ds_read_b128 v[184:187], v133 offset:1024
	v_mov_b32_e32 v129, v197
	v_lshl_add_u64 v[128:129], s[4:5], 0, v[128:129]
	s_mov_b64 s[10:11], 0xf80
	s_mov_b32 m0, s40
	v_lshl_add_u64 v[128:129], v[128:129], 0, s[10:11]
	v_mov_b32_e32 v131, v197
	global_load_lds_dwordx4 v[128:129], off
	v_lshl_add_u64 v[128:129], s[4:5], 0, v[130:131]
	v_lshl_add_u64 v[128:129], v[128:129], 0, s[10:11]
	s_mov_b32 m0, s39
	s_nop 0
	global_load_lds_dwordx4 v[128:129], off
	s_barrier
	s_waitcnt lgkmcnt(0)
	s_setprio 1
	s_waitcnt lgkmcnt(0)
	v_mfma_f32_16x16x32_bf16 v[124:127], v[140:143], v[156:159], v[124:127]
	v_mfma_f32_16x16x32_bf16 v[116:119], v[140:143], v[164:167], v[116:119]
	v_mfma_f32_16x16x32_bf16 v[112:115], v[148:151], v[164:167], v[112:115]
	v_mfma_f32_16x16x32_bf16 v[108:111], v[140:143], v[172:175], v[108:111]
	v_mfma_f32_16x16x32_bf16 v[104:107], v[148:151], v[172:175], v[104:107]
	v_mfma_f32_16x16x32_bf16 v[100:103], v[140:143], v[180:183], v[100:103]
	v_mfma_f32_16x16x32_bf16 v[96:99], v[148:151], v[180:183], v[96:99]
	v_mfma_f32_16x16x32_bf16 v[124:127], v[144:147], v[160:163], v[124:127]
	v_mfma_f32_16x16x32_bf16 v[120:123], v[148:151], v[156:159], v[120:123]
	v_mfma_f32_16x16x32_bf16 v[116:119], v[144:147], v[168:171], v[116:119]
	v_mfma_f32_16x16x32_bf16 v[112:115], v[152:155], v[168:171], v[112:115]
	v_mfma_f32_16x16x32_bf16 v[108:111], v[144:147], v[176:179], v[108:111]
	v_mfma_f32_16x16x32_bf16 v[104:107], v[152:155], v[176:179], v[104:107]
	v_mfma_f32_16x16x32_bf16 v[100:103], v[144:147], v[184:187], v[100:103]
	v_mfma_f32_16x16x32_bf16 v[96:99], v[152:155], v[184:187], v[96:99]
	v_mfma_f32_16x16x32_bf16 v[128:131], v[152:155], v[160:163], v[120:123]
	s_setprio 0
	s_barrier
	s_nop 0
	ds_read_b128 v[120:123], v139
	ds_read_b128 v[188:191], v139 offset:1024
	ds_read_b128 v[192:195], v139 offset:2048
	ds_read_b128 v[202:205], v139 offset:3072
	s_barrier
	s_waitcnt lgkmcnt(0)
	s_setprio 1
	s_waitcnt lgkmcnt(0)
	v_mfma_f32_16x16x32_bf16 v[76:79], v[120:123], v[172:175], v[76:79]
	v_mfma_f32_16x16x32_bf16 v[68:71], v[120:123], v[180:183], v[68:71]
	v_mfma_f32_16x16x32_bf16 v[64:67], v[192:195], v[180:183], v[64:67]
	v_mfma_f32_16x16x32_bf16 v[92:95], v[120:123], v[156:159], v[92:95]
	v_mfma_f32_16x16x32_bf16 v[88:91], v[192:195], v[156:159], v[88:91]
	v_mfma_f32_16x16x32_bf16 v[84:87], v[120:123], v[164:167], v[84:87]
	v_mfma_f32_16x16x32_bf16 v[80:83], v[192:195], v[164:167], v[80:83]
	v_mfma_f32_16x16x32_bf16 v[76:79], v[188:191], v[176:179], v[76:79]
	v_mfma_f32_16x16x32_bf16 v[72:75], v[192:195], v[172:175], v[72:75]
	v_mfma_f32_16x16x32_bf16 v[68:71], v[188:191], v[184:187], v[68:71]
	v_mfma_f32_16x16x32_bf16 v[64:67], v[202:205], v[184:187], v[64:67]
	v_mfma_f32_16x16x32_bf16 v[206:209], v[188:191], v[160:163], v[92:95]
	v_mfma_f32_16x16x32_bf16 v[156:159], v[202:205], v[160:163], v[88:91]
	v_mfma_f32_16x16x32_bf16 v[160:163], v[188:191], v[168:171], v[84:87]
	v_mfma_f32_16x16x32_bf16 v[164:167], v[202:205], v[168:171], v[80:83]
	v_mfma_f32_16x16x32_bf16 v[168:171], v[202:205], v[176:179], v[72:75]
	s_setprio 0
	s_barrier
	s_nop 0
	ds_read_b128 v[72:75], v136 offset:16384
	ds_read_b128 v[80:83], v136 offset:17408
	ds_read_b128 v[84:87], v135 offset:16384
	ds_read_b128 v[88:91], v135 offset:17408
	ds_read_b128 v[92:95], v134 offset:16384
	ds_read_b128 v[172:175], v134 offset:17408
	ds_read_b128 v[176:179], v133 offset:16384
	ds_read_b128 v[180:183], v133 offset:17408
	s_waitcnt vmcnt(4)
	s_barrier
	s_waitcnt lgkmcnt(0)
	s_setprio 1
	s_waitcnt lgkmcnt(0)
	v_mfma_f32_16x16x32_bf16 v[60:63], v[140:143], v[72:75], v[60:63]
	v_mfma_f32_16x16x32_bf16 v[52:55], v[140:143], v[84:87], v[52:55]
	v_mfma_f32_16x16x32_bf16 v[48:51], v[148:151], v[84:87], v[48:51]
	v_mfma_f32_16x16x32_bf16 v[44:47], v[140:143], v[92:95], v[44:47]
	v_mfma_f32_16x16x32_bf16 v[40:43], v[148:151], v[92:95], v[40:43]
	v_mfma_f32_16x16x32_bf16 v[36:39], v[140:143], v[176:179], v[36:39]
	v_mfma_f32_16x16x32_bf16 v[32:35], v[148:151], v[176:179], v[32:35]
	v_mfma_f32_16x16x32_bf16 v[60:63], v[144:147], v[80:83], v[60:63]
	v_mfma_f32_16x16x32_bf16 v[56:59], v[148:151], v[72:75], v[56:59]
	v_mfma_f32_16x16x32_bf16 v[52:55], v[144:147], v[88:91], v[52:55]
	v_mfma_f32_16x16x32_bf16 v[48:51], v[152:155], v[88:91], v[48:51]
	v_mfma_f32_16x16x32_bf16 v[44:47], v[144:147], v[172:175], v[44:47]
	v_mfma_f32_16x16x32_bf16 v[40:43], v[152:155], v[172:175], v[40:43]
	v_mfma_f32_16x16x32_bf16 v[36:39], v[144:147], v[180:183], v[36:39]
	v_mfma_f32_16x16x32_bf16 v[32:35], v[152:155], v[180:183], v[32:35]
	v_mfma_f32_16x16x32_bf16 v[184:187], v[152:155], v[80:83], v[56:59]
	s_setprio 0
	s_setprio 1
	v_mfma_f32_16x16x32_bf16 v[12:15], v[120:123], v[92:95], v[12:15]
	v_mfma_f32_16x16x32_bf16 v[4:7], v[120:123], v[176:179], v[4:7]
	v_mfma_f32_16x16x32_bf16 v[0:3], v[192:195], v[176:179], v[0:3]
	v_mfma_f32_16x16x32_bf16 v[28:31], v[120:123], v[72:75], v[28:31]
	v_mfma_f32_16x16x32_bf16 v[24:27], v[192:195], v[72:75], v[24:27]
	v_mfma_f32_16x16x32_bf16 v[20:23], v[120:123], v[84:87], v[20:23]
	v_mfma_f32_16x16x32_bf16 v[16:19], v[192:195], v[84:87], v[16:19]
	v_mfma_f32_16x16x32_bf16 v[12:15], v[188:191], v[172:175], v[12:15]
	v_mfma_f32_16x16x32_bf16 v[8:11], v[192:195], v[92:95], v[8:11]
	v_mfma_f32_16x16x32_bf16 v[4:7], v[188:191], v[180:183], v[4:7]
	v_mfma_f32_16x16x32_bf16 v[0:3], v[202:205], v[180:183], v[0:3]
	v_mfma_f32_16x16x32_bf16 v[140:143], v[188:191], v[80:83], v[28:31]
	v_mfma_f32_16x16x32_bf16 v[144:147], v[202:205], v[80:83], v[24:27]
	v_mfma_f32_16x16x32_bf16 v[148:151], v[188:191], v[88:91], v[20:23]
	v_mfma_f32_16x16x32_bf16 v[152:155], v[202:205], v[88:91], v[16:19]
	v_mfma_f32_16x16x32_bf16 v[172:175], v[202:205], v[172:175], v[8:11]
	s_setprio 0
	s_barrier
	s_nop 0
	ds_read_b128 v[8:11], v138
	ds_read_b128 v[16:19], v138 offset:1024
	ds_read_b128 v[176:179], v138 offset:2048
	ds_read_b128 v[180:183], v138 offset:3072
	ds_read_b128 v[20:23], v136 offset:32768
	ds_read_b128 v[24:27], v136 offset:33792
	ds_read_b128 v[28:31], v135 offset:32768
	ds_read_b128 v[56:59], v135 offset:33792
	ds_read_b128 v[188:191], v134 offset:32768
	ds_read_b128 v[192:195], v134 offset:33792
	ds_read_b128 v[202:205], v133 offset:32768
	ds_read_b128 v[210:213], v133 offset:33792
	s_waitcnt vmcnt(2)
	s_barrier
	s_waitcnt lgkmcnt(0)
	s_setprio 1
	s_waitcnt lgkmcnt(0)
	v_mfma_f32_16x16x32_bf16 v[72:75], v[8:11], v[20:23], v[124:127]
	v_mfma_f32_16x16x32_bf16 v[120:123], v[16:19], v[24:27], v[72:75]
	v_mfma_f32_16x16x32_bf16 v[72:75], v[176:179], v[20:23], v[128:131]
	v_mfma_f32_16x16x32_bf16 v[124:127], v[180:183], v[24:27], v[72:75]
	v_mfma_f32_16x16x32_bf16 v[72:75], v[8:11], v[28:31], v[116:119]
	v_mfma_f32_16x16x32_bf16 v[116:119], v[16:19], v[56:59], v[72:75]
	v_mfma_f32_16x16x32_bf16 v[72:75], v[176:179], v[28:31], v[112:115]
	v_mfma_f32_16x16x32_bf16 v[112:115], v[180:183], v[56:59], v[72:75]
	v_mfma_f32_16x16x32_bf16 v[72:75], v[8:11], v[188:191], v[108:111]
	v_mfma_f32_16x16x32_bf16 v[88:91], v[16:19], v[192:195], v[72:75]
	v_mfma_f32_16x16x32_bf16 v[72:75], v[176:179], v[188:191], v[104:107]
	v_mfma_f32_16x16x32_bf16 v[92:95], v[180:183], v[192:195], v[72:75]
	v_mfma_f32_16x16x32_bf16 v[72:75], v[8:11], v[202:205], v[100:103]
	v_mfma_f32_16x16x32_bf16 v[84:87], v[16:19], v[210:213], v[72:75]
	v_mfma_f32_16x16x32_bf16 v[72:75], v[176:179], v[202:205], v[96:99]
	v_mfma_f32_16x16x32_bf16 v[80:83], v[180:183], v[210:213], v[72:75]
	s_setprio 0
	s_barrier
	ds_read_b128 v[128:131], v137
	ds_read_b128 v[214:217], v137 offset:1024
	ds_read_b128 v[218:221], v137 offset:2048
	ds_read_b128 v[222:225], v137 offset:3072
	s_waitcnt vmcnt(0)
	s_barrier
	s_waitcnt lgkmcnt(0)
	s_setprio 1
	s_waitcnt lgkmcnt(0)
	v_mfma_f32_16x16x32_bf16 v[72:75], v[128:131], v[20:23], v[206:209]
	v_mfma_f32_16x16x32_bf16 v[20:23], v[218:221], v[20:23], v[156:159]
	v_mfma_f32_16x16x32_bf16 v[108:111], v[222:225], v[24:27], v[20:23]
	v_mfma_f32_16x16x32_bf16 v[20:23], v[128:131], v[28:31], v[160:163]
	v_mfma_f32_16x16x32_bf16 v[100:103], v[214:217], v[56:59], v[20:23]
	v_mfma_f32_16x16x32_bf16 v[20:23], v[218:221], v[28:31], v[164:167]
	v_mfma_f32_16x16x32_bf16 v[96:99], v[222:225], v[56:59], v[20:23]
	v_mfma_f32_16x16x32_bf16 v[20:23], v[128:131], v[188:191], v[76:79]
	v_mfma_f32_16x16x32_bf16 v[104:107], v[214:217], v[24:27], v[72:75]
	v_mfma_f32_16x16x32_bf16 v[72:75], v[214:217], v[192:195], v[20:23]
	v_mfma_f32_16x16x32_bf16 v[20:23], v[218:221], v[188:191], v[168:171]
	v_mfma_f32_16x16x32_bf16 v[76:79], v[222:225], v[192:195], v[20:23]
	v_mfma_f32_16x16x32_bf16 v[20:23], v[128:131], v[202:205], v[68:71]
	v_mfma_f32_16x16x32_bf16 v[68:71], v[214:217], v[210:213], v[20:23]
	v_mfma_f32_16x16x32_bf16 v[20:23], v[218:221], v[202:205], v[64:67]
	v_mfma_f32_16x16x32_bf16 v[64:67], v[222:225], v[210:213], v[20:23]
	s_setprio 0
	s_barrier
	ds_read_b128 v[156:159], v136 offset:49152
	ds_read_b128 v[136:139], v136 offset:50176
	ds_read_b128 v[160:163], v135 offset:49152
	ds_read_b128 v[164:167], v135 offset:50176
	ds_read_b128 v[168:171], v134 offset:49152
	ds_read_b128 v[188:191], v134 offset:50176
	ds_read_b128 v[192:195], v133 offset:49152
	ds_read_b128 v[202:205], v133 offset:50176
	s_barrier
	s_waitcnt lgkmcnt(0)
	s_setprio 1
	s_waitcnt lgkmcnt(0)
	v_mfma_f32_16x16x32_bf16 v[20:23], v[8:11], v[156:159], v[60:63]
	v_mfma_f32_16x16x32_bf16 v[56:59], v[16:19], v[136:139], v[20:23]
	v_mfma_f32_16x16x32_bf16 v[20:23], v[176:179], v[156:159], v[184:187]
	v_mfma_f32_16x16x32_bf16 v[60:63], v[180:183], v[136:139], v[20:23]
	v_mfma_f32_16x16x32_bf16 v[20:23], v[8:11], v[160:163], v[52:55]
	v_mfma_f32_16x16x32_bf16 v[52:55], v[16:19], v[164:167], v[20:23]
	v_mfma_f32_16x16x32_bf16 v[20:23], v[176:179], v[160:163], v[48:51]
	v_mfma_f32_16x16x32_bf16 v[48:51], v[180:183], v[164:167], v[20:23]
	v_mfma_f32_16x16x32_bf16 v[20:23], v[8:11], v[168:171], v[44:47]
	v_mfma_f32_16x16x32_bf16 v[24:27], v[16:19], v[188:191], v[20:23]
	v_mfma_f32_16x16x32_bf16 v[20:23], v[176:179], v[168:171], v[40:43]
	v_mfma_f32_16x16x32_bf16 v[8:11], v[8:11], v[192:195], v[36:39]
	v_mfma_f32_16x16x32_bf16 v[28:31], v[180:183], v[188:191], v[20:23]
	v_mfma_f32_16x16x32_bf16 v[20:23], v[16:19], v[202:205], v[8:11]
	v_mfma_f32_16x16x32_bf16 v[8:11], v[176:179], v[192:195], v[32:35]
	v_mfma_f32_16x16x32_bf16 v[16:19], v[180:183], v[202:205], v[8:11]
	s_setprio 0
	s_setprio 1
	v_mfma_f32_16x16x32_bf16 v[8:11], v[128:131], v[156:159], v[140:143]
	v_mfma_f32_16x16x32_bf16 v[40:43], v[214:217], v[136:139], v[8:11]
	v_mfma_f32_16x16x32_bf16 v[8:11], v[218:221], v[156:159], v[144:147]
	v_mfma_f32_16x16x32_bf16 v[44:47], v[222:225], v[136:139], v[8:11]
	v_mfma_f32_16x16x32_bf16 v[8:11], v[128:131], v[160:163], v[148:151]
	v_mfma_f32_16x16x32_bf16 v[36:39], v[214:217], v[164:167], v[8:11]
	v_mfma_f32_16x16x32_bf16 v[8:11], v[218:221], v[160:163], v[152:155]
	v_mfma_f32_16x16x32_bf16 v[32:35], v[222:225], v[164:167], v[8:11]
	v_mfma_f32_16x16x32_bf16 v[8:11], v[128:131], v[168:171], v[12:15]
	v_mfma_f32_16x16x32_bf16 v[12:15], v[218:221], v[168:171], v[172:175]
	v_mfma_f32_16x16x32_bf16 v[4:7], v[128:131], v[192:195], v[4:7]
	v_mfma_f32_16x16x32_bf16 v[0:3], v[218:221], v[192:195], v[0:3]
	v_mfma_f32_16x16x32_bf16 v[8:11], v[214:217], v[188:191], v[8:11]
	v_mfma_f32_16x16x32_bf16 v[12:15], v[222:225], v[188:191], v[12:15]
	v_mfma_f32_16x16x32_bf16 v[4:7], v[214:217], v[202:205], v[4:7]
	v_mfma_f32_16x16x32_bf16 v[0:3], v[222:225], v[202:205], v[0:3]
	s_setprio 0
	s_movk_i32 s4, 0x100
	v_cmp_gt_u32_e32 vcc, s4, v132
	s_barrier
	s_and_saveexec_b64 s[4:5], vcc
	s_cbranch_execz .LBB0_195
	s_barrier

.Lh1_loop:
	ds_read_b128 v[140:143], v129
	ds_read_b128 v[144:147], v129 offset:1024
	ds_read_b128 v[148:151], v129 offset:2048
	ds_read_b128 v[152:155], v129 offset:3072
	s_add_u32 s28, s60, s56
	s_addc_u32 s29, s61, s57
	ds_read_b128 v[156:159], v136
	ds_read_b128 v[164:167], v135
	ds_read_b128 v[172:175], v134
	ds_read_b128 v[180:183], v133
	ds_read_b128 v[160:163], v136 offset:1024
	ds_read_b128 v[168:171], v135 offset:1024
	ds_read_b128 v[176:179], v134 offset:1024
	ds_read_b128 v[184:187], v133 offset:1024
	s_add_i32 s40, s53, 0xc000
	s_mov_b32 m0, s40
	s_add_i32 s39, s53, 0xe000
	s_mov_b32 m0, s39
	s_nop 0
	s_waitcnt lgkmcnt(8)
	s_barrier
	s_waitcnt lgkmcnt(7)
	v_mfma_f32_16x16x32_bf16 v[124:127], v[140:143], v[156:159], v[124:127]
	v_mfma_f32_16x16x32_bf16 v[120:123], v[148:151], v[156:159], v[120:123]
	s_waitcnt lgkmcnt(6)
	v_mfma_f32_16x16x32_bf16 v[116:119], v[140:143], v[164:167], v[116:119]
	v_mfma_f32_16x16x32_bf16 v[112:115], v[148:151], v[164:167], v[112:115]
	s_waitcnt lgkmcnt(5)
	v_mfma_f32_16x16x32_bf16 v[108:111], v[140:143], v[172:175], v[108:111]
	v_mfma_f32_16x16x32_bf16 v[104:107], v[148:151], v[172:175], v[104:107]
	s_waitcnt lgkmcnt(4)
	v_mfma_f32_16x16x32_bf16 v[100:103], v[140:143], v[180:183], v[100:103]
	v_mfma_f32_16x16x32_bf16 v[96:99], v[148:151], v[180:183], v[96:99]
	s_waitcnt lgkmcnt(3)
	v_mfma_f32_16x16x32_bf16 v[124:127], v[144:147], v[160:163], v[124:127]
	v_mfma_f32_16x16x32_bf16 v[120:123], v[152:155], v[160:163], v[120:123]
	s_waitcnt lgkmcnt(2)
	v_mfma_f32_16x16x32_bf16 v[116:119], v[144:147], v[168:171], v[116:119]
	v_mfma_f32_16x16x32_bf16 v[112:115], v[152:155], v[168:171], v[112:115]
	s_waitcnt lgkmcnt(1)
	v_mfma_f32_16x16x32_bf16 v[108:111], v[144:147], v[176:179], v[108:111]
	v_mfma_f32_16x16x32_bf16 v[104:107], v[152:155], v[176:179], v[104:107]
	s_waitcnt lgkmcnt(0)
	v_mfma_f32_16x16x32_bf16 v[100:103], v[144:147], v[184:187], v[100:103]
	v_mfma_f32_16x16x32_bf16 v[96:99], v[152:155], v[184:187], v[96:99]
	s_barrier
	s_add_u32 s62, s60, s36
	s_addc_u32 s63, s61, s37
	ds_read_b128 v[188:191], v139
	ds_read_b128 v[192:195], v139 offset:1024
	ds_read_b128 v[202:205], v139 offset:2048
	ds_read_b128 v[206:209], v139 offset:3072
	s_mov_b32 m0, s68
	s_add_u32 s98, s62, s46
	s_addc_u32 s99, s63, s47
	global_load_lds_dwordx4 v128, s[98:99]
	s_mov_b32 m0, s69
	s_nop 0
	global_load_lds_dwordx4 v130, s[98:99]
	s_barrier
	s_waitcnt lgkmcnt(3)
	v_mfma_f32_16x16x32_bf16 v[92:95], v[188:191], v[156:159], v[92:95]
	s_waitcnt lgkmcnt(1)
	v_mfma_f32_16x16x32_bf16 v[88:91], v[202:205], v[156:159], v[88:91]
	v_mfma_f32_16x16x32_bf16 v[84:87], v[188:191], v[164:167], v[84:87]
	v_mfma_f32_16x16x32_bf16 v[80:83], v[202:205], v[164:167], v[80:83]
	v_mfma_f32_16x16x32_bf16 v[76:79], v[188:191], v[172:175], v[76:79]
	v_mfma_f32_16x16x32_bf16 v[72:75], v[202:205], v[172:175], v[72:75]
	v_mfma_f32_16x16x32_bf16 v[68:71], v[188:191], v[180:183], v[68:71]
	v_mfma_f32_16x16x32_bf16 v[64:67], v[202:205], v[180:183], v[64:67]
	v_mfma_f32_16x16x32_bf16 v[92:95], v[192:195], v[160:163], v[92:95]
	s_waitcnt lgkmcnt(0)
	v_mfma_f32_16x16x32_bf16 v[88:91], v[206:209], v[160:163], v[88:91]
	v_mfma_f32_16x16x32_bf16 v[84:87], v[192:195], v[168:171], v[84:87]
	v_mfma_f32_16x16x32_bf16 v[80:83], v[206:209], v[168:171], v[80:83]
	v_mfma_f32_16x16x32_bf16 v[76:79], v[192:195], v[176:179], v[76:79]
	v_mfma_f32_16x16x32_bf16 v[72:75], v[206:209], v[176:179], v[72:75]
	v_mfma_f32_16x16x32_bf16 v[68:71], v[192:195], v[184:187], v[68:71]
	v_mfma_f32_16x16x32_bf16 v[64:67], v[206:209], v[184:187], v[64:67]
	s_barrier
	s_mov_b32 m0, s53
	s_add_u32 s98, s28, s48
	s_addc_u32 s99, s29, s49
	global_load_lds_dwordx4 v128, s[98:99]
	s_mov_b32 m0, s11
	s_nop 0
	global_load_lds_dwordx4 v130, s[98:99]
	s_waitcnt vmcnt(4)
	s_barrier
	s_mov_b32 m0, s9
	s_add_u32 s98, s62, s50
	s_addc_u32 s99, s63, s51
	global_load_lds_dwordx4 v128, s[98:99]
	s_mov_b32 m0, s70
	s_nop 0
	global_load_lds_dwordx4 v130, s[98:99]
	s_barrier
	ds_read_b128 v[140:143], v138
	ds_read_b128 v[144:147], v138 offset:1024
	ds_read_b128 v[148:151], v138 offset:2048
	ds_read_b128 v[156:159], v136 offset:32768
	ds_read_b128 v[164:167], v135 offset:32768
	ds_read_b128 v[172:175], v134 offset:32768
	ds_read_b128 v[152:155], v138 offset:3072
	ds_read_b128 v[160:163], v136 offset:33792
	ds_read_b128 v[168:171], v135 offset:33792
	ds_read_b128 v[176:179], v134 offset:33792
	ds_read_b128 v[180:183], v133 offset:32768
	ds_read_b128 v[184:187], v133 offset:33792
	s_mov_b32 m0, s71
	s_mov_b32 m0, s72
	s_nop 0
	s_waitcnt lgkmcnt(8)
	s_barrier
	s_waitcnt lgkmcnt(8)
	v_mfma_f32_16x16x32_bf16 v[124:127], v[140:143], v[156:159], v[124:127]
	v_mfma_f32_16x16x32_bf16 v[120:123], v[148:151], v[156:159], v[120:123]
	s_waitcnt lgkmcnt(7)
	v_mfma_f32_16x16x32_bf16 v[116:119], v[140:143], v[164:167], v[116:119]
	v_mfma_f32_16x16x32_bf16 v[112:115], v[148:151], v[164:167], v[112:115]
	s_waitcnt lgkmcnt(6)
	v_mfma_f32_16x16x32_bf16 v[108:111], v[140:143], v[172:175], v[108:111]
	v_mfma_f32_16x16x32_bf16 v[104:107], v[148:151], v[172:175], v[104:107]
	s_waitcnt lgkmcnt(1)
	v_mfma_f32_16x16x32_bf16 v[100:103], v[140:143], v[180:183], v[100:103]
	v_mfma_f32_16x16x32_bf16 v[96:99], v[148:151], v[180:183], v[96:99]
	v_mfma_f32_16x16x32_bf16 v[124:127], v[144:147], v[160:163], v[124:127]
	v_mfma_f32_16x16x32_bf16 v[120:123], v[152:155], v[160:163], v[120:123]
	v_mfma_f32_16x16x32_bf16 v[116:119], v[144:147], v[168:171], v[116:119]
	v_mfma_f32_16x16x32_bf16 v[112:115], v[152:155], v[168:171], v[112:115]
	v_mfma_f32_16x16x32_bf16 v[108:111], v[144:147], v[176:179], v[108:111]
	v_mfma_f32_16x16x32_bf16 v[104:107], v[152:155], v[176:179], v[104:107]
	s_waitcnt lgkmcnt(0)
	v_mfma_f32_16x16x32_bf16 v[100:103], v[144:147], v[184:187], v[100:103]
	v_mfma_f32_16x16x32_bf16 v[96:99], v[152:155], v[184:187], v[96:99]
	s_barrier
	ds_read_b128 v[188:191], v137
	ds_read_b128 v[192:195], v137 offset:1024
	ds_read_b128 v[202:205], v137 offset:2048
	ds_read_b128 v[206:209], v137 offset:3072
	s_mov_b32 m0, s66
	s_add_u32 s98, s62, s90
	s_addc_u32 s99, s63, s91
	global_load_lds_dwordx4 v128, s[98:99]
	s_mov_b32 m0, s64
	s_nop 0
	global_load_lds_dwordx4 v130, s[98:99]
	s_barrier
	s_waitcnt lgkmcnt(3)
	v_mfma_f32_16x16x32_bf16 v[92:95], v[188:191], v[156:159], v[92:95]
	s_waitcnt lgkmcnt(1)
	v_mfma_f32_16x16x32_bf16 v[88:91], v[202:205], v[156:159], v[88:91]
	v_mfma_f32_16x16x32_bf16 v[84:87], v[188:191], v[164:167], v[84:87]
	v_mfma_f32_16x16x32_bf16 v[80:83], v[202:205], v[164:167], v[80:83]
	v_mfma_f32_16x16x32_bf16 v[76:79], v[188:191], v[172:175], v[76:79]
	v_mfma_f32_16x16x32_bf16 v[72:75], v[202:205], v[172:175], v[72:75]
	v_mfma_f32_16x16x32_bf16 v[68:71], v[188:191], v[180:183], v[68:71]
	v_mfma_f32_16x16x32_bf16 v[64:67], v[202:205], v[180:183], v[64:67]
	v_mfma_f32_16x16x32_bf16 v[92:95], v[192:195], v[160:163], v[92:95]
	s_waitcnt lgkmcnt(0)
	v_mfma_f32_16x16x32_bf16 v[88:91], v[206:209], v[160:163], v[88:91]
	v_mfma_f32_16x16x32_bf16 v[84:87], v[192:195], v[168:171], v[84:87]
	v_mfma_f32_16x16x32_bf16 v[80:83], v[206:209], v[168:171], v[80:83]
	v_mfma_f32_16x16x32_bf16 v[76:79], v[192:195], v[176:179], v[76:79]
	v_mfma_f32_16x16x32_bf16 v[72:75], v[206:209], v[176:179], v[72:75]
	v_mfma_f32_16x16x32_bf16 v[68:71], v[192:195], v[184:187], v[68:71]
	v_mfma_f32_16x16x32_bf16 v[64:67], v[206:209], v[184:187], v[64:67]
	v_mov_b32_e32 v210, v130
	s_barrier
	v_mov_b32_e32 v211, v197
	s_mov_b32 m0, s65
	s_add_u32 s98, s28, s92
	s_addc_u32 s99, s29, s93
	global_load_lds_dwordx4 v128, s[98:99]
	s_mov_b32 m0, s67
	s_nop 0
	global_load_lds_dwordx4 v130, s[98:99]
	s_waitcnt vmcnt(4)
	s_barrier
	v_mov_b32_e32 v196, v128
	s_mov_b32 m0, s33
	s_add_u32 s98, s62, s96
	s_addc_u32 s99, s63, s97
	global_load_lds_dwordx4 v128, s[98:99]
	s_mov_b32 m0, s73
	s_nop 0
	global_load_lds_dwordx4 v130, s[98:99]
	s_barrier
	s_add_i32 s38, s38, 2
	s_add_u32 s60, s60, 0x100
	s_addc_u32 s61, s61, 0
	s_cmp_lt_u32 s38, 28
	s_cbranch_scc1 .Lh1_loop
	ds_read_b128 v[140:143], v129
	ds_read_b128 v[144:147], v129 offset:1024
	ds_read_b128 v[148:151], v129 offset:2048
	ds_read_b128 v[152:155], v129 offset:3072
	ds_read_b128 v[156:159], v136
	ds_read_b128 v[160:163], v136 offset:1024
	ds_read_b128 v[164:167], v135
	ds_read_b128 v[168:171], v135 offset:1024
	ds_read_b128 v[172:175], v134
	ds_read_b128 v[176:179], v134 offset:1024
	ds_read_b128 v[180:183], v133
	ds_read_b128 v[184:187], v133 offset:1024
	v_mov_b32_e32 v129, v197
	v_lshl_add_u64 v[128:129], s[58:59], 0, v[128:129]
	s_mov_b64 s[28:29], 0xf80
	s_mov_b32 m0, s40
	v_lshl_add_u64 v[128:129], v[128:129], 0, s[28:29]
	v_mov_b32_e32 v131, v197
	v_lshl_add_u64 v[128:129], s[58:59], 0, v[130:131]
	v_lshl_add_u64 v[128:129], v[128:129], 0, s[28:29]
	s_mov_b32 m0, s39
	s_nop 0
	s_barrier
	s_waitcnt lgkmcnt(0)
	s_setprio 1
	s_waitcnt lgkmcnt(0)
	v_mfma_f32_16x16x32_bf16 v[124:127], v[140:143], v[156:159], v[124:127]
	v_mfma_f32_16x16x32_bf16 v[120:123], v[148:151], v[156:159], v[120:123]
	v_mfma_f32_16x16x32_bf16 v[116:119], v[140:143], v[164:167], v[116:119]
	v_mfma_f32_16x16x32_bf16 v[112:115], v[148:151], v[164:167], v[112:115]
	v_mfma_f32_16x16x32_bf16 v[108:111], v[140:143], v[172:175], v[108:111]
	v_mfma_f32_16x16x32_bf16 v[100:103], v[140:143], v[180:183], v[100:103]
	v_mfma_f32_16x16x32_bf16 v[96:99], v[148:151], v[180:183], v[96:99]
	v_mfma_f32_16x16x32_bf16 v[124:127], v[144:147], v[160:163], v[124:127]
	v_mfma_f32_16x16x32_bf16 v[120:123], v[152:155], v[160:163], v[120:123]
	v_mfma_f32_16x16x32_bf16 v[116:119], v[144:147], v[168:171], v[116:119]
	v_mfma_f32_16x16x32_bf16 v[112:115], v[152:155], v[168:171], v[112:115]
	v_mfma_f32_16x16x32_bf16 v[108:111], v[144:147], v[176:179], v[108:111]
	v_mfma_f32_16x16x32_bf16 v[104:107], v[148:151], v[172:175], v[104:107]
	v_mfma_f32_16x16x32_bf16 v[100:103], v[144:147], v[184:187], v[100:103]
	v_mfma_f32_16x16x32_bf16 v[96:99], v[152:155], v[184:187], v[96:99]
	v_mfma_f32_16x16x32_bf16 v[128:131], v[152:155], v[176:179], v[104:107]
	s_setprio 0
	s_barrier
	s_nop 2
	ds_read_b128 v[104:107], v139
	ds_read_b128 v[188:191], v139 offset:1024
	ds_read_b128 v[192:195], v139 offset:2048
	ds_read_b128 v[202:205], v139 offset:3072
	s_barrier
	s_waitcnt lgkmcnt(0)
	s_setprio 1
	s_waitcnt lgkmcnt(0)
	v_mfma_f32_16x16x32_bf16 v[92:95], v[104:107], v[156:159], v[92:95]
	v_mfma_f32_16x16x32_bf16 v[84:87], v[104:107], v[164:167], v[84:87]
	v_mfma_f32_16x16x32_bf16 v[76:79], v[104:107], v[172:175], v[76:79]
	v_mfma_f32_16x16x32_bf16 v[68:71], v[104:107], v[180:183], v[68:71]
	v_mfma_f32_16x16x32_bf16 v[64:67], v[192:195], v[180:183], v[64:67]
	v_mfma_f32_16x16x32_bf16 v[92:95], v[188:191], v[160:163], v[92:95]
	v_mfma_f32_16x16x32_bf16 v[88:91], v[192:195], v[156:159], v[88:91]
	v_mfma_f32_16x16x32_bf16 v[84:87], v[188:191], v[168:171], v[84:87]
	v_mfma_f32_16x16x32_bf16 v[80:83], v[192:195], v[164:167], v[80:83]
	v_mfma_f32_16x16x32_bf16 v[76:79], v[188:191], v[176:179], v[76:79]
	v_mfma_f32_16x16x32_bf16 v[72:75], v[192:195], v[172:175], v[72:75]
	v_mfma_f32_16x16x32_bf16 v[68:71], v[188:191], v[184:187], v[68:71]
	v_mfma_f32_16x16x32_bf16 v[64:67], v[202:205], v[184:187], v[64:67]
	v_mfma_f32_16x16x32_bf16 v[156:159], v[202:205], v[160:163], v[88:91]
	v_mfma_f32_16x16x32_bf16 v[160:163], v[202:205], v[168:171], v[80:83]
	v_mfma_f32_16x16x32_bf16 v[164:167], v[202:205], v[176:179], v[72:75]
	s_setprio 0
	s_barrier
	s_nop 0
	s_waitcnt vmcnt(2)
	s_barrier
	s_waitcnt lgkmcnt(0)
	s_setprio 1
	s_waitcnt lgkmcnt(0)
	s_setprio 0
	s_setprio 1
	s_setprio 0
	s_barrier
	ds_read_b128 v[16:19], v138
	ds_read_b128 v[180:183], v138 offset:1024
	ds_read_b128 v[184:187], v138 offset:2048
	ds_read_b128 v[188:191], v138 offset:3072
	ds_read_b128 v[0:3], v136 offset:32768
	ds_read_b128 v[4:7], v136 offset:33792
	ds_read_b128 v[8:11], v135 offset:32768
	ds_read_b128 v[12:15], v135 offset:33792
	ds_read_b128 v[44:47], v134 offset:32768
	ds_read_b128 v[192:195], v134 offset:33792
	ds_read_b128 v[202:205], v133 offset:32768
	ds_read_b128 v[218:221], v133 offset:33792
	s_waitcnt vmcnt(0)
	s_barrier
	s_waitcnt lgkmcnt(0)
	s_setprio 1
	s_waitcnt lgkmcnt(0)
	v_mfma_f32_16x16x32_bf16 v[28:31], v[16:19], v[0:3], v[124:127]
	v_mfma_f32_16x16x32_bf16 v[52:55], v[180:183], v[4:7], v[28:31]
	v_mfma_f32_16x16x32_bf16 v[28:31], v[184:187], v[0:3], v[120:123]
	v_mfma_f32_16x16x32_bf16 v[104:107], v[188:191], v[4:7], v[28:31]
	v_mfma_f32_16x16x32_bf16 v[28:31], v[16:19], v[8:11], v[116:119]
	v_mfma_f32_16x16x32_bf16 v[72:75], v[180:183], v[12:15], v[28:31]
	v_mfma_f32_16x16x32_bf16 v[28:31], v[184:187], v[8:11], v[112:115]
	v_mfma_f32_16x16x32_bf16 v[116:119], v[188:191], v[12:15], v[28:31]
	v_mfma_f32_16x16x32_bf16 v[28:31], v[16:19], v[44:47], v[108:111]
	v_mfma_f32_16x16x32_bf16 v[80:83], v[180:183], v[192:195], v[28:31]
	v_mfma_f32_16x16x32_bf16 v[28:31], v[184:187], v[44:47], v[128:131]
	v_mfma_f32_16x16x32_bf16 v[108:111], v[188:191], v[192:195], v[28:31]
	v_mfma_f32_16x16x32_bf16 v[28:31], v[16:19], v[202:205], v[100:103]
	v_mfma_f32_16x16x32_bf16 v[88:91], v[180:183], v[218:221], v[28:31]
	v_mfma_f32_16x16x32_bf16 v[28:31], v[184:187], v[202:205], v[96:99]
	v_mfma_f32_16x16x32_bf16 v[96:99], v[188:191], v[218:221], v[28:31]
	s_setprio 0
	s_barrier
	ds_read_b128 v[128:131], v137
	ds_read_b128 v[222:225], v137 offset:1024
	ds_read_b128 v[228:231], v137 offset:2048
	ds_read_b128 v[232:235], v137 offset:3072
	s_waitcnt vmcnt(0)
	s_barrier
	s_waitcnt lgkmcnt(0)
	s_setprio 1
	s_waitcnt lgkmcnt(0)
	v_mfma_f32_16x16x32_bf16 v[28:31], v[128:131], v[0:3], v[92:95]
	v_mfma_f32_16x16x32_bf16 v[0:3], v[228:231], v[0:3], v[156:159]
	v_mfma_f32_16x16x32_bf16 v[28:31], v[222:225], v[4:7], v[28:31]
	v_mfma_f32_16x16x32_bf16 v[0:3], v[232:235], v[4:7], v[0:3]
	v_mfma_f32_16x16x32_bf16 v[4:7], v[128:131], v[8:11], v[84:87]
	v_mfma_f32_16x16x32_bf16 v[36:39], v[222:225], v[12:15], v[4:7]
	v_mfma_f32_16x16x32_bf16 v[4:7], v[228:231], v[8:11], v[160:163]
	v_mfma_f32_16x16x32_bf16 v[4:7], v[232:235], v[12:15], v[4:7]
	v_mfma_f32_16x16x32_bf16 v[8:11], v[128:131], v[44:47], v[76:79]
	v_mfma_f32_16x16x32_bf16 v[12:15], v[128:131], v[202:205], v[68:71]
	v_mfma_f32_16x16x32_bf16 v[40:43], v[222:225], v[192:195], v[8:11]
	v_mfma_f32_16x16x32_bf16 v[8:11], v[228:231], v[44:47], v[164:167]
	v_mfma_f32_16x16x32_bf16 v[44:47], v[222:225], v[218:221], v[12:15]
	v_mfma_f32_16x16x32_bf16 v[12:15], v[228:231], v[202:205], v[64:67]
	v_mfma_f32_16x16x32_bf16 v[8:11], v[232:235], v[192:195], v[8:11]
	v_mfma_f32_16x16x32_bf16 v[12:15], v[232:235], v[218:221], v[12:15]
	s_setprio 0
	s_barrier
	s_barrier
	s_waitcnt lgkmcnt(0)
	s_setprio 1
	s_waitcnt lgkmcnt(0)
	s_setprio 0
	s_setprio 1
	s_setprio 0
	s_movk_i32 s9, 0x100
	v_cmp_gt_u32_e32 vcc, s9, v132
	s_barrier
	s_and_saveexec_b64 s[28:29], vcc
	s_cbranch_execz .Lh1_epi
	s_barrier

.LBB0_255:
	ds_read_b128 v[140:143], v129
	ds_read_b128 v[144:147], v129 offset:1024
	ds_read_b128 v[148:151], v129 offset:2048
	ds_read_b128 v[152:155], v129 offset:3072
	s_add_u32 s28, s60, s56
	s_addc_u32 s29, s61, s57
	ds_read_b128 v[156:159], v136
	ds_read_b128 v[164:167], v135
	ds_read_b128 v[172:175], v134
	ds_read_b128 v[180:183], v133
	ds_read_b128 v[160:163], v136 offset:1024
	ds_read_b128 v[168:171], v135 offset:1024
	ds_read_b128 v[176:179], v134 offset:1024
	ds_read_b128 v[184:187], v133 offset:1024
	s_add_i32 s40, s53, 0xc000
	s_mov_b32 m0, s40
	s_add_i32 s39, s53, 0xe000
	s_add_u32 s98, s28, s44
	s_addc_u32 s99, s29, s45
	global_load_lds_dwordx4 v128, s[98:99]
	s_mov_b32 m0, s39
	s_nop 0
	global_load_lds_dwordx4 v130, s[98:99]
	s_waitcnt lgkmcnt(8)
	s_barrier
	s_waitcnt lgkmcnt(7)
	v_mfma_f32_16x16x32_bf16 v[124:127], v[140:143], v[156:159], v[124:127]
	v_mfma_f32_16x16x32_bf16 v[120:123], v[148:151], v[156:159], v[120:123]
	s_waitcnt lgkmcnt(6)
	v_mfma_f32_16x16x32_bf16 v[116:119], v[140:143], v[164:167], v[116:119]
	v_mfma_f32_16x16x32_bf16 v[112:115], v[148:151], v[164:167], v[112:115]
	s_waitcnt lgkmcnt(5)
	v_mfma_f32_16x16x32_bf16 v[108:111], v[140:143], v[172:175], v[108:111]
	v_mfma_f32_16x16x32_bf16 v[104:107], v[148:151], v[172:175], v[104:107]
	s_waitcnt lgkmcnt(4)
	v_mfma_f32_16x16x32_bf16 v[100:103], v[140:143], v[180:183], v[100:103]
	v_mfma_f32_16x16x32_bf16 v[96:99], v[148:151], v[180:183], v[96:99]
	s_waitcnt lgkmcnt(3)
	v_mfma_f32_16x16x32_bf16 v[124:127], v[144:147], v[160:163], v[124:127]
	v_mfma_f32_16x16x32_bf16 v[120:123], v[152:155], v[160:163], v[120:123]
	s_waitcnt lgkmcnt(2)
	v_mfma_f32_16x16x32_bf16 v[116:119], v[144:147], v[168:171], v[116:119]
	v_mfma_f32_16x16x32_bf16 v[112:115], v[152:155], v[168:171], v[112:115]
	s_waitcnt lgkmcnt(1)
	v_mfma_f32_16x16x32_bf16 v[108:111], v[144:147], v[176:179], v[108:111]
	v_mfma_f32_16x16x32_bf16 v[104:107], v[152:155], v[176:179], v[104:107]
	s_waitcnt lgkmcnt(0)
	v_mfma_f32_16x16x32_bf16 v[100:103], v[144:147], v[184:187], v[100:103]
	v_mfma_f32_16x16x32_bf16 v[96:99], v[152:155], v[184:187], v[96:99]
	s_barrier
	s_add_u32 s62, s60, s36
	s_addc_u32 s63, s61, s37
	ds_read_b128 v[188:191], v139
	ds_read_b128 v[192:195], v139 offset:1024
	ds_read_b128 v[202:205], v139 offset:2048
	ds_read_b128 v[206:209], v139 offset:3072
	s_mov_b32 m0, s68
	s_add_u32 s98, s62, s46
	s_addc_u32 s99, s63, s47
	global_load_lds_dwordx4 v128, s[98:99]
	s_mov_b32 m0, s69
	s_nop 0
	global_load_lds_dwordx4 v130, s[98:99]
	s_barrier
	s_waitcnt lgkmcnt(3)
	v_mfma_f32_16x16x32_bf16 v[92:95], v[188:191], v[156:159], v[92:95]
	s_waitcnt lgkmcnt(1)
	v_mfma_f32_16x16x32_bf16 v[88:91], v[202:205], v[156:159], v[88:91]
	v_mfma_f32_16x16x32_bf16 v[84:87], v[188:191], v[164:167], v[84:87]
	v_mfma_f32_16x16x32_bf16 v[80:83], v[202:205], v[164:167], v[80:83]
	v_mfma_f32_16x16x32_bf16 v[76:79], v[188:191], v[172:175], v[76:79]
	v_mfma_f32_16x16x32_bf16 v[72:75], v[202:205], v[172:175], v[72:75]
	v_mfma_f32_16x16x32_bf16 v[68:71], v[188:191], v[180:183], v[68:71]
	v_mfma_f32_16x16x32_bf16 v[64:67], v[202:205], v[180:183], v[64:67]
	v_mfma_f32_16x16x32_bf16 v[92:95], v[192:195], v[160:163], v[92:95]
	s_waitcnt lgkmcnt(0)
	v_mfma_f32_16x16x32_bf16 v[88:91], v[206:209], v[160:163], v[88:91]
	v_mfma_f32_16x16x32_bf16 v[84:87], v[192:195], v[168:171], v[84:87]
	v_mfma_f32_16x16x32_bf16 v[80:83], v[206:209], v[168:171], v[80:83]
	v_mfma_f32_16x16x32_bf16 v[76:79], v[192:195], v[176:179], v[76:79]
	v_mfma_f32_16x16x32_bf16 v[72:75], v[206:209], v[176:179], v[72:75]
	v_mfma_f32_16x16x32_bf16 v[68:71], v[192:195], v[184:187], v[68:71]
	v_mfma_f32_16x16x32_bf16 v[64:67], v[206:209], v[184:187], v[64:67]
	s_barrier
	ds_read_b128 v[156:159], v136 offset:16384
	ds_read_b128 v[164:167], v135 offset:16384
	ds_read_b128 v[172:175], v134 offset:16384
	ds_read_b128 v[180:183], v133 offset:16384
	ds_read_b128 v[160:163], v136 offset:17408
	ds_read_b128 v[168:171], v135 offset:17408
	ds_read_b128 v[176:179], v134 offset:17408
	ds_read_b128 v[184:187], v133 offset:17408
	s_mov_b32 m0, s53
	s_add_u32 s98, s28, s48
	s_addc_u32 s99, s29, s49
	global_load_lds_dwordx4 v128, s[98:99]
	s_mov_b32 m0, s11
	s_nop 0
	global_load_lds_dwordx4 v130, s[98:99]
	s_barrier
	s_waitcnt lgkmcnt(7)
	v_mfma_f32_16x16x32_bf16 v[60:63], v[140:143], v[156:159], v[60:63]
	v_mfma_f32_16x16x32_bf16 v[56:59], v[148:151], v[156:159], v[56:59]
	s_waitcnt lgkmcnt(6)
	v_mfma_f32_16x16x32_bf16 v[52:55], v[140:143], v[164:167], v[52:55]
	v_mfma_f32_16x16x32_bf16 v[48:51], v[148:151], v[164:167], v[48:51]
	s_waitcnt lgkmcnt(5)
	v_mfma_f32_16x16x32_bf16 v[44:47], v[140:143], v[172:175], v[44:47]
	v_mfma_f32_16x16x32_bf16 v[40:43], v[148:151], v[172:175], v[40:43]
	s_waitcnt lgkmcnt(4)
	v_mfma_f32_16x16x32_bf16 v[36:39], v[140:143], v[180:183], v[36:39]
	v_mfma_f32_16x16x32_bf16 v[32:35], v[148:151], v[180:183], v[32:35]
	s_waitcnt lgkmcnt(3)
	v_mfma_f32_16x16x32_bf16 v[60:63], v[144:147], v[160:163], v[60:63]
	v_mfma_f32_16x16x32_bf16 v[56:59], v[152:155], v[160:163], v[56:59]
	s_waitcnt lgkmcnt(2)
	v_mfma_f32_16x16x32_bf16 v[52:55], v[144:147], v[168:171], v[52:55]
	v_mfma_f32_16x16x32_bf16 v[48:51], v[152:155], v[168:171], v[48:51]
	s_waitcnt lgkmcnt(1)
	v_mfma_f32_16x16x32_bf16 v[44:47], v[144:147], v[176:179], v[44:47]
	v_mfma_f32_16x16x32_bf16 v[40:43], v[152:155], v[176:179], v[40:43]
	s_waitcnt lgkmcnt(0)
	v_mfma_f32_16x16x32_bf16 v[36:39], v[144:147], v[184:187], v[36:39]
	v_mfma_f32_16x16x32_bf16 v[32:35], v[152:155], v[184:187], v[32:35]
	s_barrier
	s_mov_b32 m0, s9
	s_add_u32 s98, s62, s50
	s_addc_u32 s99, s63, s51
	global_load_lds_dwordx4 v128, s[98:99]
	s_mov_b32 m0, s70
	s_nop 0
	global_load_lds_dwordx4 v130, s[98:99]
	s_waitcnt vmcnt(6)
	s_barrier
	v_mfma_f32_16x16x32_bf16 v[28:31], v[188:191], v[156:159], v[28:31]
	v_mfma_f32_16x16x32_bf16 v[24:27], v[202:205], v[156:159], v[24:27]
	v_mfma_f32_16x16x32_bf16 v[20:23], v[188:191], v[164:167], v[20:23]
	v_mfma_f32_16x16x32_bf16 v[16:19], v[202:205], v[164:167], v[16:19]
	v_mfma_f32_16x16x32_bf16 v[12:15], v[188:191], v[172:175], v[12:15]
	v_mfma_f32_16x16x32_bf16 v[8:11], v[202:205], v[172:175], v[8:11]
	v_mfma_f32_16x16x32_bf16 v[4:7], v[188:191], v[180:183], v[4:7]
	v_mfma_f32_16x16x32_bf16 v[0:3], v[202:205], v[180:183], v[0:3]
	v_mfma_f32_16x16x32_bf16 v[28:31], v[192:195], v[160:163], v[28:31]
	v_mfma_f32_16x16x32_bf16 v[24:27], v[206:209], v[160:163], v[24:27]
	v_mfma_f32_16x16x32_bf16 v[20:23], v[192:195], v[168:171], v[20:23]
	v_mfma_f32_16x16x32_bf16 v[16:19], v[206:209], v[168:171], v[16:19]
	v_mfma_f32_16x16x32_bf16 v[12:15], v[192:195], v[176:179], v[12:15]
	v_mfma_f32_16x16x32_bf16 v[8:11], v[206:209], v[176:179], v[8:11]
	v_mfma_f32_16x16x32_bf16 v[4:7], v[192:195], v[184:187], v[4:7]
	v_mfma_f32_16x16x32_bf16 v[0:3], v[206:209], v[184:187], v[0:3]
	s_barrier
	ds_read_b128 v[140:143], v138
	ds_read_b128 v[144:147], v138 offset:1024
	ds_read_b128 v[148:151], v138 offset:2048
	ds_read_b128 v[152:155], v138 offset:3072
	ds_read_b128 v[156:159], v136 offset:32768
	ds_read_b128 v[164:167], v135 offset:32768
	ds_read_b128 v[172:175], v134 offset:32768
	ds_read_b128 v[180:183], v133 offset:32768
	ds_read_b128 v[160:163], v136 offset:33792
	ds_read_b128 v[168:171], v135 offset:33792
	ds_read_b128 v[176:179], v134 offset:33792
	ds_read_b128 v[184:187], v133 offset:33792
	s_mov_b32 m0, s71
	s_add_u32 s98, s28, s74
	s_addc_u32 s99, s29, s75
	global_load_lds_dwordx4 v128, s[98:99]
	s_mov_b32 m0, s72
	s_nop 0
	global_load_lds_dwordx4 v130, s[98:99]
	s_waitcnt lgkmcnt(8)
	s_barrier
	s_waitcnt lgkmcnt(7)
	v_mfma_f32_16x16x32_bf16 v[124:127], v[140:143], v[156:159], v[124:127]
	v_mfma_f32_16x16x32_bf16 v[120:123], v[148:151], v[156:159], v[120:123]
	s_waitcnt lgkmcnt(6)
	v_mfma_f32_16x16x32_bf16 v[116:119], v[140:143], v[164:167], v[116:119]
	v_mfma_f32_16x16x32_bf16 v[112:115], v[148:151], v[164:167], v[112:115]
	s_waitcnt lgkmcnt(5)
	v_mfma_f32_16x16x32_bf16 v[108:111], v[140:143], v[172:175], v[108:111]
	v_mfma_f32_16x16x32_bf16 v[104:107], v[148:151], v[172:175], v[104:107]
	s_waitcnt lgkmcnt(4)
	v_mfma_f32_16x16x32_bf16 v[100:103], v[140:143], v[180:183], v[100:103]
	v_mfma_f32_16x16x32_bf16 v[96:99], v[148:151], v[180:183], v[96:99]
	s_waitcnt lgkmcnt(3)
	v_mfma_f32_16x16x32_bf16 v[124:127], v[144:147], v[160:163], v[124:127]
	v_mfma_f32_16x16x32_bf16 v[120:123], v[152:155], v[160:163], v[120:123]
	s_waitcnt lgkmcnt(2)
	v_mfma_f32_16x16x32_bf16 v[116:119], v[144:147], v[168:171], v[116:119]
	v_mfma_f32_16x16x32_bf16 v[112:115], v[152:155], v[168:171], v[112:115]
	s_waitcnt lgkmcnt(1)
	v_mfma_f32_16x16x32_bf16 v[108:111], v[144:147], v[176:179], v[108:111]
	v_mfma_f32_16x16x32_bf16 v[104:107], v[152:155], v[176:179], v[104:107]
	s_waitcnt lgkmcnt(0)
	v_mfma_f32_16x16x32_bf16 v[100:103], v[144:147], v[184:187], v[100:103]
	v_mfma_f32_16x16x32_bf16 v[96:99], v[152:155], v[184:187], v[96:99]
	s_barrier
	ds_read_b128 v[188:191], v137
	ds_read_b128 v[192:195], v137 offset:1024
	ds_read_b128 v[202:205], v137 offset:2048
	ds_read_b128 v[206:209], v137 offset:3072
	s_mov_b32 m0, s66
	s_add_u32 s98, s62, s90
	s_addc_u32 s99, s63, s91
	global_load_lds_dwordx4 v128, s[98:99]
	s_mov_b32 m0, s64
	s_nop 0
	global_load_lds_dwordx4 v130, s[98:99]
	s_barrier
	s_waitcnt lgkmcnt(3)
	v_mfma_f32_16x16x32_bf16 v[92:95], v[188:191], v[156:159], v[92:95]
	s_waitcnt lgkmcnt(1)
	v_mfma_f32_16x16x32_bf16 v[88:91], v[202:205], v[156:159], v[88:91]
	v_mfma_f32_16x16x32_bf16 v[84:87], v[188:191], v[164:167], v[84:87]
	v_mfma_f32_16x16x32_bf16 v[80:83], v[202:205], v[164:167], v[80:83]
	v_mfma_f32_16x16x32_bf16 v[76:79], v[188:191], v[172:175], v[76:79]
	v_mfma_f32_16x16x32_bf16 v[72:75], v[202:205], v[172:175], v[72:75]
	v_mfma_f32_16x16x32_bf16 v[68:71], v[188:191], v[180:183], v[68:71]
	v_mfma_f32_16x16x32_bf16 v[64:67], v[202:205], v[180:183], v[64:67]
	v_mfma_f32_16x16x32_bf16 v[92:95], v[192:195], v[160:163], v[92:95]
	s_waitcnt lgkmcnt(0)
	v_mfma_f32_16x16x32_bf16 v[88:91], v[206:209], v[160:163], v[88:91]
	v_mfma_f32_16x16x32_bf16 v[84:87], v[192:195], v[168:171], v[84:87]
	v_mfma_f32_16x16x32_bf16 v[80:83], v[206:209], v[168:171], v[80:83]
	v_mfma_f32_16x16x32_bf16 v[76:79], v[192:195], v[176:179], v[76:79]
	v_mfma_f32_16x16x32_bf16 v[72:75], v[206:209], v[176:179], v[72:75]
	v_mfma_f32_16x16x32_bf16 v[68:71], v[192:195], v[184:187], v[68:71]
	v_mfma_f32_16x16x32_bf16 v[64:67], v[206:209], v[184:187], v[64:67]
	v_mov_b32_e32 v210, v130
	s_barrier
	ds_read_b128 v[156:159], v136 offset:49152
	ds_read_b128 v[164:167], v135 offset:49152
	ds_read_b128 v[172:175], v134 offset:49152
	ds_read_b128 v[180:183], v133 offset:49152
	ds_read_b128 v[160:163], v136 offset:50176
	ds_read_b128 v[168:171], v135 offset:50176
	ds_read_b128 v[176:179], v134 offset:50176
	ds_read_b128 v[184:187], v133 offset:50176
	v_mov_b32_e32 v211, v197
	s_mov_b32 m0, s65
	s_add_u32 s98, s28, s92
	s_addc_u32 s99, s29, s93
	global_load_lds_dwordx4 v128, s[98:99]
	s_mov_b32 m0, s67
	s_nop 0
	global_load_lds_dwordx4 v130, s[98:99]
	s_barrier
	s_waitcnt lgkmcnt(7)
	v_mfma_f32_16x16x32_bf16 v[60:63], v[140:143], v[156:159], v[60:63]
	v_mfma_f32_16x16x32_bf16 v[56:59], v[148:151], v[156:159], v[56:59]
	s_waitcnt lgkmcnt(6)
	v_mfma_f32_16x16x32_bf16 v[52:55], v[140:143], v[164:167], v[52:55]
	v_mfma_f32_16x16x32_bf16 v[48:51], v[148:151], v[164:167], v[48:51]
	s_waitcnt lgkmcnt(5)
	v_mfma_f32_16x16x32_bf16 v[44:47], v[140:143], v[172:175], v[44:47]
	v_mfma_f32_16x16x32_bf16 v[40:43], v[148:151], v[172:175], v[40:43]
	s_waitcnt lgkmcnt(4)
	v_mfma_f32_16x16x32_bf16 v[36:39], v[140:143], v[180:183], v[36:39]
	v_mfma_f32_16x16x32_bf16 v[32:35], v[148:151], v[180:183], v[32:35]
	s_waitcnt lgkmcnt(3)
	v_mfma_f32_16x16x32_bf16 v[60:63], v[144:147], v[160:163], v[60:63]
	v_mfma_f32_16x16x32_bf16 v[56:59], v[152:155], v[160:163], v[56:59]
	s_waitcnt lgkmcnt(2)
	v_mfma_f32_16x16x32_bf16 v[52:55], v[144:147], v[168:171], v[52:55]
	v_mfma_f32_16x16x32_bf16 v[48:51], v[152:155], v[168:171], v[48:51]
	s_waitcnt lgkmcnt(1)
	v_mfma_f32_16x16x32_bf16 v[44:47], v[144:147], v[176:179], v[44:47]
	v_mfma_f32_16x16x32_bf16 v[40:43], v[152:155], v[176:179], v[40:43]
	s_waitcnt lgkmcnt(0)
	v_mfma_f32_16x16x32_bf16 v[36:39], v[144:147], v[184:187], v[36:39]
	v_mfma_f32_16x16x32_bf16 v[32:35], v[152:155], v[184:187], v[32:35]
	s_barrier
	v_mov_b32_e32 v196, v128
	s_mov_b32 m0, s33
	s_add_u32 s98, s62, s96
	s_addc_u32 s99, s63, s97
	global_load_lds_dwordx4 v128, s[98:99]
	s_mov_b32 m0, s73
	s_nop 0
	global_load_lds_dwordx4 v130, s[98:99]
	s_waitcnt vmcnt(6)
	s_barrier
	v_mfma_f32_16x16x32_bf16 v[28:31], v[188:191], v[156:159], v[28:31]
	v_mfma_f32_16x16x32_bf16 v[24:27], v[202:205], v[156:159], v[24:27]
	v_mfma_f32_16x16x32_bf16 v[20:23], v[188:191], v[164:167], v[20:23]
	v_mfma_f32_16x16x32_bf16 v[16:19], v[202:205], v[164:167], v[16:19]
	v_mfma_f32_16x16x32_bf16 v[12:15], v[188:191], v[172:175], v[12:15]
	v_mfma_f32_16x16x32_bf16 v[8:11], v[202:205], v[172:175], v[8:11]
	v_mfma_f32_16x16x32_bf16 v[4:7], v[188:191], v[180:183], v[4:7]
	v_mfma_f32_16x16x32_bf16 v[0:3], v[202:205], v[180:183], v[0:3]
	v_mfma_f32_16x16x32_bf16 v[28:31], v[192:195], v[160:163], v[28:31]
	v_mfma_f32_16x16x32_bf16 v[24:27], v[206:209], v[160:163], v[24:27]
	v_mfma_f32_16x16x32_bf16 v[20:23], v[192:195], v[168:171], v[20:23]
	v_mfma_f32_16x16x32_bf16 v[16:19], v[206:209], v[168:171], v[16:19]
	v_mfma_f32_16x16x32_bf16 v[12:15], v[192:195], v[176:179], v[12:15]
	v_mfma_f32_16x16x32_bf16 v[8:11], v[206:209], v[176:179], v[8:11]
	v_mfma_f32_16x16x32_bf16 v[4:7], v[192:195], v[184:187], v[4:7]
	v_mfma_f32_16x16x32_bf16 v[0:3], v[206:209], v[184:187], v[0:3]
	s_add_i32 s38, s38, 2
	s_add_u32 s60, s60, 0x100
	s_addc_u32 s61, s61, 0
	s_cmp_lt_u32 s38, 28
	s_barrier
	s_cbranch_scc1 .LBB0_255
	ds_read_b128 v[140:143], v129
	ds_read_b128 v[144:147], v129 offset:1024
	ds_read_b128 v[148:151], v129 offset:2048
	ds_read_b128 v[152:155], v129 offset:3072
	ds_read_b128 v[156:159], v136
	ds_read_b128 v[160:163], v136 offset:1024
	ds_read_b128 v[164:167], v135
	ds_read_b128 v[168:171], v135 offset:1024
	ds_read_b128 v[172:175], v134
	ds_read_b128 v[176:179], v134 offset:1024
	ds_read_b128 v[180:183], v133
	ds_read_b128 v[184:187], v133 offset:1024
	v_mov_b32_e32 v129, v197
	v_lshl_add_u64 v[128:129], s[58:59], 0, v[128:129]
	s_mov_b64 s[28:29], 0xf80
	s_mov_b32 m0, s40
	v_lshl_add_u64 v[128:129], v[128:129], 0, s[28:29]
	v_mov_b32_e32 v131, v197
	global_load_lds_dwordx4 v[128:129], off
	v_lshl_add_u64 v[128:129], s[58:59], 0, v[130:131]
	v_lshl_add_u64 v[128:129], v[128:129], 0, s[28:29]
	s_mov_b32 m0, s39
	s_nop 0
	global_load_lds_dwordx4 v[128:129], off
	s_barrier
	s_waitcnt lgkmcnt(0)
	s_setprio 1
	s_waitcnt lgkmcnt(0)
	v_mfma_f32_16x16x32_bf16 v[124:127], v[140:143], v[156:159], v[124:127]
	v_mfma_f32_16x16x32_bf16 v[120:123], v[148:151], v[156:159], v[120:123]
	v_mfma_f32_16x16x32_bf16 v[116:119], v[140:143], v[164:167], v[116:119]
	v_mfma_f32_16x16x32_bf16 v[112:115], v[148:151], v[164:167], v[112:115]
	v_mfma_f32_16x16x32_bf16 v[108:111], v[140:143], v[172:175], v[108:111]
	v_mfma_f32_16x16x32_bf16 v[100:103], v[140:143], v[180:183], v[100:103]
	v_mfma_f32_16x16x32_bf16 v[96:99], v[148:151], v[180:183], v[96:99]
	v_mfma_f32_16x16x32_bf16 v[124:127], v[144:147], v[160:163], v[124:127]
	v_mfma_f32_16x16x32_bf16 v[120:123], v[152:155], v[160:163], v[120:123]
	v_mfma_f32_16x16x32_bf16 v[116:119], v[144:147], v[168:171], v[116:119]
	v_mfma_f32_16x16x32_bf16 v[112:115], v[152:155], v[168:171], v[112:115]
	v_mfma_f32_16x16x32_bf16 v[108:111], v[144:147], v[176:179], v[108:111]
	v_mfma_f32_16x16x32_bf16 v[104:107], v[148:151], v[172:175], v[104:107]
	v_mfma_f32_16x16x32_bf16 v[100:103], v[144:147], v[184:187], v[100:103]
	v_mfma_f32_16x16x32_bf16 v[96:99], v[152:155], v[184:187], v[96:99]
	v_mfma_f32_16x16x32_bf16 v[128:131], v[152:155], v[176:179], v[104:107]
	s_setprio 0
	s_barrier
	s_nop 2
	ds_read_b128 v[104:107], v139
	ds_read_b128 v[188:191], v139 offset:1024
	ds_read_b128 v[192:195], v139 offset:2048
	ds_read_b128 v[202:205], v139 offset:3072
	s_barrier
	s_waitcnt lgkmcnt(0)
	s_setprio 1
	s_waitcnt lgkmcnt(0)
	v_mfma_f32_16x16x32_bf16 v[92:95], v[104:107], v[156:159], v[92:95]
	v_mfma_f32_16x16x32_bf16 v[84:87], v[104:107], v[164:167], v[84:87]
	v_mfma_f32_16x16x32_bf16 v[76:79], v[104:107], v[172:175], v[76:79]
	v_mfma_f32_16x16x32_bf16 v[68:71], v[104:107], v[180:183], v[68:71]
	v_mfma_f32_16x16x32_bf16 v[64:67], v[192:195], v[180:183], v[64:67]
	v_mfma_f32_16x16x32_bf16 v[92:95], v[188:191], v[160:163], v[92:95]
	v_mfma_f32_16x16x32_bf16 v[88:91], v[192:195], v[156:159], v[88:91]
	v_mfma_f32_16x16x32_bf16 v[84:87], v[188:191], v[168:171], v[84:87]
	v_mfma_f32_16x16x32_bf16 v[80:83], v[192:195], v[164:167], v[80:83]
	v_mfma_f32_16x16x32_bf16 v[76:79], v[188:191], v[176:179], v[76:79]
	v_mfma_f32_16x16x32_bf16 v[72:75], v[192:195], v[172:175], v[72:75]
	v_mfma_f32_16x16x32_bf16 v[68:71], v[188:191], v[184:187], v[68:71]
	v_mfma_f32_16x16x32_bf16 v[64:67], v[202:205], v[184:187], v[64:67]
	v_mfma_f32_16x16x32_bf16 v[156:159], v[202:205], v[160:163], v[88:91]
	v_mfma_f32_16x16x32_bf16 v[160:163], v[202:205], v[168:171], v[80:83]
	v_mfma_f32_16x16x32_bf16 v[164:167], v[202:205], v[176:179], v[72:75]
	s_setprio 0
	s_barrier
	s_nop 0
	ds_read_b128 v[72:75], v136 offset:16384
	ds_read_b128 v[80:83], v136 offset:17408
	ds_read_b128 v[88:91], v135 offset:16384
	ds_read_b128 v[168:171], v135 offset:17408
	ds_read_b128 v[172:175], v134 offset:16384
	ds_read_b128 v[176:179], v134 offset:17408
	ds_read_b128 v[180:183], v133 offset:16384
	ds_read_b128 v[184:187], v133 offset:17408
	s_waitcnt vmcnt(4)
	s_barrier
	s_waitcnt lgkmcnt(0)
	s_setprio 1
	s_waitcnt lgkmcnt(0)
	v_mfma_f32_16x16x32_bf16 v[60:63], v[140:143], v[72:75], v[60:63]
	v_mfma_f32_16x16x32_bf16 v[56:59], v[148:151], v[72:75], v[56:59]
	v_mfma_f32_16x16x32_bf16 v[48:51], v[148:151], v[88:91], v[48:51]
	v_mfma_f32_16x16x32_bf16 v[32:35], v[148:151], v[180:183], v[32:35]
	v_mfma_f32_16x16x32_bf16 v[60:63], v[144:147], v[80:83], v[60:63]
	v_mfma_f32_16x16x32_bf16 v[56:59], v[152:155], v[80:83], v[56:59]
	v_mfma_f32_16x16x32_bf16 v[52:55], v[140:143], v[88:91], v[52:55]
	v_mfma_f32_16x16x32_bf16 v[48:51], v[152:155], v[168:171], v[48:51]
	v_mfma_f32_16x16x32_bf16 v[44:47], v[140:143], v[172:175], v[44:47]
	v_mfma_f32_16x16x32_bf16 v[40:43], v[148:151], v[172:175], v[40:43]
	v_mfma_f32_16x16x32_bf16 v[36:39], v[140:143], v[180:183], v[36:39]
	v_mfma_f32_16x16x32_bf16 v[32:35], v[152:155], v[184:187], v[32:35]
	v_mfma_f32_16x16x32_bf16 v[206:209], v[144:147], v[168:171], v[52:55]
	v_mfma_f32_16x16x32_bf16 v[210:213], v[144:147], v[176:179], v[44:47]
	v_mfma_f32_16x16x32_bf16 v[214:217], v[152:155], v[176:179], v[40:43]
	v_mfma_f32_16x16x32_bf16 v[140:143], v[144:147], v[184:187], v[36:39]
	s_setprio 0
	s_setprio 1
	v_mfma_f32_16x16x32_bf16 v[24:27], v[192:195], v[72:75], v[24:27]
	v_mfma_f32_16x16x32_bf16 v[20:23], v[104:107], v[88:91], v[20:23]
	v_mfma_f32_16x16x32_bf16 v[28:31], v[104:107], v[72:75], v[28:31]
	v_mfma_f32_16x16x32_bf16 v[24:27], v[202:205], v[80:83], v[24:27]
	v_mfma_f32_16x16x32_bf16 v[20:23], v[188:191], v[168:171], v[20:23]
	v_mfma_f32_16x16x32_bf16 v[16:19], v[192:195], v[88:91], v[16:19]
	v_mfma_f32_16x16x32_bf16 v[12:15], v[104:107], v[172:175], v[12:15]
	v_mfma_f32_16x16x32_bf16 v[8:11], v[192:195], v[172:175], v[8:11]
	v_mfma_f32_16x16x32_bf16 v[4:7], v[104:107], v[180:183], v[4:7]
	v_mfma_f32_16x16x32_bf16 v[0:3], v[192:195], v[180:183], v[0:3]
	v_mfma_f32_16x16x32_bf16 v[144:147], v[188:191], v[80:83], v[28:31]
	v_mfma_f32_16x16x32_bf16 v[148:151], v[202:205], v[168:171], v[16:19]
	v_mfma_f32_16x16x32_bf16 v[152:155], v[188:191], v[176:179], v[12:15]
	v_mfma_f32_16x16x32_bf16 v[168:171], v[202:205], v[176:179], v[8:11]
	v_mfma_f32_16x16x32_bf16 v[172:175], v[188:191], v[184:187], v[4:7]
	v_mfma_f32_16x16x32_bf16 v[176:179], v[202:205], v[184:187], v[0:3]
	s_setprio 0
	s_barrier
	ds_read_b128 v[16:19], v138
	ds_read_b128 v[180:183], v138 offset:1024
	ds_read_b128 v[184:187], v138 offset:2048
	ds_read_b128 v[188:191], v138 offset:3072
	ds_read_b128 v[0:3], v136 offset:32768
	ds_read_b128 v[4:7], v136 offset:33792
	ds_read_b128 v[8:11], v135 offset:32768
	ds_read_b128 v[12:15], v135 offset:33792
	ds_read_b128 v[44:47], v134 offset:32768
	ds_read_b128 v[192:195], v134 offset:33792
	ds_read_b128 v[202:205], v133 offset:32768
	ds_read_b128 v[218:221], v133 offset:33792
	s_waitcnt vmcnt(2)
	s_barrier
	s_waitcnt lgkmcnt(0)
	s_setprio 1
	s_waitcnt lgkmcnt(0)
	v_mfma_f32_16x16x32_bf16 v[28:31], v[16:19], v[0:3], v[124:127]
	v_mfma_f32_16x16x32_bf16 v[52:55], v[180:183], v[4:7], v[28:31]
	v_mfma_f32_16x16x32_bf16 v[28:31], v[184:187], v[0:3], v[120:123]
	v_mfma_f32_16x16x32_bf16 v[104:107], v[188:191], v[4:7], v[28:31]
	v_mfma_f32_16x16x32_bf16 v[28:31], v[16:19], v[8:11], v[116:119]
	v_mfma_f32_16x16x32_bf16 v[72:75], v[180:183], v[12:15], v[28:31]
	v_mfma_f32_16x16x32_bf16 v[28:31], v[184:187], v[8:11], v[112:115]
	v_mfma_f32_16x16x32_bf16 v[116:119], v[188:191], v[12:15], v[28:31]
	v_mfma_f32_16x16x32_bf16 v[28:31], v[16:19], v[44:47], v[108:111]
	v_mfma_f32_16x16x32_bf16 v[80:83], v[180:183], v[192:195], v[28:31]
	v_mfma_f32_16x16x32_bf16 v[28:31], v[184:187], v[44:47], v[128:131]
	v_mfma_f32_16x16x32_bf16 v[108:111], v[188:191], v[192:195], v[28:31]
	v_mfma_f32_16x16x32_bf16 v[28:31], v[16:19], v[202:205], v[100:103]
	v_mfma_f32_16x16x32_bf16 v[88:91], v[180:183], v[218:221], v[28:31]
	v_mfma_f32_16x16x32_bf16 v[28:31], v[184:187], v[202:205], v[96:99]
	v_mfma_f32_16x16x32_bf16 v[96:99], v[188:191], v[218:221], v[28:31]
	s_setprio 0
	s_barrier
	ds_read_b128 v[128:131], v137
	ds_read_b128 v[222:225], v137 offset:1024
	ds_read_b128 v[228:231], v137 offset:2048
	ds_read_b128 v[232:235], v137 offset:3072
	s_waitcnt vmcnt(0)
	s_barrier
	s_waitcnt lgkmcnt(0)
	s_setprio 1
	s_waitcnt lgkmcnt(0)
	v_mfma_f32_16x16x32_bf16 v[28:31], v[128:131], v[0:3], v[92:95]
	v_mfma_f32_16x16x32_bf16 v[0:3], v[228:231], v[0:3], v[156:159]
	v_mfma_f32_16x16x32_bf16 v[28:31], v[222:225], v[4:7], v[28:31]
	v_mfma_f32_16x16x32_bf16 v[0:3], v[232:235], v[4:7], v[0:3]
	v_mfma_f32_16x16x32_bf16 v[4:7], v[128:131], v[8:11], v[84:87]
	v_mfma_f32_16x16x32_bf16 v[36:39], v[222:225], v[12:15], v[4:7]
	v_mfma_f32_16x16x32_bf16 v[4:7], v[228:231], v[8:11], v[160:163]
	v_mfma_f32_16x16x32_bf16 v[4:7], v[232:235], v[12:15], v[4:7]
	v_mfma_f32_16x16x32_bf16 v[8:11], v[128:131], v[44:47], v[76:79]
	v_mfma_f32_16x16x32_bf16 v[12:15], v[128:131], v[202:205], v[68:71]
	v_mfma_f32_16x16x32_bf16 v[40:43], v[222:225], v[192:195], v[8:11]
	v_mfma_f32_16x16x32_bf16 v[8:11], v[228:231], v[44:47], v[164:167]
	v_mfma_f32_16x16x32_bf16 v[44:47], v[222:225], v[218:221], v[12:15]
	v_mfma_f32_16x16x32_bf16 v[12:15], v[228:231], v[202:205], v[64:67]
	v_mfma_f32_16x16x32_bf16 v[8:11], v[232:235], v[192:195], v[8:11]
	v_mfma_f32_16x16x32_bf16 v[12:15], v[232:235], v[218:221], v[12:15]
	s_setprio 0
	s_barrier
	ds_read_b128 v[64:67], v136 offset:49152
	ds_read_b128 v[136:139], v136 offset:50176
	ds_read_b128 v[156:159], v135 offset:49152
	ds_read_b128 v[160:163], v135 offset:50176
	ds_read_b128 v[164:167], v134 offset:49152
	ds_read_b128 v[192:195], v134 offset:50176
	ds_read_b128 v[202:205], v133 offset:49152
	ds_read_b128 v[218:221], v133 offset:50176
	s_barrier
	s_waitcnt lgkmcnt(0)
	s_setprio 1
	s_waitcnt lgkmcnt(0)
	v_mfma_f32_16x16x32_bf16 v[56:59], v[184:187], v[64:67], v[56:59]
	v_mfma_f32_16x16x32_bf16 v[48:51], v[184:187], v[156:159], v[48:51]
	v_mfma_f32_16x16x32_bf16 v[60:63], v[16:19], v[64:67], v[60:63]
	v_mfma_f32_16x16x32_bf16 v[92:95], v[188:191], v[136:139], v[56:59]
	v_mfma_f32_16x16x32_bf16 v[56:59], v[16:19], v[156:159], v[206:209]
	v_mfma_f32_16x16x32_bf16 v[84:87], v[188:191], v[160:163], v[48:51]
	v_mfma_f32_16x16x32_bf16 v[48:51], v[16:19], v[164:167], v[210:213]
	v_mfma_f32_16x16x32_bf16 v[16:19], v[16:19], v[202:205], v[140:143]
	v_mfma_f32_16x16x32_bf16 v[120:123], v[180:183], v[192:195], v[48:51]
	v_mfma_f32_16x16x32_bf16 v[48:51], v[184:187], v[164:167], v[214:217]
	v_mfma_f32_16x16x32_bf16 v[124:127], v[180:183], v[218:221], v[16:19]
	v_mfma_f32_16x16x32_bf16 v[16:19], v[184:187], v[202:205], v[32:35]
	v_mfma_f32_16x16x32_bf16 v[100:103], v[180:183], v[136:139], v[60:63]
	v_mfma_f32_16x16x32_bf16 v[112:115], v[180:183], v[160:163], v[56:59]
	v_mfma_f32_16x16x32_bf16 v[76:79], v[188:191], v[192:195], v[48:51]
	v_mfma_f32_16x16x32_bf16 v[68:71], v[188:191], v[218:221], v[16:19]
	s_setprio 0
	s_setprio 1
	v_mfma_f32_16x16x32_bf16 v[16:19], v[128:131], v[64:67], v[144:147]
	v_mfma_f32_16x16x32_bf16 v[48:51], v[222:225], v[136:139], v[16:19]
	v_mfma_f32_16x16x32_bf16 v[16:19], v[228:231], v[64:67], v[24:27]
	v_mfma_f32_16x16x32_bf16 v[20:23], v[128:131], v[156:159], v[20:23]
	v_mfma_f32_16x16x32_bf16 v[24:27], v[128:131], v[164:167], v[152:155]
	v_mfma_f32_16x16x32_bf16 v[32:35], v[128:131], v[202:205], v[172:175]
	v_mfma_f32_16x16x32_bf16 v[56:59], v[222:225], v[160:163], v[20:23]
	v_mfma_f32_16x16x32_bf16 v[20:23], v[228:231], v[156:159], v[148:151]
	v_mfma_f32_16x16x32_bf16 v[60:63], v[222:225], v[192:195], v[24:27]
	v_mfma_f32_16x16x32_bf16 v[24:27], v[228:231], v[164:167], v[168:171]
	v_mfma_f32_16x16x32_bf16 v[64:67], v[222:225], v[218:221], v[32:35]
	v_mfma_f32_16x16x32_bf16 v[32:35], v[228:231], v[202:205], v[176:179]
	v_mfma_f32_16x16x32_bf16 v[16:19], v[232:235], v[136:139], v[16:19]
	v_mfma_f32_16x16x32_bf16 v[20:23], v[232:235], v[160:163], v[20:23]
	v_mfma_f32_16x16x32_bf16 v[24:27], v[232:235], v[192:195], v[24:27]
	v_mfma_f32_16x16x32_bf16 v[32:35], v[232:235], v[218:221], v[32:35]
	s_setprio 0
	s_movk_i32 s9, 0x100
	v_cmp_gt_u32_e32 vcc, s9, v132
	s_barrier
	s_and_saveexec_b64 s[28:29], vcc
	s_cbranch_execz .LBB0_212
	s_barrier
	s_branch .LBB0_212

.LBB0_314:
	ds_read_b128 v[172:175], v170
	ds_read_b128 v[176:179], v170 offset:1024
	ds_read_b128 v[180:183], v170 offset:2048
	ds_read_b128 v[184:187], v170 offset:3072
	s_add_u32 s8, s37, vcc_lo
	s_addc_u32 s9, s38, vcc_hi
	ds_read_b128 v[188:191], v166
	ds_read_b128 v[202:205], v165
	ds_read_b128 v[210:213], v163
	ds_read_b128 v[218:221], v162
	ds_read_b128 v[192:195], v166 offset:1024
	ds_read_b128 v[206:209], v165 offset:1024
	ds_read_b128 v[214:217], v163 offset:1024
	ds_read_b128 v[236:239], v162 offset:1024
	s_add_i32 s40, s34, 0xc000
	s_mov_b32 m0, s40
	s_add_i32 s41, s34, 0xe000
	s_add_u32 s98, s8, s94
	s_addc_u32 s99, s9, s95
	global_load_lds_dwordx4 v160, s[98:99]
	s_mov_b32 m0, s41
	s_nop 0
	global_load_lds_dwordx4 v161, s[98:99]
	s_waitcnt lgkmcnt(8)
	s_barrier
	s_waitcnt lgkmcnt(7)
	v_mfma_f32_16x16x32_bf16 v[44:47], v[172:175], v[188:191], v[44:47]
	v_mfma_f32_16x16x32_bf16 v[40:43], v[180:183], v[188:191], v[40:43]
	s_waitcnt lgkmcnt(6)
	v_mfma_f32_16x16x32_bf16 v[60:63], v[172:175], v[202:205], v[60:63]
	v_mfma_f32_16x16x32_bf16 v[56:59], v[180:183], v[202:205], v[56:59]
	s_waitcnt lgkmcnt(5)
	v_mfma_f32_16x16x32_bf16 v[76:79], v[172:175], v[210:213], v[76:79]
	v_mfma_f32_16x16x32_bf16 v[72:75], v[180:183], v[210:213], v[72:75]
	s_waitcnt lgkmcnt(4)
	v_mfma_f32_16x16x32_bf16 v[92:95], v[172:175], v[218:221], v[92:95]
	v_mfma_f32_16x16x32_bf16 v[88:91], v[180:183], v[218:221], v[88:91]
	s_waitcnt lgkmcnt(3)
	v_mfma_f32_16x16x32_bf16 v[44:47], v[176:179], v[192:195], v[44:47]
	v_mfma_f32_16x16x32_bf16 v[40:43], v[184:187], v[192:195], v[40:43]
	s_waitcnt lgkmcnt(2)
	v_mfma_f32_16x16x32_bf16 v[60:63], v[176:179], v[206:209], v[60:63]
	v_mfma_f32_16x16x32_bf16 v[56:59], v[184:187], v[206:209], v[56:59]
	s_waitcnt lgkmcnt(1)
	v_mfma_f32_16x16x32_bf16 v[76:79], v[176:179], v[214:217], v[76:79]
	v_mfma_f32_16x16x32_bf16 v[72:75], v[184:187], v[214:217], v[72:75]
	s_waitcnt lgkmcnt(0)
	v_mfma_f32_16x16x32_bf16 v[92:95], v[176:179], v[236:239], v[92:95]
	v_mfma_f32_16x16x32_bf16 v[88:91], v[184:187], v[236:239], v[88:91]
	s_barrier
	s_add_i32 s39, s39, 2
	s_add_u32 s28, s6, vcc_lo
	s_addc_u32 s29, s7, vcc_hi
	ds_read_b128 v[240:243], v169
	ds_read_b128 v[244:247], v169 offset:1024
	ds_read_b128 v[248:251], v169 offset:2048
	ds_read_b128 v[228:231], v169 offset:3072
	s_mov_b32 m0, s59
	s_add_u32 s98, s28, s0
	s_addc_u32 s99, s29, s1
	global_load_lds_dwordx4 v160, s[98:99]
	s_mov_b32 m0, s61
	s_nop 0
	global_load_lds_dwordx4 v161, s[98:99]
	s_barrier
	s_waitcnt lgkmcnt(3)
	v_mfma_f32_16x16x32_bf16 v[32:35], v[240:243], v[188:191], v[32:35]
	s_waitcnt lgkmcnt(1)
	v_mfma_f32_16x16x32_bf16 v[36:39], v[248:251], v[188:191], v[36:39]
	v_mfma_f32_16x16x32_bf16 v[48:51], v[240:243], v[202:205], v[48:51]
	v_mfma_f32_16x16x32_bf16 v[52:55], v[248:251], v[202:205], v[52:55]
	v_mfma_f32_16x16x32_bf16 v[64:67], v[240:243], v[210:213], v[64:67]
	v_mfma_f32_16x16x32_bf16 v[68:71], v[248:251], v[210:213], v[68:71]
	v_mfma_f32_16x16x32_bf16 v[80:83], v[240:243], v[218:221], v[80:83]
	v_mfma_f32_16x16x32_bf16 v[84:87], v[248:251], v[218:221], v[84:87]
	v_mfma_f32_16x16x32_bf16 v[32:35], v[244:247], v[192:195], v[32:35]
	s_waitcnt lgkmcnt(0)
	v_mfma_f32_16x16x32_bf16 v[36:39], v[228:231], v[192:195], v[36:39]
	v_mfma_f32_16x16x32_bf16 v[48:51], v[244:247], v[206:209], v[48:51]
	v_mfma_f32_16x16x32_bf16 v[52:55], v[228:231], v[206:209], v[52:55]
	v_mfma_f32_16x16x32_bf16 v[64:67], v[244:247], v[214:217], v[64:67]
	v_mfma_f32_16x16x32_bf16 v[68:71], v[228:231], v[214:217], v[68:71]
	v_mfma_f32_16x16x32_bf16 v[80:83], v[244:247], v[236:239], v[80:83]
	v_mfma_f32_16x16x32_bf16 v[84:87], v[228:231], v[236:239], v[84:87]
	s_add_u32 s92, s90, vcc_lo
	s_addc_u32 s93, s91, vcc_hi
	s_barrier
	ds_read_b128 v[188:191], v166 offset:16384
	ds_read_b128 v[202:205], v165 offset:16384
	ds_read_b128 v[210:213], v163 offset:16384
	ds_read_b128 v[218:221], v162 offset:16384
	ds_read_b128 v[192:195], v166 offset:17408
	ds_read_b128 v[206:209], v165 offset:17408
	ds_read_b128 v[214:217], v163 offset:17408
	ds_read_b128 v[236:239], v162 offset:17408
	s_mov_b32 m0, s34
	s_add_u32 s98, s92, s0
	s_addc_u32 s99, s93, s1
	global_load_lds_dwordx4 v160, s[98:99]
	s_mov_b32 m0, s79
	s_nop 0
	global_load_lds_dwordx4 v161, s[98:99]
	s_barrier
	s_waitcnt lgkmcnt(7)
	v_mfma_f32_16x16x32_bf16 v[108:111], v[172:175], v[188:191], v[108:111]
	v_mfma_f32_16x16x32_bf16 v[104:107], v[180:183], v[188:191], v[104:107]
	s_waitcnt lgkmcnt(6)
	v_mfma_f32_16x16x32_bf16 v[124:127], v[172:175], v[202:205], v[124:127]
	v_mfma_f32_16x16x32_bf16 v[120:123], v[180:183], v[202:205], v[120:123]
	s_waitcnt lgkmcnt(5)
	v_mfma_f32_16x16x32_bf16 v[140:143], v[172:175], v[210:213], v[140:143]
	v_mfma_f32_16x16x32_bf16 v[136:139], v[180:183], v[210:213], v[136:139]
	s_waitcnt lgkmcnt(4)
	v_mfma_f32_16x16x32_bf16 v[156:159], v[172:175], v[218:221], v[156:159]
	v_mfma_f32_16x16x32_bf16 v[152:155], v[180:183], v[218:221], v[152:155]
	s_waitcnt lgkmcnt(3)
	v_mfma_f32_16x16x32_bf16 v[108:111], v[176:179], v[192:195], v[108:111]
	v_mfma_f32_16x16x32_bf16 v[104:107], v[184:187], v[192:195], v[104:107]
	s_waitcnt lgkmcnt(2)
	v_mfma_f32_16x16x32_bf16 v[124:127], v[176:179], v[206:209], v[124:127]
	v_mfma_f32_16x16x32_bf16 v[120:123], v[184:187], v[206:209], v[120:123]
	s_waitcnt lgkmcnt(1)
	v_mfma_f32_16x16x32_bf16 v[140:143], v[176:179], v[214:217], v[140:143]
	v_mfma_f32_16x16x32_bf16 v[136:139], v[184:187], v[214:217], v[136:139]
	s_waitcnt lgkmcnt(0)
	v_mfma_f32_16x16x32_bf16 v[156:159], v[176:179], v[236:239], v[156:159]
	v_mfma_f32_16x16x32_bf16 v[152:155], v[184:187], v[236:239], v[152:155]
	s_barrier
	s_add_u32 s96, s82, vcc_lo
	s_addc_u32 s97, s36, vcc_hi
	s_mov_b32 m0, s52
	s_add_u32 s98, s96, s0
	s_addc_u32 s99, s97, s1
	global_load_lds_dwordx4 v160, s[98:99]
	s_mov_b32 m0, s53
	s_nop 0
	global_load_lds_dwordx4 v161, s[98:99]
	s_waitcnt vmcnt(6)
	s_barrier
	v_mfma_f32_16x16x32_bf16 v[96:99], v[240:243], v[188:191], v[96:99]
	v_mfma_f32_16x16x32_bf16 v[100:103], v[248:251], v[188:191], v[100:103]
	v_mfma_f32_16x16x32_bf16 v[112:115], v[240:243], v[202:205], v[112:115]
	v_mfma_f32_16x16x32_bf16 v[116:119], v[248:251], v[202:205], v[116:119]
	v_mfma_f32_16x16x32_bf16 v[128:131], v[240:243], v[210:213], v[128:131]
	v_mfma_f32_16x16x32_bf16 v[132:135], v[248:251], v[210:213], v[132:135]
	v_mfma_f32_16x16x32_bf16 v[144:147], v[240:243], v[218:221], v[144:147]
	v_mfma_f32_16x16x32_bf16 v[148:151], v[248:251], v[218:221], v[148:151]
	v_mfma_f32_16x16x32_bf16 v[96:99], v[244:247], v[192:195], v[96:99]
	v_mfma_f32_16x16x32_bf16 v[100:103], v[228:231], v[192:195], v[100:103]
	v_mfma_f32_16x16x32_bf16 v[112:115], v[244:247], v[206:209], v[112:115]
	v_mfma_f32_16x16x32_bf16 v[116:119], v[228:231], v[206:209], v[116:119]
	v_mfma_f32_16x16x32_bf16 v[128:131], v[244:247], v[214:217], v[128:131]
	v_mfma_f32_16x16x32_bf16 v[132:135], v[228:231], v[214:217], v[132:135]
	v_mfma_f32_16x16x32_bf16 v[144:147], v[244:247], v[236:239], v[144:147]
	v_mfma_f32_16x16x32_bf16 v[148:151], v[228:231], v[236:239], v[148:151]
	s_barrier
	ds_read_b128 v[172:175], v168
	ds_read_b128 v[176:179], v168 offset:1024
	ds_read_b128 v[180:183], v168 offset:2048
	ds_read_b128 v[184:187], v168 offset:3072
	ds_read_b128 v[188:191], v166 offset:32768
	ds_read_b128 v[202:205], v165 offset:32768
	ds_read_b128 v[210:213], v163 offset:32768
	ds_read_b128 v[218:221], v162 offset:32768
	ds_read_b128 v[192:195], v166 offset:33792
	ds_read_b128 v[206:209], v165 offset:33792
	ds_read_b128 v[214:217], v163 offset:33792
	ds_read_b128 v[228:231], v162 offset:33792
	s_mov_b32 m0, s68
	s_add_u32 s98, s8, s0
	s_addc_u32 s99, s9, s1
	global_load_lds_dwordx4 v160, s[98:99]
	s_mov_b32 m0, s69
	s_nop 0
	global_load_lds_dwordx4 v161, s[98:99]
	s_waitcnt lgkmcnt(8)
	s_barrier
	s_waitcnt lgkmcnt(7)
	v_mfma_f32_16x16x32_bf16 v[44:47], v[172:175], v[188:191], v[44:47]
	v_mfma_f32_16x16x32_bf16 v[40:43], v[180:183], v[188:191], v[40:43]
	s_waitcnt lgkmcnt(6)
	v_mfma_f32_16x16x32_bf16 v[60:63], v[172:175], v[202:205], v[60:63]
	v_mfma_f32_16x16x32_bf16 v[56:59], v[180:183], v[202:205], v[56:59]
	s_waitcnt lgkmcnt(5)
	v_mfma_f32_16x16x32_bf16 v[76:79], v[172:175], v[210:213], v[76:79]
	v_mfma_f32_16x16x32_bf16 v[72:75], v[180:183], v[210:213], v[72:75]
	s_waitcnt lgkmcnt(4)
	v_mfma_f32_16x16x32_bf16 v[92:95], v[172:175], v[218:221], v[92:95]
	v_mfma_f32_16x16x32_bf16 v[88:91], v[180:183], v[218:221], v[88:91]
	s_waitcnt lgkmcnt(3)
	v_mfma_f32_16x16x32_bf16 v[44:47], v[176:179], v[192:195], v[44:47]
	v_mfma_f32_16x16x32_bf16 v[40:43], v[184:187], v[192:195], v[40:43]
	s_waitcnt lgkmcnt(2)
	v_mfma_f32_16x16x32_bf16 v[60:63], v[176:179], v[206:209], v[60:63]
	v_mfma_f32_16x16x32_bf16 v[56:59], v[184:187], v[206:209], v[56:59]
	s_waitcnt lgkmcnt(1)
	v_mfma_f32_16x16x32_bf16 v[76:79], v[176:179], v[214:217], v[76:79]
	v_mfma_f32_16x16x32_bf16 v[72:75], v[184:187], v[214:217], v[72:75]
	s_waitcnt lgkmcnt(0)
	v_mfma_f32_16x16x32_bf16 v[92:95], v[176:179], v[228:231], v[92:95]
	v_mfma_f32_16x16x32_bf16 v[88:91], v[184:187], v[228:231], v[88:91]
	s_barrier
	ds_read_b128 v[236:239], v167
	ds_read_b128 v[240:243], v167 offset:1024
	ds_read_b128 v[244:247], v167 offset:2048
	ds_read_b128 v[248:251], v167 offset:3072
	s_mov_b32 m0, s70
	s_add_u32 s98, s28, s30
	s_addc_u32 s99, s29, s31
	global_load_lds_dwordx4 v160, s[98:99]
	s_mov_b32 m0, s71
	s_nop 0
	global_load_lds_dwordx4 v161, s[98:99]
	s_barrier
	s_waitcnt lgkmcnt(3)
	v_mfma_f32_16x16x32_bf16 v[32:35], v[236:239], v[188:191], v[32:35]
	s_waitcnt lgkmcnt(1)
	v_mfma_f32_16x16x32_bf16 v[36:39], v[244:247], v[188:191], v[36:39]
	v_mfma_f32_16x16x32_bf16 v[48:51], v[236:239], v[202:205], v[48:51]
	v_mfma_f32_16x16x32_bf16 v[52:55], v[244:247], v[202:205], v[52:55]
	v_mfma_f32_16x16x32_bf16 v[64:67], v[236:239], v[210:213], v[64:67]
	v_mfma_f32_16x16x32_bf16 v[68:71], v[244:247], v[210:213], v[68:71]
	v_mfma_f32_16x16x32_bf16 v[80:83], v[236:239], v[218:221], v[80:83]
	v_mfma_f32_16x16x32_bf16 v[84:87], v[244:247], v[218:221], v[84:87]
	v_mfma_f32_16x16x32_bf16 v[32:35], v[240:243], v[192:195], v[32:35]
	s_waitcnt lgkmcnt(0)
	v_mfma_f32_16x16x32_bf16 v[36:39], v[248:251], v[192:195], v[36:39]
	v_mfma_f32_16x16x32_bf16 v[48:51], v[240:243], v[206:209], v[48:51]
	v_mfma_f32_16x16x32_bf16 v[52:55], v[248:251], v[206:209], v[52:55]
	v_mfma_f32_16x16x32_bf16 v[64:67], v[240:243], v[214:217], v[64:67]
	v_mfma_f32_16x16x32_bf16 v[68:71], v[248:251], v[214:217], v[68:71]
	v_mfma_f32_16x16x32_bf16 v[80:83], v[240:243], v[228:231], v[80:83]
	v_mfma_f32_16x16x32_bf16 v[84:87], v[248:251], v[228:231], v[84:87]
	v_mov_b32_e32 v222, v161
	s_barrier
	ds_read_b128 v[188:191], v166 offset:49152
	ds_read_b128 v[202:205], v165 offset:49152
	ds_read_b128 v[210:213], v163 offset:49152
	ds_read_b128 v[218:221], v162 offset:49152
	ds_read_b128 v[192:195], v166 offset:50176
	ds_read_b128 v[206:209], v165 offset:50176
	ds_read_b128 v[214:217], v163 offset:50176
	ds_read_b128 v[228:231], v162 offset:50176
	v_mov_b32_e32 v223, v197
	s_mov_b32 m0, s72
	s_add_u32 s98, s92, s30
	s_addc_u32 s99, s93, s31
	global_load_lds_dwordx4 v160, s[98:99]
	s_mov_b32 m0, s73
	s_nop 0
	global_load_lds_dwordx4 v161, s[98:99]
	s_barrier
	s_waitcnt lgkmcnt(7)
	v_mfma_f32_16x16x32_bf16 v[108:111], v[172:175], v[188:191], v[108:111]
	v_mfma_f32_16x16x32_bf16 v[104:107], v[180:183], v[188:191], v[104:107]
	s_waitcnt lgkmcnt(6)
	v_mfma_f32_16x16x32_bf16 v[124:127], v[172:175], v[202:205], v[124:127]
	v_mfma_f32_16x16x32_bf16 v[120:123], v[180:183], v[202:205], v[120:123]
	s_waitcnt lgkmcnt(5)
	v_mfma_f32_16x16x32_bf16 v[140:143], v[172:175], v[210:213], v[140:143]
	v_mfma_f32_16x16x32_bf16 v[136:139], v[180:183], v[210:213], v[136:139]
	s_waitcnt lgkmcnt(4)
	v_mfma_f32_16x16x32_bf16 v[156:159], v[172:175], v[218:221], v[156:159]
	v_mfma_f32_16x16x32_bf16 v[152:155], v[180:183], v[218:221], v[152:155]
	s_waitcnt lgkmcnt(3)
	v_mfma_f32_16x16x32_bf16 v[108:111], v[176:179], v[192:195], v[108:111]
	v_mfma_f32_16x16x32_bf16 v[104:107], v[184:187], v[192:195], v[104:107]
	s_waitcnt lgkmcnt(2)
	v_mfma_f32_16x16x32_bf16 v[124:127], v[176:179], v[206:209], v[124:127]
	v_mfma_f32_16x16x32_bf16 v[120:123], v[184:187], v[206:209], v[120:123]
	s_waitcnt lgkmcnt(1)
	v_mfma_f32_16x16x32_bf16 v[140:143], v[176:179], v[214:217], v[140:143]
	v_mfma_f32_16x16x32_bf16 v[136:139], v[184:187], v[214:217], v[136:139]
	s_waitcnt lgkmcnt(0)
	v_mfma_f32_16x16x32_bf16 v[156:159], v[176:179], v[228:231], v[156:159]
	v_mfma_f32_16x16x32_bf16 v[152:155], v[184:187], v[228:231], v[152:155]
	s_barrier
	v_mov_b32_e32 v196, v160
	s_mov_b32 m0, s75
	s_add_u32 s98, s96, s30
	s_addc_u32 s99, s97, s31
	global_load_lds_dwordx4 v160, s[98:99]
	s_mov_b32 m0, s89
	s_nop 0
	global_load_lds_dwordx4 v161, s[98:99]
	s_waitcnt vmcnt(6)
	s_barrier
	v_mfma_f32_16x16x32_bf16 v[96:99], v[236:239], v[188:191], v[96:99]
	v_mfma_f32_16x16x32_bf16 v[100:103], v[244:247], v[188:191], v[100:103]
	v_mfma_f32_16x16x32_bf16 v[112:115], v[236:239], v[202:205], v[112:115]
	v_mfma_f32_16x16x32_bf16 v[116:119], v[244:247], v[202:205], v[116:119]
	v_mfma_f32_16x16x32_bf16 v[128:131], v[236:239], v[210:213], v[128:131]
	v_mfma_f32_16x16x32_bf16 v[132:135], v[244:247], v[210:213], v[132:135]
	v_mfma_f32_16x16x32_bf16 v[144:147], v[236:239], v[218:221], v[144:147]
	v_mfma_f32_16x16x32_bf16 v[148:151], v[244:247], v[218:221], v[148:151]
	v_mfma_f32_16x16x32_bf16 v[96:99], v[240:243], v[192:195], v[96:99]
	v_mfma_f32_16x16x32_bf16 v[100:103], v[248:251], v[192:195], v[100:103]
	v_mfma_f32_16x16x32_bf16 v[112:115], v[240:243], v[206:209], v[112:115]
	v_mfma_f32_16x16x32_bf16 v[116:119], v[248:251], v[206:209], v[116:119]
	v_mfma_f32_16x16x32_bf16 v[128:131], v[240:243], v[214:217], v[128:131]
	v_mfma_f32_16x16x32_bf16 v[132:135], v[248:251], v[214:217], v[132:135]
	v_mfma_f32_16x16x32_bf16 v[144:147], v[240:243], v[228:231], v[144:147]
	v_mfma_f32_16x16x32_bf16 v[148:151], v[248:251], v[228:231], v[148:151]
	s_add_u32 vcc_lo, vcc_lo, 0x100
	s_addc_u32 vcc_hi, vcc_hi, 0
	s_cmp_lt_u32 s39, s74
	s_barrier
	s_cbranch_scc1 .LBB0_314
	s_add_i32 s34, s33, -1
	s_lshl_b64 s[6:7], s[34:35], 7
	s_add_u32 s6, s84, s6
	s_addc_u32 s7, s85, s7
	s_mov_b32 m0, s40
	ds_read_b128 v[172:175], v170
	ds_read_b128 v[176:179], v170 offset:1024
	ds_read_b128 v[180:183], v170 offset:2048
	ds_read_b128 v[184:187], v170 offset:3072
	ds_read_b128 v[188:191], v166
	ds_read_b128 v[192:195], v166 offset:1024
	ds_read_b128 v[202:205], v165
	ds_read_b128 v[206:209], v165 offset:1024
	ds_read_b128 v[210:213], v163
	ds_read_b128 v[214:217], v163 offset:1024
	ds_read_b128 v[218:221], v162
	ds_read_b128 v[228:231], v162 offset:1024
	s_nop 0
	global_load_lds_dwordx4 v160, s[6:7]
	s_mov_b32 m0, s41
	s_nop 0
	global_load_lds_dwordx4 v161, s[6:7]
	s_barrier
	s_waitcnt lgkmcnt(0)
	s_setprio 1
	s_waitcnt lgkmcnt(0)
	v_mfma_f32_16x16x32_bf16 v[40:43], v[180:183], v[188:191], v[40:43]
	v_mfma_f32_16x16x32_bf16 v[56:59], v[180:183], v[202:205], v[56:59]
	v_mfma_f32_16x16x32_bf16 v[72:75], v[180:183], v[210:213], v[72:75]
	v_mfma_f32_16x16x32_bf16 v[92:95], v[172:175], v[218:221], v[92:95]
	v_mfma_f32_16x16x32_bf16 v[88:91], v[180:183], v[218:221], v[88:91]
	v_mfma_f32_16x16x32_bf16 v[44:47], v[172:175], v[188:191], v[44:47]
	v_mfma_f32_16x16x32_bf16 v[40:43], v[184:187], v[192:195], v[40:43]
	v_mfma_f32_16x16x32_bf16 v[60:63], v[172:175], v[202:205], v[60:63]
	v_mfma_f32_16x16x32_bf16 v[56:59], v[184:187], v[206:209], v[56:59]
	v_mfma_f32_16x16x32_bf16 v[76:79], v[172:175], v[210:213], v[76:79]
	v_mfma_f32_16x16x32_bf16 v[72:75], v[184:187], v[214:217], v[72:75]
	v_mfma_f32_16x16x32_bf16 v[92:95], v[176:179], v[228:231], v[92:95]
	v_mfma_f32_16x16x32_bf16 v[88:91], v[184:187], v[228:231], v[88:91]
	v_mfma_f32_16x16x32_bf16 v[44:47], v[176:179], v[192:195], v[44:47]
	v_mfma_f32_16x16x32_bf16 v[60:63], v[176:179], v[206:209], v[60:63]
	v_mfma_f32_16x16x32_bf16 v[76:79], v[176:179], v[214:217], v[76:79]
	s_setprio 0
	s_barrier
	ds_read_b128 v[236:239], v169
	ds_read_b128 v[240:243], v169 offset:1024
	ds_read_b128 v[244:247], v169 offset:2048
	ds_read_b128 v[248:251], v169 offset:3072
	s_barrier
	s_waitcnt lgkmcnt(0)
	s_setprio 1
	s_waitcnt lgkmcnt(0)
	v_mfma_f32_16x16x32_bf16 v[36:39], v[244:247], v[188:191], v[36:39]
	v_mfma_f32_16x16x32_bf16 v[32:35], v[236:239], v[188:191], v[32:35]
	v_mfma_f32_16x16x32_bf16 v[188:191], v[248:251], v[192:195], v[36:39]
	v_mfma_f32_16x16x32_bf16 v[36:39], v[236:239], v[202:205], v[48:51]
	v_mfma_f32_16x16x32_bf16 v[48:51], v[240:243], v[206:209], v[36:39]
	v_mfma_f32_16x16x32_bf16 v[36:39], v[244:247], v[202:205], v[52:55]
	v_mfma_f32_16x16x32_bf16 v[32:35], v[240:243], v[192:195], v[32:35]
	v_mfma_f32_16x16x32_bf16 v[192:195], v[248:251], v[206:209], v[36:39]
	v_mfma_f32_16x16x32_bf16 v[36:39], v[236:239], v[210:213], v[64:67]
	v_mfma_f32_16x16x32_bf16 v[64:67], v[240:243], v[214:217], v[36:39]
	v_mfma_f32_16x16x32_bf16 v[36:39], v[244:247], v[210:213], v[68:71]
	v_mfma_f32_16x16x32_bf16 v[202:205], v[248:251], v[214:217], v[36:39]
	v_mfma_f32_16x16x32_bf16 v[36:39], v[236:239], v[218:221], v[80:83]
	v_mfma_f32_16x16x32_bf16 v[80:83], v[240:243], v[228:231], v[36:39]
	v_mfma_f32_16x16x32_bf16 v[36:39], v[244:247], v[218:221], v[84:87]
	v_mfma_f32_16x16x32_bf16 v[206:209], v[248:251], v[228:231], v[36:39]
	s_setprio 0
	s_barrier
	s_nop 4
	ds_read_b128 v[36:39], v166 offset:16384
	ds_read_b128 v[52:55], v166 offset:17408
	ds_read_b128 v[68:71], v165 offset:16384
	ds_read_b128 v[84:87], v165 offset:17408
	ds_read_b128 v[210:213], v163 offset:16384
	ds_read_b128 v[214:217], v163 offset:17408
	ds_read_b128 v[218:221], v162 offset:16384
	ds_read_b128 v[228:231], v162 offset:17408
	s_waitcnt vmcnt(4)
	s_barrier
	s_waitcnt lgkmcnt(0)
	s_setprio 1
	s_waitcnt lgkmcnt(0)
	v_mfma_f32_16x16x32_bf16 v[108:111], v[172:175], v[36:39], v[108:111]
	v_mfma_f32_16x16x32_bf16 v[222:225], v[176:179], v[52:55], v[108:111]
	v_mfma_f32_16x16x32_bf16 v[108:111], v[172:175], v[68:71], v[124:127]
	v_mfma_f32_16x16x32_bf16 v[124:127], v[176:179], v[84:87], v[108:111]
	v_mfma_f32_16x16x32_bf16 v[108:111], v[180:183], v[68:71], v[120:123]
	v_mfma_f32_16x16x32_bf16 v[120:123], v[184:187], v[84:87], v[108:111]
	v_mfma_f32_16x16x32_bf16 v[108:111], v[172:175], v[210:213], v[140:143]
	v_mfma_f32_16x16x32_bf16 v[140:143], v[176:179], v[214:217], v[108:111]
	v_mfma_f32_16x16x32_bf16 v[108:111], v[180:183], v[210:213], v[136:139]
	v_mfma_f32_16x16x32_bf16 v[136:139], v[184:187], v[214:217], v[108:111]
	v_mfma_f32_16x16x32_bf16 v[108:111], v[172:175], v[218:221], v[156:159]
	v_mfma_f32_16x16x32_bf16 v[104:107], v[180:183], v[36:39], v[104:107]
	v_mfma_f32_16x16x32_bf16 v[156:159], v[176:179], v[228:231], v[108:111]
	v_mfma_f32_16x16x32_bf16 v[108:111], v[180:183], v[218:221], v[152:155]
	v_mfma_f32_16x16x32_bf16 v[104:107], v[184:187], v[52:55], v[104:107]
	v_mfma_f32_16x16x32_bf16 v[152:155], v[184:187], v[228:231], v[108:111]
	s_setprio 0
	s_setprio 1
	v_mfma_f32_16x16x32_bf16 v[96:99], v[236:239], v[36:39], v[96:99]
	v_mfma_f32_16x16x32_bf16 v[36:39], v[244:247], v[36:39], v[100:103]
	v_mfma_f32_16x16x32_bf16 v[172:175], v[248:251], v[52:55], v[36:39]
	v_mfma_f32_16x16x32_bf16 v[36:39], v[236:239], v[68:71], v[112:115]
	v_mfma_f32_16x16x32_bf16 v[112:115], v[240:243], v[84:87], v[36:39]
	v_mfma_f32_16x16x32_bf16 v[36:39], v[244:247], v[68:71], v[116:119]
	v_mfma_f32_16x16x32_bf16 v[180:183], v[248:251], v[84:87], v[36:39]
	v_mfma_f32_16x16x32_bf16 v[36:39], v[236:239], v[210:213], v[128:131]
	v_mfma_f32_16x16x32_bf16 v[128:131], v[240:243], v[214:217], v[36:39]
	v_mfma_f32_16x16x32_bf16 v[36:39], v[244:247], v[210:213], v[132:135]
	v_mfma_f32_16x16x32_bf16 v[184:187], v[248:251], v[214:217], v[36:39]
	v_mfma_f32_16x16x32_bf16 v[36:39], v[236:239], v[218:221], v[144:147]
	v_mfma_f32_16x16x32_bf16 v[96:99], v[240:243], v[52:55], v[96:99]
	v_mfma_f32_16x16x32_bf16 v[144:147], v[240:243], v[228:231], v[36:39]
	v_mfma_f32_16x16x32_bf16 v[36:39], v[244:247], v[218:221], v[148:151]
	v_mfma_f32_16x16x32_bf16 v[210:213], v[248:251], v[228:231], v[36:39]
	s_setprio 0
	s_barrier
	ds_read_b128 v[148:151], v168
	ds_read_b128 v[214:217], v168 offset:1024
	ds_read_b128 v[218:221], v168 offset:2048
	ds_read_b128 v[228:231], v168 offset:3072
	ds_read_b128 v[100:103], v166 offset:32768
	ds_read_b128 v[108:111], v166 offset:33792
	ds_read_b128 v[116:119], v165 offset:32768
	ds_read_b128 v[132:135], v165 offset:33792
	ds_read_b128 v[236:239], v163 offset:32768
	ds_read_b128 v[240:243], v163 offset:33792
	ds_read_b128 v[244:247], v162 offset:32768
	ds_read_b128 v[248:251], v162 offset:33792
	s_waitcnt vmcnt(2)
	s_barrier
	s_waitcnt lgkmcnt(0)
	s_setprio 1
	s_waitcnt lgkmcnt(0)
	v_mfma_f32_16x16x32_bf16 v[36:39], v[148:151], v[100:103], v[44:47]
	v_mfma_f32_16x16x32_bf16 v[44:47], v[148:151], v[116:119], v[60:63]
	v_mfma_f32_16x16x32_bf16 v[52:55], v[214:217], v[132:135], v[44:47]
	v_mfma_f32_16x16x32_bf16 v[44:47], v[218:221], v[116:119], v[56:59]
	v_mfma_f32_16x16x32_bf16 v[56:59], v[228:231], v[132:135], v[44:47]
	v_mfma_f32_16x16x32_bf16 v[44:47], v[148:151], v[236:239], v[76:79]
	v_mfma_f32_16x16x32_bf16 v[68:71], v[214:217], v[240:243], v[44:47]
	v_mfma_f32_16x16x32_bf16 v[44:47], v[218:221], v[236:239], v[72:75]
	v_mfma_f32_16x16x32_bf16 v[72:75], v[228:231], v[240:243], v[44:47]
	v_mfma_f32_16x16x32_bf16 v[44:47], v[148:151], v[244:247], v[92:95]
	v_mfma_f32_16x16x32_bf16 v[40:43], v[218:221], v[100:103], v[40:43]
	v_mfma_f32_16x16x32_bf16 v[84:87], v[214:217], v[248:251], v[44:47]
	v_mfma_f32_16x16x32_bf16 v[44:47], v[218:221], v[244:247], v[88:91]
	v_mfma_f32_16x16x32_bf16 v[36:39], v[214:217], v[108:111], v[36:39]
	v_mfma_f32_16x16x32_bf16 v[40:43], v[228:231], v[108:111], v[40:43]
	v_mfma_f32_16x16x32_bf16 v[88:91], v[228:231], v[248:251], v[44:47]
	s_setprio 0
	s_barrier
	s_nop 2
	ds_read_b128 v[44:47], v167
	ds_read_b128 v[60:63], v167 offset:1024
	ds_read_b128 v[76:79], v167 offset:2048
	ds_read_b128 v[232:235], v167 offset:3072
	s_waitcnt vmcnt(0)
	s_barrier
	s_waitcnt lgkmcnt(0)
	s_setprio 1
	s_waitcnt lgkmcnt(0)
	v_mfma_f32_16x16x32_bf16 v[92:95], v[76:79], v[100:103], v[188:191]
	v_mfma_f32_16x16x32_bf16 v[176:179], v[232:235], v[108:111], v[92:95]
	v_mfma_f32_16x16x32_bf16 v[92:95], v[76:79], v[116:119], v[192:195]
	v_mfma_f32_16x16x32_bf16 v[32:35], v[44:47], v[100:103], v[32:35]
	v_mfma_f32_16x16x32_bf16 v[48:51], v[44:47], v[116:119], v[48:51]
	v_mfma_f32_16x16x32_bf16 v[168:171], v[232:235], v[132:135], v[92:95]
	v_mfma_f32_16x16x32_bf16 v[64:67], v[44:47], v[236:239], v[64:67]
	v_mfma_f32_16x16x32_bf16 v[92:95], v[76:79], v[236:239], v[202:205]
	v_mfma_f32_16x16x32_bf16 v[80:83], v[44:47], v[244:247], v[80:83]
	v_mfma_f32_16x16x32_bf16 v[100:103], v[76:79], v[244:247], v[206:209]
	v_mfma_f32_16x16x32_bf16 v[32:35], v[60:63], v[108:111], v[32:35]
	v_mfma_f32_16x16x32_bf16 v[48:51], v[60:63], v[132:135], v[48:51]
	v_mfma_f32_16x16x32_bf16 v[64:67], v[60:63], v[240:243], v[64:67]
	v_mfma_f32_16x16x32_bf16 v[92:95], v[232:235], v[240:243], v[92:95]
	v_mfma_f32_16x16x32_bf16 v[80:83], v[60:63], v[248:251], v[80:83]
	v_mfma_f32_16x16x32_bf16 v[108:111], v[232:235], v[248:251], v[100:103]
	s_setprio 0
	s_barrier
	ds_read_b128 v[188:191], v166 offset:49152
	ds_read_b128 v[192:195], v166 offset:50176
	ds_read_b128 v[202:205], v165 offset:49152
	ds_read_b128 v[206:209], v165 offset:50176
	ds_read_b128 v[236:239], v163 offset:49152
	ds_read_b128 v[240:243], v163 offset:50176
	ds_read_b128 v[244:247], v162 offset:49152
	ds_read_b128 v[160:163], v162 offset:50176
	s_barrier
	s_waitcnt lgkmcnt(0)
	s_setprio 1
	s_waitcnt lgkmcnt(0)
	v_mfma_f32_16x16x32_bf16 v[116:119], v[148:151], v[202:205], v[124:127]
	v_mfma_f32_16x16x32_bf16 v[124:127], v[148:151], v[236:239], v[140:143]
	v_mfma_f32_16x16x32_bf16 v[132:135], v[214:217], v[240:243], v[124:127]
	v_mfma_f32_16x16x32_bf16 v[124:127], v[218:221], v[236:239], v[136:139]
	v_mfma_f32_16x16x32_bf16 v[136:139], v[228:231], v[240:243], v[124:127]
	v_mfma_f32_16x16x32_bf16 v[124:127], v[148:151], v[244:247], v[156:159]
	v_mfma_f32_16x16x32_bf16 v[100:103], v[148:151], v[188:191], v[222:225]
	v_mfma_f32_16x16x32_bf16 v[104:107], v[218:221], v[188:191], v[104:107]
	v_mfma_f32_16x16x32_bf16 v[120:123], v[218:221], v[202:205], v[120:123]
	v_mfma_f32_16x16x32_bf16 v[148:151], v[214:217], v[160:163], v[124:127]
	v_mfma_f32_16x16x32_bf16 v[124:127], v[218:221], v[244:247], v[152:155]
	v_mfma_f32_16x16x32_bf16 v[100:103], v[214:217], v[192:195], v[100:103]
	v_mfma_f32_16x16x32_bf16 v[104:107], v[228:231], v[192:195], v[104:107]
	v_mfma_f32_16x16x32_bf16 v[116:119], v[214:217], v[206:209], v[116:119]
	v_mfma_f32_16x16x32_bf16 v[120:123], v[228:231], v[206:209], v[120:123]
	v_mfma_f32_16x16x32_bf16 v[152:155], v[228:231], v[160:163], v[124:127]
	s_setprio 0
	s_setprio 1
	v_mfma_f32_16x16x32_bf16 v[96:99], v[44:47], v[188:191], v[96:99]
	v_mfma_f32_16x16x32_bf16 v[112:115], v[44:47], v[202:205], v[112:115]
	v_mfma_f32_16x16x32_bf16 v[128:131], v[44:47], v[236:239], v[128:131]
	v_mfma_f32_16x16x32_bf16 v[44:47], v[44:47], v[244:247], v[144:147]
	v_mfma_f32_16x16x32_bf16 v[124:127], v[76:79], v[188:191], v[172:175]
	v_mfma_f32_16x16x32_bf16 v[140:143], v[76:79], v[202:205], v[180:183]
	v_mfma_f32_16x16x32_bf16 v[156:159], v[76:79], v[236:239], v[184:187]
	v_mfma_f32_16x16x32_bf16 v[144:147], v[60:63], v[160:163], v[44:47]
	v_mfma_f32_16x16x32_bf16 v[44:47], v[76:79], v[244:247], v[210:213]
	v_mfma_f32_16x16x32_bf16 v[96:99], v[60:63], v[192:195], v[96:99]
	v_mfma_f32_16x16x32_bf16 v[124:127], v[232:235], v[192:195], v[124:127]
	v_mfma_f32_16x16x32_bf16 v[112:115], v[60:63], v[206:209], v[112:115]
	v_mfma_f32_16x16x32_bf16 v[140:143], v[232:235], v[206:209], v[140:143]
	v_mfma_f32_16x16x32_bf16 v[128:131], v[60:63], v[240:243], v[128:131]
	v_mfma_f32_16x16x32_bf16 v[156:159], v[232:235], v[240:243], v[156:159]
	v_mfma_f32_16x16x32_bf16 v[160:163], v[232:235], v[160:163], v[44:47]
	s_setprio 0
	s_movk_i32 s6, 0x100
	v_cmp_gt_u32_e32 vcc, s6, v164
	s_barrier
	s_and_saveexec_b64 s[6:7], vcc
	s_cbranch_execz .LBB0_317
	s_barrier

.LBB0_568:
	ds_read_b128 v[140:143], v129
	ds_read_b128 v[144:147], v129 offset:1024
	ds_read_b128 v[148:151], v129 offset:2048
	ds_read_b128 v[152:155], v129 offset:3072
	s_add_u32 s28, s8, s10
	s_addc_u32 s29, s9, s11
	ds_read_b128 v[156:159], v136
	ds_read_b128 v[164:167], v135
	ds_read_b128 v[172:175], v134
	ds_read_b128 v[180:183], v133
	ds_read_b128 v[160:163], v136 offset:1024
	ds_read_b128 v[168:171], v135 offset:1024
	ds_read_b128 v[176:179], v134 offset:1024
	ds_read_b128 v[184:187], v133 offset:1024
	s_add_i32 s39, s68, 0xc000
	s_mov_b32 m0, s39
	s_add_i32 s38, s68, 0xe000
	s_add_u32 s98, s28, s44
	s_addc_u32 s99, s29, s45
	global_load_lds_dwordx4 v128, s[98:99]
	s_mov_b32 m0, s38
	s_nop 0
	global_load_lds_dwordx4 v130, s[98:99]
	s_waitcnt lgkmcnt(8)
	s_barrier
	s_waitcnt lgkmcnt(7)
	v_mfma_f32_16x16x32_bf16 v[124:127], v[140:143], v[156:159], v[124:127]
	v_mfma_f32_16x16x32_bf16 v[120:123], v[148:151], v[156:159], v[120:123]
	s_waitcnt lgkmcnt(6)
	v_mfma_f32_16x16x32_bf16 v[116:119], v[140:143], v[164:167], v[116:119]
	v_mfma_f32_16x16x32_bf16 v[112:115], v[148:151], v[164:167], v[112:115]
	s_waitcnt lgkmcnt(5)
	v_mfma_f32_16x16x32_bf16 v[108:111], v[140:143], v[172:175], v[108:111]
	v_mfma_f32_16x16x32_bf16 v[104:107], v[148:151], v[172:175], v[104:107]
	s_waitcnt lgkmcnt(4)
	v_mfma_f32_16x16x32_bf16 v[100:103], v[140:143], v[180:183], v[100:103]
	v_mfma_f32_16x16x32_bf16 v[96:99], v[148:151], v[180:183], v[96:99]
	s_waitcnt lgkmcnt(3)
	v_mfma_f32_16x16x32_bf16 v[124:127], v[144:147], v[160:163], v[124:127]
	v_mfma_f32_16x16x32_bf16 v[120:123], v[152:155], v[160:163], v[120:123]
	s_waitcnt lgkmcnt(2)
	v_mfma_f32_16x16x32_bf16 v[116:119], v[144:147], v[168:171], v[116:119]
	v_mfma_f32_16x16x32_bf16 v[112:115], v[152:155], v[168:171], v[112:115]
	s_waitcnt lgkmcnt(1)
	v_mfma_f32_16x16x32_bf16 v[108:111], v[144:147], v[176:179], v[108:111]
	v_mfma_f32_16x16x32_bf16 v[104:107], v[152:155], v[176:179], v[104:107]
	s_waitcnt lgkmcnt(0)
	v_mfma_f32_16x16x32_bf16 v[100:103], v[144:147], v[184:187], v[100:103]
	v_mfma_f32_16x16x32_bf16 v[96:99], v[152:155], v[184:187], v[96:99]
	s_barrier
	s_add_u32 s56, s6, s10
	s_addc_u32 s57, s7, s11
	ds_read_b128 v[188:191], v139
	ds_read_b128 v[192:195], v139 offset:1024
	ds_read_b128 v[202:205], v139 offset:2048
	ds_read_b128 v[206:209], v139 offset:3072
	s_add_i32 m0, s68, 0x10000
	s_add_u32 s98, s56, s0
	s_addc_u32 s99, s57, s1
	global_load_lds_dwordx4 v128, s[98:99]
	s_add_i32 m0, s68, 0x12000
	s_nop 0
	global_load_lds_dwordx4 v130, s[98:99]
	s_barrier
	s_waitcnt lgkmcnt(3)
	v_mfma_f32_16x16x32_bf16 v[92:95], v[188:191], v[156:159], v[92:95]
	s_waitcnt lgkmcnt(1)
	v_mfma_f32_16x16x32_bf16 v[88:91], v[202:205], v[156:159], v[88:91]
	v_mfma_f32_16x16x32_bf16 v[84:87], v[188:191], v[164:167], v[84:87]
	v_mfma_f32_16x16x32_bf16 v[80:83], v[202:205], v[164:167], v[80:83]
	v_mfma_f32_16x16x32_bf16 v[76:79], v[188:191], v[172:175], v[76:79]
	v_mfma_f32_16x16x32_bf16 v[72:75], v[202:205], v[172:175], v[72:75]
	v_mfma_f32_16x16x32_bf16 v[68:71], v[188:191], v[180:183], v[68:71]
	v_mfma_f32_16x16x32_bf16 v[64:67], v[202:205], v[180:183], v[64:67]
	v_mfma_f32_16x16x32_bf16 v[92:95], v[192:195], v[160:163], v[92:95]
	s_waitcnt lgkmcnt(0)
	v_mfma_f32_16x16x32_bf16 v[88:91], v[206:209], v[160:163], v[88:91]
	v_mfma_f32_16x16x32_bf16 v[84:87], v[192:195], v[168:171], v[84:87]
	v_mfma_f32_16x16x32_bf16 v[80:83], v[206:209], v[168:171], v[80:83]
	v_mfma_f32_16x16x32_bf16 v[76:79], v[192:195], v[176:179], v[76:79]
	v_mfma_f32_16x16x32_bf16 v[72:75], v[206:209], v[176:179], v[72:75]
	v_mfma_f32_16x16x32_bf16 v[68:71], v[192:195], v[184:187], v[68:71]
	v_mfma_f32_16x16x32_bf16 v[64:67], v[206:209], v[184:187], v[64:67]
	s_barrier
	ds_read_b128 v[156:159], v136 offset:16384
	ds_read_b128 v[164:167], v135 offset:16384
	ds_read_b128 v[172:175], v134 offset:16384
	ds_read_b128 v[180:183], v133 offset:16384
	ds_read_b128 v[160:163], v136 offset:17408
	ds_read_b128 v[168:171], v135 offset:17408
	ds_read_b128 v[176:179], v134 offset:17408
	ds_read_b128 v[184:187], v133 offset:17408
	s_mov_b32 m0, s68
	s_add_u32 s98, s28, s0
	s_addc_u32 s99, s29, s1
	global_load_lds_dwordx4 v128, s[98:99]
	s_add_i32 m0, s68, 0x2000
	s_nop 0
	global_load_lds_dwordx4 v130, s[98:99]
	s_barrier
	s_waitcnt lgkmcnt(7)
	v_mfma_f32_16x16x32_bf16 v[60:63], v[140:143], v[156:159], v[60:63]
	v_mfma_f32_16x16x32_bf16 v[56:59], v[148:151], v[156:159], v[56:59]
	s_waitcnt lgkmcnt(6)
	v_mfma_f32_16x16x32_bf16 v[52:55], v[140:143], v[164:167], v[52:55]
	v_mfma_f32_16x16x32_bf16 v[48:51], v[148:151], v[164:167], v[48:51]
	s_waitcnt lgkmcnt(5)
	v_mfma_f32_16x16x32_bf16 v[44:47], v[140:143], v[172:175], v[44:47]
	v_mfma_f32_16x16x32_bf16 v[40:43], v[148:151], v[172:175], v[40:43]
	s_waitcnt lgkmcnt(4)
	v_mfma_f32_16x16x32_bf16 v[36:39], v[140:143], v[180:183], v[36:39]
	v_mfma_f32_16x16x32_bf16 v[32:35], v[148:151], v[180:183], v[32:35]
	s_waitcnt lgkmcnt(3)
	v_mfma_f32_16x16x32_bf16 v[60:63], v[144:147], v[160:163], v[60:63]
	v_mfma_f32_16x16x32_bf16 v[56:59], v[152:155], v[160:163], v[56:59]
	s_waitcnt lgkmcnt(2)
	v_mfma_f32_16x16x32_bf16 v[52:55], v[144:147], v[168:171], v[52:55]
	v_mfma_f32_16x16x32_bf16 v[48:51], v[152:155], v[168:171], v[48:51]
	s_waitcnt lgkmcnt(1)
	v_mfma_f32_16x16x32_bf16 v[44:47], v[144:147], v[176:179], v[44:47]
	v_mfma_f32_16x16x32_bf16 v[40:43], v[152:155], v[176:179], v[40:43]
	s_waitcnt lgkmcnt(0)
	v_mfma_f32_16x16x32_bf16 v[36:39], v[144:147], v[184:187], v[36:39]
	v_mfma_f32_16x16x32_bf16 v[32:35], v[152:155], v[184:187], v[32:35]
	s_barrier
	s_add_i32 m0, s68, 0x14000
	s_add_u32 s98, s56, s46
	s_addc_u32 s99, s57, s47
	global_load_lds_dwordx4 v128, s[98:99]
	s_add_i32 m0, s68, 0x16000
	s_nop 0
	global_load_lds_dwordx4 v130, s[98:99]
	s_waitcnt vmcnt(6)
	s_barrier
	v_mfma_f32_16x16x32_bf16 v[28:31], v[188:191], v[156:159], v[28:31]
	v_mfma_f32_16x16x32_bf16 v[24:27], v[202:205], v[156:159], v[24:27]
	v_mfma_f32_16x16x32_bf16 v[20:23], v[188:191], v[164:167], v[20:23]
	v_mfma_f32_16x16x32_bf16 v[16:19], v[202:205], v[164:167], v[16:19]
	v_mfma_f32_16x16x32_bf16 v[12:15], v[188:191], v[172:175], v[12:15]
	v_mfma_f32_16x16x32_bf16 v[8:11], v[202:205], v[172:175], v[8:11]
	v_mfma_f32_16x16x32_bf16 v[4:7], v[188:191], v[180:183], v[4:7]
	v_mfma_f32_16x16x32_bf16 v[0:3], v[202:205], v[180:183], v[0:3]
	v_mfma_f32_16x16x32_bf16 v[28:31], v[192:195], v[160:163], v[28:31]
	v_mfma_f32_16x16x32_bf16 v[24:27], v[206:209], v[160:163], v[24:27]
	v_mfma_f32_16x16x32_bf16 v[20:23], v[192:195], v[168:171], v[20:23]
	v_mfma_f32_16x16x32_bf16 v[16:19], v[206:209], v[168:171], v[16:19]
	v_mfma_f32_16x16x32_bf16 v[12:15], v[192:195], v[176:179], v[12:15]
	v_mfma_f32_16x16x32_bf16 v[8:11], v[206:209], v[176:179], v[8:11]
	v_mfma_f32_16x16x32_bf16 v[4:7], v[192:195], v[184:187], v[4:7]
	v_mfma_f32_16x16x32_bf16 v[0:3], v[206:209], v[184:187], v[0:3]
	s_barrier
	ds_read_b128 v[140:143], v138
	ds_read_b128 v[144:147], v138 offset:1024
	ds_read_b128 v[148:151], v138 offset:2048
	ds_read_b128 v[152:155], v138 offset:3072
	ds_read_b128 v[156:159], v136 offset:32768
	ds_read_b128 v[164:167], v135 offset:32768
	ds_read_b128 v[172:175], v134 offset:32768
	ds_read_b128 v[180:183], v133 offset:32768
	ds_read_b128 v[160:163], v136 offset:33792
	ds_read_b128 v[168:171], v135 offset:33792
	ds_read_b128 v[176:179], v134 offset:33792
	ds_read_b128 v[184:187], v133 offset:33792
	s_add_i32 m0, s68, 0x4000
	s_add_u32 s98, s28, s46
	s_addc_u32 s99, s29, s47
	global_load_lds_dwordx4 v128, s[98:99]
	s_add_i32 m0, s68, 0x6000
	s_nop 0
	global_load_lds_dwordx4 v130, s[98:99]
	s_waitcnt lgkmcnt(8)
	s_barrier
	s_waitcnt lgkmcnt(7)
	v_mfma_f32_16x16x32_bf16 v[124:127], v[140:143], v[156:159], v[124:127]
	v_mfma_f32_16x16x32_bf16 v[120:123], v[148:151], v[156:159], v[120:123]
	s_waitcnt lgkmcnt(6)
	v_mfma_f32_16x16x32_bf16 v[116:119], v[140:143], v[164:167], v[116:119]
	v_mfma_f32_16x16x32_bf16 v[112:115], v[148:151], v[164:167], v[112:115]
	s_waitcnt lgkmcnt(5)
	v_mfma_f32_16x16x32_bf16 v[108:111], v[140:143], v[172:175], v[108:111]
	v_mfma_f32_16x16x32_bf16 v[104:107], v[148:151], v[172:175], v[104:107]
	s_waitcnt lgkmcnt(4)
	v_mfma_f32_16x16x32_bf16 v[100:103], v[140:143], v[180:183], v[100:103]
	v_mfma_f32_16x16x32_bf16 v[96:99], v[148:151], v[180:183], v[96:99]
	s_waitcnt lgkmcnt(3)
	v_mfma_f32_16x16x32_bf16 v[124:127], v[144:147], v[160:163], v[124:127]
	v_mfma_f32_16x16x32_bf16 v[120:123], v[152:155], v[160:163], v[120:123]
	s_waitcnt lgkmcnt(2)
	v_mfma_f32_16x16x32_bf16 v[116:119], v[144:147], v[168:171], v[116:119]
	v_mfma_f32_16x16x32_bf16 v[112:115], v[152:155], v[168:171], v[112:115]
	s_waitcnt lgkmcnt(1)
	v_mfma_f32_16x16x32_bf16 v[108:111], v[144:147], v[176:179], v[108:111]
	v_mfma_f32_16x16x32_bf16 v[104:107], v[152:155], v[176:179], v[104:107]
	s_waitcnt lgkmcnt(0)
	v_mfma_f32_16x16x32_bf16 v[100:103], v[144:147], v[184:187], v[100:103]
	v_mfma_f32_16x16x32_bf16 v[96:99], v[152:155], v[184:187], v[96:99]
	s_barrier
	ds_read_b128 v[188:191], v137
	ds_read_b128 v[192:195], v137 offset:1024
	ds_read_b128 v[202:205], v137 offset:2048
	ds_read_b128 v[206:209], v137 offset:3072
	s_mov_b32 m0, s69
	s_add_u32 s98, s56, s30
	s_addc_u32 s99, s57, s31
	global_load_lds_dwordx4 v128, s[98:99]
	s_mov_b32 m0, s70
	s_nop 0
	global_load_lds_dwordx4 v130, s[98:99]
	s_barrier
	s_waitcnt lgkmcnt(3)
	v_mfma_f32_16x16x32_bf16 v[92:95], v[188:191], v[156:159], v[92:95]
	s_waitcnt lgkmcnt(1)
	v_mfma_f32_16x16x32_bf16 v[88:91], v[202:205], v[156:159], v[88:91]
	v_mfma_f32_16x16x32_bf16 v[84:87], v[188:191], v[164:167], v[84:87]
	v_mfma_f32_16x16x32_bf16 v[80:83], v[202:205], v[164:167], v[80:83]
	v_mfma_f32_16x16x32_bf16 v[76:79], v[188:191], v[172:175], v[76:79]
	v_mfma_f32_16x16x32_bf16 v[72:75], v[202:205], v[172:175], v[72:75]
	v_mfma_f32_16x16x32_bf16 v[68:71], v[188:191], v[180:183], v[68:71]
	v_mfma_f32_16x16x32_bf16 v[64:67], v[202:205], v[180:183], v[64:67]
	v_mfma_f32_16x16x32_bf16 v[92:95], v[192:195], v[160:163], v[92:95]
	s_waitcnt lgkmcnt(0)
	v_mfma_f32_16x16x32_bf16 v[88:91], v[206:209], v[160:163], v[88:91]
	v_mfma_f32_16x16x32_bf16 v[84:87], v[192:195], v[168:171], v[84:87]
	v_mfma_f32_16x16x32_bf16 v[80:83], v[206:209], v[168:171], v[80:83]
	v_mfma_f32_16x16x32_bf16 v[76:79], v[192:195], v[176:179], v[76:79]
	v_mfma_f32_16x16x32_bf16 v[72:75], v[206:209], v[176:179], v[72:75]
	v_mfma_f32_16x16x32_bf16 v[68:71], v[192:195], v[184:187], v[68:71]
	v_mfma_f32_16x16x32_bf16 v[64:67], v[206:209], v[184:187], v[64:67]
	v_mov_b32_e32 v210, v130
	s_barrier
	ds_read_b128 v[156:159], v136 offset:49152
	ds_read_b128 v[164:167], v135 offset:49152
	ds_read_b128 v[172:175], v134 offset:49152
	ds_read_b128 v[180:183], v133 offset:49152
	ds_read_b128 v[160:163], v136 offset:50176
	ds_read_b128 v[168:171], v135 offset:50176
	ds_read_b128 v[176:179], v134 offset:50176
	ds_read_b128 v[184:187], v133 offset:50176
	v_mov_b32_e32 v211, v197
	s_mov_b32 m0, s71
	s_add_u32 s98, s28, s30
	s_addc_u32 s99, s29, s31
	global_load_lds_dwordx4 v128, s[98:99]
	s_mov_b32 m0, s33
	s_nop 0
	global_load_lds_dwordx4 v130, s[98:99]
	s_barrier
	s_waitcnt lgkmcnt(7)
	v_mfma_f32_16x16x32_bf16 v[60:63], v[140:143], v[156:159], v[60:63]
	v_mfma_f32_16x16x32_bf16 v[56:59], v[148:151], v[156:159], v[56:59]
	s_waitcnt lgkmcnt(6)
	v_mfma_f32_16x16x32_bf16 v[52:55], v[140:143], v[164:167], v[52:55]
	v_mfma_f32_16x16x32_bf16 v[48:51], v[148:151], v[164:167], v[48:51]
	s_waitcnt lgkmcnt(5)
	v_mfma_f32_16x16x32_bf16 v[44:47], v[140:143], v[172:175], v[44:47]
	v_mfma_f32_16x16x32_bf16 v[40:43], v[148:151], v[172:175], v[40:43]
	s_waitcnt lgkmcnt(4)
	v_mfma_f32_16x16x32_bf16 v[36:39], v[140:143], v[180:183], v[36:39]
	v_mfma_f32_16x16x32_bf16 v[32:35], v[148:151], v[180:183], v[32:35]
	s_waitcnt lgkmcnt(3)
	v_mfma_f32_16x16x32_bf16 v[60:63], v[144:147], v[160:163], v[60:63]
	v_mfma_f32_16x16x32_bf16 v[56:59], v[152:155], v[160:163], v[56:59]
	s_waitcnt lgkmcnt(2)
	v_mfma_f32_16x16x32_bf16 v[52:55], v[144:147], v[168:171], v[52:55]
	v_mfma_f32_16x16x32_bf16 v[48:51], v[152:155], v[168:171], v[48:51]
	s_waitcnt lgkmcnt(1)
	v_mfma_f32_16x16x32_bf16 v[44:47], v[144:147], v[176:179], v[44:47]
	v_mfma_f32_16x16x32_bf16 v[40:43], v[152:155], v[176:179], v[40:43]
	s_waitcnt lgkmcnt(0)
	v_mfma_f32_16x16x32_bf16 v[36:39], v[144:147], v[184:187], v[36:39]
	v_mfma_f32_16x16x32_bf16 v[32:35], v[152:155], v[184:187], v[32:35]
	s_barrier
	v_mov_b32_e32 v196, v128
	s_mov_b32 m0, s72
	s_add_u32 s98, s56, s48
	s_addc_u32 s99, s57, s49
	global_load_lds_dwordx4 v128, s[98:99]
	s_mov_b32 m0, s36
	s_nop 0
	global_load_lds_dwordx4 v130, s[98:99]
	s_waitcnt vmcnt(6)
	s_barrier
	v_mfma_f32_16x16x32_bf16 v[28:31], v[188:191], v[156:159], v[28:31]
	v_mfma_f32_16x16x32_bf16 v[24:27], v[202:205], v[156:159], v[24:27]
	v_mfma_f32_16x16x32_bf16 v[20:23], v[188:191], v[164:167], v[20:23]
	v_mfma_f32_16x16x32_bf16 v[16:19], v[202:205], v[164:167], v[16:19]
	v_mfma_f32_16x16x32_bf16 v[12:15], v[188:191], v[172:175], v[12:15]
	v_mfma_f32_16x16x32_bf16 v[8:11], v[202:205], v[172:175], v[8:11]
	v_mfma_f32_16x16x32_bf16 v[4:7], v[188:191], v[180:183], v[4:7]
	v_mfma_f32_16x16x32_bf16 v[0:3], v[202:205], v[180:183], v[0:3]
	v_mfma_f32_16x16x32_bf16 v[28:31], v[192:195], v[160:163], v[28:31]
	v_mfma_f32_16x16x32_bf16 v[24:27], v[206:209], v[160:163], v[24:27]
	v_mfma_f32_16x16x32_bf16 v[20:23], v[192:195], v[168:171], v[20:23]
	v_mfma_f32_16x16x32_bf16 v[16:19], v[206:209], v[168:171], v[16:19]
	v_mfma_f32_16x16x32_bf16 v[12:15], v[192:195], v[176:179], v[12:15]
	v_mfma_f32_16x16x32_bf16 v[8:11], v[206:209], v[176:179], v[8:11]
	v_mfma_f32_16x16x32_bf16 v[4:7], v[192:195], v[184:187], v[4:7]
	v_mfma_f32_16x16x32_bf16 v[0:3], v[206:209], v[184:187], v[0:3]
	s_add_i32 s37, s37, 2
	s_add_u32 s10, s10, 0x100
	s_addc_u32 s11, s11, 0
	s_cmp_lt_u32 s37, 28
	s_barrier
	s_cbranch_scc1 .LBB0_568
	s_lshl_b64 s[4:5], s[4:5], 12
	s_add_u32 s4, s67, s4
	s_addc_u32 s5, s53, s5
	ds_read_b128 v[140:143], v129
	ds_read_b128 v[144:147], v129 offset:1024
	ds_read_b128 v[148:151], v129 offset:2048
	ds_read_b128 v[152:155], v129 offset:3072
	ds_read_b128 v[156:159], v136
	ds_read_b128 v[160:163], v136 offset:1024
	ds_read_b128 v[164:167], v135
	ds_read_b128 v[168:171], v135 offset:1024
	ds_read_b128 v[172:175], v134
	ds_read_b128 v[176:179], v134 offset:1024
	ds_read_b128 v[180:183], v133
	ds_read_b128 v[184:187], v133 offset:1024
	v_mov_b32_e32 v129, v197
	v_lshl_add_u64 v[128:129], s[4:5], 0, v[128:129]
	s_mov_b64 s[6:7], 0xf80
	s_mov_b32 m0, s39
	v_lshl_add_u64 v[128:129], v[128:129], 0, s[6:7]
	v_mov_b32_e32 v131, v197
	global_load_lds_dwordx4 v[128:129], off
	v_lshl_add_u64 v[128:129], s[4:5], 0, v[130:131]
	v_lshl_add_u64 v[128:129], v[128:129], 0, s[6:7]
	s_mov_b32 m0, s38
	s_nop 0
	global_load_lds_dwordx4 v[128:129], off
	s_barrier
	s_waitcnt lgkmcnt(0)
	s_setprio 1
	s_waitcnt lgkmcnt(0)
	v_mfma_f32_16x16x32_bf16 v[124:127], v[140:143], v[156:159], v[124:127]
	v_mfma_f32_16x16x32_bf16 v[120:123], v[148:151], v[156:159], v[120:123]
	v_mfma_f32_16x16x32_bf16 v[116:119], v[140:143], v[164:167], v[116:119]
	v_mfma_f32_16x16x32_bf16 v[112:115], v[148:151], v[164:167], v[112:115]
	v_mfma_f32_16x16x32_bf16 v[100:103], v[140:143], v[180:183], v[100:103]
	v_mfma_f32_16x16x32_bf16 v[96:99], v[148:151], v[180:183], v[96:99]
	v_mfma_f32_16x16x32_bf16 v[124:127], v[144:147], v[160:163], v[124:127]
	v_mfma_f32_16x16x32_bf16 v[120:123], v[152:155], v[160:163], v[120:123]
	v_mfma_f32_16x16x32_bf16 v[116:119], v[144:147], v[168:171], v[116:119]
	v_mfma_f32_16x16x32_bf16 v[112:115], v[152:155], v[168:171], v[112:115]
	v_mfma_f32_16x16x32_bf16 v[108:111], v[140:143], v[172:175], v[108:111]
	v_mfma_f32_16x16x32_bf16 v[104:107], v[148:151], v[172:175], v[104:107]
	v_mfma_f32_16x16x32_bf16 v[100:103], v[144:147], v[184:187], v[100:103]
	v_mfma_f32_16x16x32_bf16 v[96:99], v[152:155], v[184:187], v[96:99]
	v_mfma_f32_16x16x32_bf16 v[128:131], v[144:147], v[176:179], v[108:111]
	v_mfma_f32_16x16x32_bf16 v[188:191], v[152:155], v[176:179], v[104:107]
	s_setprio 0
	s_barrier
	s_nop 1
	ds_read_b128 v[104:107], v139
	ds_read_b128 v[108:111], v139 offset:1024
	ds_read_b128 v[192:195], v139 offset:2048
	ds_read_b128 v[202:205], v139 offset:3072
	s_barrier
	s_waitcnt lgkmcnt(0)
	s_setprio 1
	s_waitcnt lgkmcnt(0)
	v_mfma_f32_16x16x32_bf16 v[84:87], v[104:107], v[164:167], v[84:87]
	v_mfma_f32_16x16x32_bf16 v[80:83], v[192:195], v[164:167], v[80:83]
	v_mfma_f32_16x16x32_bf16 v[68:71], v[104:107], v[180:183], v[68:71]
	v_mfma_f32_16x16x32_bf16 v[64:67], v[192:195], v[180:183], v[64:67]
	v_mfma_f32_16x16x32_bf16 v[92:95], v[104:107], v[156:159], v[92:95]
	v_mfma_f32_16x16x32_bf16 v[88:91], v[192:195], v[156:159], v[88:91]
	v_mfma_f32_16x16x32_bf16 v[84:87], v[108:111], v[168:171], v[84:87]
	v_mfma_f32_16x16x32_bf16 v[80:83], v[202:205], v[168:171], v[80:83]
	v_mfma_f32_16x16x32_bf16 v[76:79], v[104:107], v[172:175], v[76:79]
	v_mfma_f32_16x16x32_bf16 v[72:75], v[192:195], v[172:175], v[72:75]
	v_mfma_f32_16x16x32_bf16 v[68:71], v[108:111], v[184:187], v[68:71]
	v_mfma_f32_16x16x32_bf16 v[64:67], v[202:205], v[184:187], v[64:67]
	v_mfma_f32_16x16x32_bf16 v[206:209], v[108:111], v[160:163], v[92:95]
	v_mfma_f32_16x16x32_bf16 v[156:159], v[202:205], v[160:163], v[88:91]
	v_mfma_f32_16x16x32_bf16 v[160:163], v[108:111], v[176:179], v[76:79]
	v_mfma_f32_16x16x32_bf16 v[164:167], v[202:205], v[176:179], v[72:75]
	s_setprio 0
	s_barrier
	s_nop 0
	ds_read_b128 v[72:75], v136 offset:16384
	ds_read_b128 v[76:79], v136 offset:17408
	ds_read_b128 v[88:91], v135 offset:16384
	ds_read_b128 v[92:95], v135 offset:17408
	ds_read_b128 v[168:171], v134 offset:16384
	ds_read_b128 v[172:175], v134 offset:17408
	ds_read_b128 v[176:179], v133 offset:16384
	ds_read_b128 v[180:183], v133 offset:17408
	s_waitcnt vmcnt(4)
	s_barrier
	s_waitcnt lgkmcnt(0)
	s_setprio 1
	s_waitcnt lgkmcnt(0)
	v_mfma_f32_16x16x32_bf16 v[60:63], v[140:143], v[72:75], v[60:63]
	v_mfma_f32_16x16x32_bf16 v[56:59], v[148:151], v[72:75], v[56:59]
	v_mfma_f32_16x16x32_bf16 v[52:55], v[140:143], v[88:91], v[52:55]
	v_mfma_f32_16x16x32_bf16 v[48:51], v[148:151], v[88:91], v[48:51]
	v_mfma_f32_16x16x32_bf16 v[36:39], v[140:143], v[176:179], v[36:39]
	v_mfma_f32_16x16x32_bf16 v[32:35], v[148:151], v[176:179], v[32:35]
	v_mfma_f32_16x16x32_bf16 v[60:63], v[144:147], v[76:79], v[60:63]
	v_mfma_f32_16x16x32_bf16 v[56:59], v[152:155], v[76:79], v[56:59]
	v_mfma_f32_16x16x32_bf16 v[52:55], v[144:147], v[92:95], v[52:55]
	v_mfma_f32_16x16x32_bf16 v[48:51], v[152:155], v[92:95], v[48:51]
	v_mfma_f32_16x16x32_bf16 v[44:47], v[140:143], v[168:171], v[44:47]
	v_mfma_f32_16x16x32_bf16 v[40:43], v[148:151], v[168:171], v[40:43]
	v_mfma_f32_16x16x32_bf16 v[36:39], v[144:147], v[180:183], v[36:39]
	v_mfma_f32_16x16x32_bf16 v[32:35], v[152:155], v[180:183], v[32:35]
	v_mfma_f32_16x16x32_bf16 v[184:187], v[144:147], v[172:175], v[44:47]
	v_mfma_f32_16x16x32_bf16 v[210:213], v[152:155], v[172:175], v[40:43]
	s_setprio 0
	s_setprio 1
	v_mfma_f32_16x16x32_bf16 v[20:23], v[104:107], v[88:91], v[20:23]
	v_mfma_f32_16x16x32_bf16 v[16:19], v[192:195], v[88:91], v[16:19]
	v_mfma_f32_16x16x32_bf16 v[4:7], v[104:107], v[176:179], v[4:7]
	v_mfma_f32_16x16x32_bf16 v[0:3], v[192:195], v[176:179], v[0:3]
	v_mfma_f32_16x16x32_bf16 v[28:31], v[104:107], v[72:75], v[28:31]
	v_mfma_f32_16x16x32_bf16 v[24:27], v[192:195], v[72:75], v[24:27]
	v_mfma_f32_16x16x32_bf16 v[20:23], v[108:111], v[92:95], v[20:23]
	v_mfma_f32_16x16x32_bf16 v[16:19], v[202:205], v[92:95], v[16:19]
	v_mfma_f32_16x16x32_bf16 v[12:15], v[104:107], v[168:171], v[12:15]
	v_mfma_f32_16x16x32_bf16 v[8:11], v[192:195], v[168:171], v[8:11]
	v_mfma_f32_16x16x32_bf16 v[4:7], v[108:111], v[180:183], v[4:7]
	v_mfma_f32_16x16x32_bf16 v[0:3], v[202:205], v[180:183], v[0:3]
	v_mfma_f32_16x16x32_bf16 v[140:143], v[108:111], v[76:79], v[28:31]
	v_mfma_f32_16x16x32_bf16 v[144:147], v[202:205], v[76:79], v[24:27]
	v_mfma_f32_16x16x32_bf16 v[148:151], v[108:111], v[172:175], v[12:15]
	v_mfma_f32_16x16x32_bf16 v[152:155], v[202:205], v[172:175], v[8:11]
	s_setprio 0
	s_barrier
	s_nop 0
	ds_read_b128 v[8:11], v138
	ds_read_b128 v[12:15], v138 offset:1024
	ds_read_b128 v[168:171], v138 offset:2048
	ds_read_b128 v[172:175], v138 offset:3072
	ds_read_b128 v[24:27], v136 offset:32768
	ds_read_b128 v[28:31], v136 offset:33792
	ds_read_b128 v[40:43], v135 offset:32768
	ds_read_b128 v[44:47], v135 offset:33792
	ds_read_b128 v[176:179], v134 offset:32768
	ds_read_b128 v[180:183], v134 offset:33792
	ds_read_b128 v[192:195], v133 offset:32768
	ds_read_b128 v[202:205], v133 offset:33792
	s_waitcnt vmcnt(2)
	s_barrier
	s_waitcnt lgkmcnt(0)
	s_setprio 1
	s_waitcnt lgkmcnt(0)
	v_mfma_f32_16x16x32_bf16 v[72:75], v[8:11], v[24:27], v[124:127]
	v_mfma_f32_16x16x32_bf16 v[124:127], v[12:15], v[28:31], v[72:75]
	v_mfma_f32_16x16x32_bf16 v[72:75], v[168:171], v[24:27], v[120:123]
	v_mfma_f32_16x16x32_bf16 v[120:123], v[172:175], v[28:31], v[72:75]
	v_mfma_f32_16x16x32_bf16 v[72:75], v[8:11], v[40:43], v[116:119]
	v_mfma_f32_16x16x32_bf16 v[108:111], v[12:15], v[44:47], v[72:75]
	v_mfma_f32_16x16x32_bf16 v[72:75], v[168:171], v[40:43], v[112:115]
	v_mfma_f32_16x16x32_bf16 v[104:107], v[172:175], v[44:47], v[72:75]
	v_mfma_f32_16x16x32_bf16 v[72:75], v[8:11], v[176:179], v[128:131]
	v_mfma_f32_16x16x32_bf16 v[92:95], v[12:15], v[180:183], v[72:75]
	v_mfma_f32_16x16x32_bf16 v[72:75], v[168:171], v[176:179], v[188:191]
	v_mfma_f32_16x16x32_bf16 v[88:91], v[172:175], v[180:183], v[72:75]
	v_mfma_f32_16x16x32_bf16 v[72:75], v[8:11], v[192:195], v[100:103]
	v_mfma_f32_16x16x32_bf16 v[76:79], v[12:15], v[202:205], v[72:75]
	v_mfma_f32_16x16x32_bf16 v[72:75], v[168:171], v[192:195], v[96:99]
	v_mfma_f32_16x16x32_bf16 v[72:75], v[172:175], v[202:205], v[72:75]
	s_setprio 0
	s_barrier
	ds_read_b128 v[128:131], v137
	ds_read_b128 v[188:191], v137 offset:1024
	ds_read_b128 v[214:217], v137 offset:2048
	ds_read_b128 v[218:221], v137 offset:3072
	s_waitcnt vmcnt(0)
	s_barrier
	s_waitcnt lgkmcnt(0)
	s_setprio 1
	s_waitcnt lgkmcnt(0)
	v_mfma_f32_16x16x32_bf16 v[96:99], v[128:131], v[24:27], v[206:209]
	v_mfma_f32_16x16x32_bf16 v[24:27], v[214:217], v[24:27], v[156:159]
	v_mfma_f32_16x16x32_bf16 v[112:115], v[218:221], v[28:31], v[24:27]
	v_mfma_f32_16x16x32_bf16 v[24:27], v[128:131], v[40:43], v[84:87]
	v_mfma_f32_16x16x32_bf16 v[100:103], v[188:191], v[44:47], v[24:27]
	v_mfma_f32_16x16x32_bf16 v[24:27], v[214:217], v[40:43], v[80:83]
	v_mfma_f32_16x16x32_bf16 v[116:119], v[188:191], v[28:31], v[96:99]
	v_mfma_f32_16x16x32_bf16 v[96:99], v[218:221], v[44:47], v[24:27]
	v_mfma_f32_16x16x32_bf16 v[24:27], v[128:131], v[176:179], v[160:163]
	v_mfma_f32_16x16x32_bf16 v[84:87], v[188:191], v[180:183], v[24:27]
	v_mfma_f32_16x16x32_bf16 v[24:27], v[214:217], v[176:179], v[164:167]
	v_mfma_f32_16x16x32_bf16 v[80:83], v[218:221], v[180:183], v[24:27]
	v_mfma_f32_16x16x32_bf16 v[24:27], v[128:131], v[192:195], v[68:71]
	v_mfma_f32_16x16x32_bf16 v[68:71], v[188:191], v[202:205], v[24:27]
	v_mfma_f32_16x16x32_bf16 v[24:27], v[214:217], v[192:195], v[64:67]
	v_mfma_f32_16x16x32_bf16 v[64:67], v[218:221], v[202:205], v[24:27]
	s_setprio 0
	s_barrier
	ds_read_b128 v[156:159], v136 offset:49152
	ds_read_b128 v[136:139], v136 offset:50176
	ds_read_b128 v[160:163], v135 offset:49152
	ds_read_b128 v[164:167], v135 offset:50176
	ds_read_b128 v[176:179], v134 offset:49152
	ds_read_b128 v[180:183], v134 offset:50176
	ds_read_b128 v[192:195], v133 offset:49152
	ds_read_b128 v[202:205], v133 offset:50176
	s_barrier
	s_waitcnt lgkmcnt(0)
	s_setprio 1
	s_waitcnt lgkmcnt(0)
	v_mfma_f32_16x16x32_bf16 v[24:27], v[8:11], v[156:159], v[60:63]
	v_mfma_f32_16x16x32_bf16 v[60:63], v[12:15], v[136:139], v[24:27]
	v_mfma_f32_16x16x32_bf16 v[24:27], v[168:171], v[156:159], v[56:59]
	v_mfma_f32_16x16x32_bf16 v[56:59], v[172:175], v[136:139], v[24:27]
	v_mfma_f32_16x16x32_bf16 v[24:27], v[8:11], v[160:163], v[52:55]
	v_mfma_f32_16x16x32_bf16 v[44:47], v[12:15], v[164:167], v[24:27]
	v_mfma_f32_16x16x32_bf16 v[24:27], v[168:171], v[160:163], v[48:51]
	v_mfma_f32_16x16x32_bf16 v[40:43], v[172:175], v[164:167], v[24:27]
	v_mfma_f32_16x16x32_bf16 v[24:27], v[8:11], v[176:179], v[184:187]
	v_mfma_f32_16x16x32_bf16 v[8:11], v[8:11], v[192:195], v[36:39]
	v_mfma_f32_16x16x32_bf16 v[28:31], v[12:15], v[180:183], v[24:27]
	v_mfma_f32_16x16x32_bf16 v[24:27], v[168:171], v[176:179], v[210:213]
	v_mfma_f32_16x16x32_bf16 v[12:15], v[12:15], v[202:205], v[8:11]
	v_mfma_f32_16x16x32_bf16 v[8:11], v[168:171], v[192:195], v[32:35]
	v_mfma_f32_16x16x32_bf16 v[24:27], v[172:175], v[180:183], v[24:27]
	v_mfma_f32_16x16x32_bf16 v[8:11], v[172:175], v[202:205], v[8:11]
	s_setprio 0
	s_setprio 1
	v_mfma_f32_16x16x32_bf16 v[32:35], v[128:131], v[156:159], v[140:143]
	v_mfma_f32_16x16x32_bf16 v[52:55], v[188:191], v[136:139], v[32:35]
	v_mfma_f32_16x16x32_bf16 v[32:35], v[214:217], v[156:159], v[144:147]
	v_mfma_f32_16x16x32_bf16 v[16:19], v[214:217], v[160:163], v[16:19]
	v_mfma_f32_16x16x32_bf16 v[48:51], v[218:221], v[136:139], v[32:35]
	v_mfma_f32_16x16x32_bf16 v[20:23], v[128:131], v[160:163], v[20:23]
	v_mfma_f32_16x16x32_bf16 v[32:35], v[218:221], v[164:167], v[16:19]
	v_mfma_f32_16x16x32_bf16 v[16:19], v[128:131], v[176:179], v[148:151]
	v_mfma_f32_16x16x32_bf16 v[36:39], v[188:191], v[164:167], v[20:23]
	v_mfma_f32_16x16x32_bf16 v[20:23], v[188:191], v[180:183], v[16:19]
	v_mfma_f32_16x16x32_bf16 v[16:19], v[214:217], v[176:179], v[152:155]
	v_mfma_f32_16x16x32_bf16 v[4:7], v[128:131], v[192:195], v[4:7]
	v_mfma_f32_16x16x32_bf16 v[0:3], v[214:217], v[192:195], v[0:3]
	v_mfma_f32_16x16x32_bf16 v[16:19], v[218:221], v[180:183], v[16:19]
	v_mfma_f32_16x16x32_bf16 v[4:7], v[188:191], v[202:205], v[4:7]
	v_mfma_f32_16x16x32_bf16 v[0:3], v[218:221], v[202:205], v[0:3]
	s_setprio 0
	s_movk_i32 s4, 0x100
	v_cmp_gt_u32_e32 vcc, s4, v132
	s_barrier
	s_and_saveexec_b64 s[4:5], vcc
	s_cbranch_execz .LBB0_571
	s_barrier
